# K-loop barrier hand-over: s_setprio 1 moved in front of the opening barrier, satisfied lgkmcnt(0) after it deleted, s_setprio 0 moved behind the closing barrier
# baseline (speedup 1.0000x reference)
; #define PG8_STAGE(bufoff, gbase, voff) do { _Pragma("unroll") for (int _i = 0; _i < 2; ++_i) \
;         __builtin_amdgcn_global_load_lds((const unsigned*)((const char*)(gbase) + (voff)[_i]), (PG8_LAS unsigned*)(lds + (bufoff) + ldsw + _i * 8192), 16, 0, 0); } while (0)
; #define PG8_STAGEA(bufoff, gbase, voff) do { _Pragma("unroll") for (int _i = 0; _i < 2; ++_i) \
;         __builtin_amdgcn_global_load_lds((const unsigned*)((const char*)(gbase) + (voff)[_i]), (PG8_LAS unsigned*)(lds + (bufoff) + ldsw + _i * 8192), 16, 0, A_AUX); } while (0)
; #define PG8_LDA(dst, b, h) do { _Pragma("unroll") for (int m = 0; m < 4; ++m) _Pragma("unroll") for (int k = 0; k < 2; ++k) dst[m][k] = *(const PG8_LAS bf16x8*)(lds + PG8_SA(b, h) + aoff + m * 2048 + k * 1024); } while (0)
; #define PG8_LDB(dst, b, h) do { _Pragma("unroll") for (int n = 0; n < 2; ++n) _Pragma("unroll") for (int k = 0; k < 2; ++k) dst[n][k] = *(const PG8_LAS bf16x8*)(lds + PG8_SB(b, h) + boff + n * 2048 + k * 1024); } while (0)
; #define PG8_WAIT_V(n) asm volatile("s_waitcnt vmcnt(" #n ")" ::: "memory")
; #define PG8_WAIT_L(n) asm volatile("s_waitcnt lgkmcnt(" #n ")" ::: "memory")
; #define PG8_BAR __builtin_amdgcn_s_barrier()
;     ...
;         const bool has_next = S.next(ui + 1, nxt);
;         const char* nA = has_next ? (const char*)g.A + (size_t)nxt.pm * tstep : cA; const char* nB = has_next ? (const char*)g.Bt + (size_t)nxt.pn * tstep : cB;
;         for (int t = 0; t < nt; t += 2) {
;             const bool last = (t == nt - 2);
;             const char* a1 = cA + (size_t)(t + 1) * kstep;
;             const char* a2 = last ? nA : cA + (size_t)(t + 2) * kstep; const char* b2 = last ? nB : cB + (size_t)(t + 2) * kstep;
;             const char* a3 = a2 + kstep; const char* b3 = b2 + kstep;
;             if (last && has_next) S.a_ready(nxt);
;             if constexpr (SP2) {
;             PG8_LDB(B0, 0, 0); PG8_LDB(B1, 0, 1); PG8_SCHED; PG8_LDA(At, 0, 0); PG8_STAGEA(PG8_SA(1, 1), a1 + hstep, voffA);
;             PG8_WAIT_V(8); PG8_WAIT_L(0); PG8_BAR; PG8_MMA(0, 0, At, B0); PG8_MMA(0, 1, At, B1); PG8_BAR; PG8_SCHED;
;             PG8_LDA(At, 0, 1); PG8_STAGE(PG8_SB(0, 0), b2, voffB); PG8_STAGE(PG8_SB(0, 1), b2 + hstep, voffB); PG8_STAGEA(PG8_SA(0, 0), a2, voffA);
;             PG8_WAIT_V(8); PG8_WAIT_L(0); PG8_BAR; PG8_MMA(1, 0, At, B0); PG8_MMA(1, 1, At, B1); PG8_BAR; PG8_SCHED;
.LBB0_185:
	s_ashr_i32 s53, s52, 31
	s_lshl_b64 s[16:17], s[52:53], 19
	s_add_u32 s54, s97, s16
	s_addc_u32 s55, s29, s17
	s_and_b64 s[16:17], s[38:39], exec
	s_cselect_b32 s16, s55, s1
	s_cselect_b32 s17, s54, s0
	s_ashr_i32 s51, s50, 31
	s_lshl_b64 s[42:43], s[50:51], 19
	v_readlane_b32 s51, v246, 9
	s_add_u32 s56, s51, s42
	v_readlane_b32 s42, v246, 6
	s_addc_u32 s57, s42, s43
	s_and_b64 s[42:43], s[38:39], exec
	s_cselect_b32 s51, s57, s41
	s_cselect_b32 s53, s56, s40
	s_add_u32 s0, s0, 0x40080
	s_addc_u32 s1, s1, 0
	s_add_u32 s58, s40, 0x100
	s_addc_u32 s59, s41, 0
	s_mov_b32 vcc_lo, -2
	s_add_u32 s40, s0, 0xfffc0080
	s_addc_u32 s41, s1, -1
	s_add_i32 s70, 0, 0x10000
	s_cmp_eq_u32 vcc_lo, 12
	s_cselect_b32 s43, s16, s41
	s_cselect_b32 s42, s17, s40
	s_cselect_b32 s41, s51, s59
	s_cselect_b32 s40, s53, s58
	s_add_i32 vcc_hi, 0, 0x14000
	v_add_u32_e32 v94, s70, v201
	v_add_u32_e32 v158, vcc_hi, v201
	ds_read_b128 v[74:77], v94
	ds_read_b128 v[78:81], v94 offset:1024
	ds_read_b128 v[90:93], v94 offset:2048
	ds_read_b128 v[94:97], v94 offset:3072
	ds_read_b128 v[146:149], v158
	ds_read_b128 v[150:153], v158 offset:1024
	ds_read_b128 v[154:157], v158 offset:2048
	ds_read_b128 v[158:161], v158 offset:3072
	v_lshl_add_u64 v[190:191], s[0:1], 0, v[182:183]
	s_add_i32 m0, s61, 0xc000
	ds_read_b128 v[186:189], v203
	ds_read_b128 v[208:211], v203 offset:1024
	ds_read_b128 v[212:215], v203 offset:2048
	ds_read_b128 v[216:219], v203 offset:3072
	ds_read_b128 v[220:223], v203 offset:4096
	ds_read_b128 v[224:227], v203 offset:5120
	ds_read_b128 v[228:231], v203 offset:6144
	ds_read_b128 v[232:235], v203 offset:7168
	global_load_lds_dwordx4 v[190:191], off
	v_lshl_add_u64 v[190:191], s[0:1], 0, v[184:185]
	s_add_i32 m0, s61, 0xe000
	s_nop 0
	global_load_lds_dwordx4 v[190:191], off
	s_waitcnt vmcnt(8)
	s_waitcnt lgkmcnt(0)
	s_setprio 1
	s_barrier
	v_mfma_f32_16x16x32_bf16 v[142:145], v[74:77], v[186:189], 0
	v_mfma_f32_16x16x32_bf16 v[138:141], v[90:93], v[186:189], 0
	v_mfma_f32_16x16x32_bf16 v[126:129], v[74:77], v[212:215], 0
	v_mfma_f32_16x16x32_bf16 v[122:125], v[90:93], v[212:215], 0
	v_mfma_f32_16x16x32_bf16 v[110:113], v[74:77], v[220:223], 0
	v_mfma_f32_16x16x32_bf16 v[106:109], v[90:93], v[220:223], 0
	v_mfma_f32_16x16x32_bf16 v[86:89], v[74:77], v[228:231], 0
	v_mfma_f32_16x16x32_bf16 v[82:85], v[90:93], v[228:231], 0
	v_mfma_f32_16x16x32_bf16 v[142:145], v[78:81], v[208:211], v[142:145]
	v_mfma_f32_16x16x32_bf16 v[138:141], v[94:97], v[208:211], v[138:141]
	v_mfma_f32_16x16x32_bf16 v[126:129], v[78:81], v[216:219], v[126:129]
	v_mfma_f32_16x16x32_bf16 v[122:125], v[94:97], v[216:219], v[122:125]
	v_mfma_f32_16x16x32_bf16 v[110:113], v[78:81], v[224:227], v[110:113]
	v_mfma_f32_16x16x32_bf16 v[106:109], v[94:97], v[224:227], v[106:109]
	v_mfma_f32_16x16x32_bf16 v[86:89], v[78:81], v[232:235], v[86:89]
	v_mfma_f32_16x16x32_bf16 v[82:85], v[94:97], v[232:235], v[82:85]
	s_setprio 0
	s_setprio 1
	v_mfma_f32_16x16x32_bf16 v[134:137], v[146:149], v[186:189], 0
	v_mfma_f32_16x16x32_bf16 v[130:133], v[154:157], v[186:189], 0
	v_mfma_f32_16x16x32_bf16 v[118:121], v[146:149], v[212:215], 0
	v_mfma_f32_16x16x32_bf16 v[114:117], v[154:157], v[212:215], 0
	v_mfma_f32_16x16x32_bf16 v[102:105], v[146:149], v[220:223], 0
	v_mfma_f32_16x16x32_bf16 v[98:101], v[154:157], v[220:223], 0
	v_mfma_f32_16x16x32_bf16 v[70:73], v[146:149], v[228:231], 0
	v_mfma_f32_16x16x32_bf16 v[66:69], v[154:157], v[228:231], 0
	v_mfma_f32_16x16x32_bf16 v[134:137], v[150:153], v[208:211], v[134:137]
	v_mfma_f32_16x16x32_bf16 v[130:133], v[158:161], v[208:211], v[130:133]
	v_mfma_f32_16x16x32_bf16 v[118:121], v[150:153], v[216:219], v[118:121]
	v_mfma_f32_16x16x32_bf16 v[114:117], v[158:161], v[216:219], v[114:117]
	v_mfma_f32_16x16x32_bf16 v[102:105], v[150:153], v[224:227], v[102:105]
	v_mfma_f32_16x16x32_bf16 v[98:101], v[158:161], v[224:227], v[98:101]
	v_mfma_f32_16x16x32_bf16 v[70:73], v[150:153], v[232:235], v[70:73]
	v_mfma_f32_16x16x32_bf16 v[66:69], v[158:161], v[232:235], v[66:69]
	s_barrier
	s_setprio 0
	s_add_i32 s70, s70, s60
	v_lshl_add_u64 v[190:191], s[40:41], 0, v[0:1]
	s_mov_b32 m0, s70
	ds_read_b128 v[186:189], v203 offset:16384
	ds_read_b128 v[208:211], v203 offset:17408
	ds_read_b128 v[212:215], v203 offset:18432
	ds_read_b128 v[216:219], v203 offset:19456
	ds_read_b128 v[220:223], v203 offset:20480
	ds_read_b128 v[224:227], v203 offset:21504
	ds_read_b128 v[228:231], v203 offset:22528
	ds_read_b128 v[232:235], v203 offset:23552
	global_load_lds_dwordx4 v[190:191], off
	s_add_i32 m0, s70, 0x2000
	s_add_u32 s70, s40, 0x40000
	v_lshl_add_u64 v[236:237], s[40:41], 0, v[174:175]
	s_addc_u32 s71, s41, 0
	s_add_i32 vcc_hi, vcc_hi, s60
	global_load_lds_dwordx4 v[236:237], off
	v_lshl_add_u64 v[238:239], s[70:71], 0, v[0:1]
	s_mov_b32 m0, vcc_hi
	v_lshl_add_u64 v[240:241], s[42:43], 0, v[176:177]
	global_load_lds_dwordx4 v[238:239], off
	v_lshl_add_u64 v[238:239], s[70:71], 0, v[174:175]
	s_add_i32 m0, vcc_hi, 0x2000
	s_nop 0
	global_load_lds_dwordx4 v[238:239], off
	v_lshl_add_u64 v[238:239], s[42:43], 0, v[178:179]
	s_mov_b32 m0, s61
	s_nop 0
	global_load_lds_dwordx4 v[238:239], off
	s_mov_b32 m0, s62
	s_nop 0
	global_load_lds_dwordx4 v[240:241], off
	s_waitcnt vmcnt(8)
	s_waitcnt lgkmcnt(0)
	s_setprio 1
	s_barrier
; #define PG8_STAGEA(bufoff, gbase, voff) do { _Pragma("unroll") for (int _i = 0; _i < 2; ++_i) \
;         __builtin_amdgcn_global_load_lds((const unsigned*)((const char*)(gbase) + (voff)[_i]), (PG8_LAS unsigned*)(lds + (bufoff) + ldsw + _i * 8192), 16, 0, A_AUX); } while (0)
; #define PG8_LDA(dst, b, h) do { _Pragma("unroll") for (int m = 0; m < 4; ++m) _Pragma("unroll") for (int k = 0; k < 2; ++k) dst[m][k] = *(const PG8_LAS bf16x8*)(lds + PG8_SA(b, h) + aoff + m * 2048 + k * 1024); } while (0)
; #define PG8_LDB(dst, b, h) do { _Pragma("unroll") for (int n = 0; n < 2; ++n) _Pragma("unroll") for (int k = 0; k < 2; ++k) dst[n][k] = *(const PG8_LAS bf16x8*)(lds + PG8_SB(b, h) + boff + n * 2048 + k * 1024); } while (0)
; #define PG8_MMA(ai, bj, At, Bt) do { __builtin_amdgcn_s_setprio(1); _Pragma("unroll") for (int m = 0; m < 4; ++m) _Pragma("unroll") for (int n = 0; n < 2; ++n) _Pragma("unroll") for (int k = 0; k < 2; ++k) \
;         acc[ai][bj][m][n] = __builtin_amdgcn_mfma_f32_16x16x32_bf16(Bt[n][k], At[m][k], acc[ai][bj][m][n], 0, 0, 0); __builtin_amdgcn_s_setprio(0); } while (0)
; #define PG8_WAIT_V(n) asm volatile("s_waitcnt vmcnt(" #n ")" ::: "memory")
; #define PG8_WAIT_L(n) asm volatile("s_waitcnt lgkmcnt(" #n ")" ::: "memory")
; #define PG8_BAR __builtin_amdgcn_s_barrier()
; #define PG8_SCHED __builtin_amdgcn_sched_barrier(0)
;     ...
;             PG8_WAIT_V(8); PG8_WAIT_L(0); PG8_BAR; PG8_MMA(1, 0, At, B0); PG8_MMA(1, 1, At, B1); PG8_BAR; PG8_SCHED;
;             PG8_LDB(B0, 1, 0); PG8_LDB(B1, 1, 1); PG8_SCHED; PG8_LDA(At, 1, 0); PG8_STAGEA(PG8_SA(0, 1), a2 + hstep, voffA);
;             PG8_WAIT_V(8); PG8_WAIT_L(0); PG8_BAR; PG8_MMA(0, 0, At, B0); PG8_MMA(0, 1, At, B1); PG8_BAR; PG8_SCHED;
	v_mfma_f32_16x16x32_bf16 v[62:65], v[74:77], v[186:189], 0
	v_mfma_f32_16x16x32_bf16 v[58:61], v[90:93], v[186:189], 0
	v_mfma_f32_16x16x32_bf16 v[46:49], v[74:77], v[212:215], 0
	v_mfma_f32_16x16x32_bf16 v[42:45], v[90:93], v[212:215], 0
	v_mfma_f32_16x16x32_bf16 v[30:33], v[74:77], v[220:223], 0
	v_mfma_f32_16x16x32_bf16 v[26:29], v[90:93], v[220:223], 0
	v_mfma_f32_16x16x32_bf16 v[14:17], v[74:77], v[228:231], 0
	v_mfma_f32_16x16x32_bf16 v[10:13], v[90:93], v[228:231], 0
	v_mfma_f32_16x16x32_bf16 v[62:65], v[78:81], v[208:211], v[62:65]
	v_mfma_f32_16x16x32_bf16 v[58:61], v[94:97], v[208:211], v[58:61]
	v_mfma_f32_16x16x32_bf16 v[46:49], v[78:81], v[216:219], v[46:49]
	v_mfma_f32_16x16x32_bf16 v[42:45], v[94:97], v[216:219], v[42:45]
	v_mfma_f32_16x16x32_bf16 v[30:33], v[78:81], v[224:227], v[30:33]
	v_mfma_f32_16x16x32_bf16 v[26:29], v[94:97], v[224:227], v[26:29]
	v_mfma_f32_16x16x32_bf16 v[14:17], v[78:81], v[232:235], v[14:17]
	v_mfma_f32_16x16x32_bf16 v[10:13], v[94:97], v[232:235], v[10:13]
	s_setprio 0
	s_setprio 1
	v_mfma_f32_16x16x32_bf16 v[54:57], v[146:149], v[186:189], 0
	v_mfma_f32_16x16x32_bf16 v[50:53], v[154:157], v[186:189], 0
	v_mfma_f32_16x16x32_bf16 v[38:41], v[146:149], v[212:215], 0
	v_mfma_f32_16x16x32_bf16 v[34:37], v[154:157], v[212:215], 0
	v_mfma_f32_16x16x32_bf16 v[22:25], v[146:149], v[220:223], 0
	v_mfma_f32_16x16x32_bf16 v[18:21], v[154:157], v[220:223], 0
	v_mfma_f32_16x16x32_bf16 v[6:9], v[146:149], v[228:231], 0
	v_mfma_f32_16x16x32_bf16 v[2:5], v[154:157], v[228:231], 0
	v_mfma_f32_16x16x32_bf16 v[54:57], v[150:153], v[208:211], v[54:57]
	v_mfma_f32_16x16x32_bf16 v[50:53], v[158:161], v[208:211], v[50:53]
	v_mfma_f32_16x16x32_bf16 v[38:41], v[150:153], v[216:219], v[38:41]
	v_mfma_f32_16x16x32_bf16 v[34:37], v[158:161], v[216:219], v[34:37]
	v_mfma_f32_16x16x32_bf16 v[22:25], v[150:153], v[224:227], v[22:25]
	v_mfma_f32_16x16x32_bf16 v[18:21], v[158:161], v[224:227], v[18:21]
	v_mfma_f32_16x16x32_bf16 v[6:9], v[150:153], v[232:235], v[6:9]
	v_mfma_f32_16x16x32_bf16 v[2:5], v[158:161], v[232:235], v[2:5]
	s_barrier
	s_setprio 0
	s_add_i32 s70, 0, 0x18000
	s_add_i32 s71, 0, 0x1c000
	v_add_u32_e32 v94, s70, v201
	v_add_u32_e32 v158, s71, v201
	ds_read_b128 v[74:77], v94
	ds_read_b128 v[78:81], v94 offset:1024
	ds_read_b128 v[90:93], v94 offset:2048
	ds_read_b128 v[94:97], v94 offset:3072
	ds_read_b128 v[146:149], v158
	ds_read_b128 v[150:153], v158 offset:1024
	ds_read_b128 v[154:157], v158 offset:2048
	ds_read_b128 v[158:161], v158 offset:3072
	s_add_u32 s42, s42, 0x40000
	s_addc_u32 s43, s43, 0
	s_mov_b32 m0, s63
	v_lshl_add_u64 v[242:243], s[42:43], 0, v[178:179]
	ds_read_b128 v[186:189], v203 offset:32768
	ds_read_b128 v[208:211], v203 offset:33792
	ds_read_b128 v[212:215], v203 offset:34816
	ds_read_b128 v[216:219], v203 offset:35840
	ds_read_b128 v[220:223], v203 offset:36864
	ds_read_b128 v[224:227], v203 offset:37888
	ds_read_b128 v[228:231], v203 offset:38912
	ds_read_b128 v[232:235], v203 offset:39936
	global_load_lds_dwordx4 v[242:243], off
	v_lshl_add_u64 v[242:243], s[42:43], 0, v[176:177]
	s_mov_b32 m0, s64
	s_nop 0
	global_load_lds_dwordx4 v[242:243], off
	s_waitcnt vmcnt(8)
	s_waitcnt lgkmcnt(0)
	s_setprio 1
	s_barrier
	v_mfma_f32_16x16x32_bf16 v[142:145], v[74:77], v[186:189], v[142:145]
	v_mfma_f32_16x16x32_bf16 v[138:141], v[90:93], v[186:189], v[138:141]
	v_mfma_f32_16x16x32_bf16 v[126:129], v[74:77], v[212:215], v[126:129]
	v_mfma_f32_16x16x32_bf16 v[122:125], v[90:93], v[212:215], v[122:125]
	v_mfma_f32_16x16x32_bf16 v[110:113], v[74:77], v[220:223], v[110:113]
	v_mfma_f32_16x16x32_bf16 v[106:109], v[90:93], v[220:223], v[106:109]
	v_mfma_f32_16x16x32_bf16 v[86:89], v[74:77], v[228:231], v[86:89]
	v_mfma_f32_16x16x32_bf16 v[82:85], v[90:93], v[228:231], v[82:85]
	v_mfma_f32_16x16x32_bf16 v[142:145], v[78:81], v[208:211], v[142:145]
	v_mfma_f32_16x16x32_bf16 v[138:141], v[94:97], v[208:211], v[138:141]
	v_mfma_f32_16x16x32_bf16 v[126:129], v[78:81], v[216:219], v[126:129]
	v_mfma_f32_16x16x32_bf16 v[122:125], v[94:97], v[216:219], v[122:125]
	v_mfma_f32_16x16x32_bf16 v[110:113], v[78:81], v[224:227], v[110:113]
	v_mfma_f32_16x16x32_bf16 v[106:109], v[94:97], v[224:227], v[106:109]
	v_mfma_f32_16x16x32_bf16 v[86:89], v[78:81], v[232:235], v[86:89]
	v_mfma_f32_16x16x32_bf16 v[82:85], v[94:97], v[232:235], v[82:85]
	s_setprio 0
	s_setprio 1
	v_mfma_f32_16x16x32_bf16 v[134:137], v[146:149], v[186:189], v[134:137]
	v_mfma_f32_16x16x32_bf16 v[130:133], v[154:157], v[186:189], v[130:133]
	v_mfma_f32_16x16x32_bf16 v[118:121], v[146:149], v[212:215], v[118:121]
	v_mfma_f32_16x16x32_bf16 v[114:117], v[154:157], v[212:215], v[114:117]
	v_mfma_f32_16x16x32_bf16 v[102:105], v[146:149], v[220:223], v[102:105]
	v_mfma_f32_16x16x32_bf16 v[98:101], v[154:157], v[220:223], v[98:101]
	v_mfma_f32_16x16x32_bf16 v[70:73], v[146:149], v[228:231], v[70:73]
	v_mfma_f32_16x16x32_bf16 v[66:69], v[154:157], v[228:231], v[66:69]
	v_mfma_f32_16x16x32_bf16 v[134:137], v[150:153], v[208:211], v[134:137]
	v_mfma_f32_16x16x32_bf16 v[130:133], v[158:161], v[208:211], v[130:133]
	v_mfma_f32_16x16x32_bf16 v[118:121], v[150:153], v[216:219], v[118:121]
	v_mfma_f32_16x16x32_bf16 v[114:117], v[158:161], v[216:219], v[114:117]
	v_mfma_f32_16x16x32_bf16 v[102:105], v[150:153], v[224:227], v[102:105]
	v_mfma_f32_16x16x32_bf16 v[98:101], v[158:161], v[224:227], v[98:101]
	v_mfma_f32_16x16x32_bf16 v[70:73], v[150:153], v[232:235], v[70:73]
	v_mfma_f32_16x16x32_bf16 v[66:69], v[158:161], v[232:235], v[66:69]
	s_barrier
; #define PG8_STAGE(bufoff, gbase, voff) do { _Pragma("unroll") for (int _i = 0; _i < 2; ++_i) \
;         __builtin_amdgcn_global_load_lds((const unsigned*)((const char*)(gbase) + (voff)[_i]), (PG8_LAS unsigned*)(lds + (bufoff) + ldsw + _i * 8192), 16, 0, 0); } while (0)
; #define PG8_STAGEA(bufoff, gbase, voff) do { _Pragma("unroll") for (int _i = 0; _i < 2; ++_i) \
;         __builtin_amdgcn_global_load_lds((const unsigned*)((const char*)(gbase) + (voff)[_i]), (PG8_LAS unsigned*)(lds + (bufoff) + ldsw + _i * 8192), 16, 0, A_AUX); } while (0)
; #define PG8_LDA(dst, b, h) do { _Pragma("unroll") for (int m = 0; m < 4; ++m) _Pragma("unroll") for (int k = 0; k < 2; ++k) dst[m][k] = *(const PG8_LAS bf16x8*)(lds + PG8_SA(b, h) + aoff + m * 2048 + k * 1024); } while (0)
; #define PG8_LDB(dst, b, h) do { _Pragma("unroll") for (int n = 0; n < 2; ++n) _Pragma("unroll") for (int k = 0; k < 2; ++k) dst[n][k] = *(const PG8_LAS bf16x8*)(lds + PG8_SB(b, h) + boff + n * 2048 + k * 1024); } while (0)
; #define PG8_MMA(ai, bj, At, Bt) do { __builtin_amdgcn_s_setprio(1); _Pragma("unroll") for (int m = 0; m < 4; ++m) _Pragma("unroll") for (int n = 0; n < 2; ++n) _Pragma("unroll") for (int k = 0; k < 2; ++k) \
;         acc[ai][bj][m][n] = __builtin_amdgcn_mfma_f32_16x16x32_bf16(Bt[n][k], At[m][k], acc[ai][bj][m][n], 0, 0, 0); __builtin_amdgcn_s_setprio(0); } while (0)
; #define PG8_BAR __builtin_amdgcn_s_barrier()
;     ...
;         for (int t = 0; t < nt; t += 2) {
;             const bool last = (t == nt - 2);
;             const char* a1 = cA + (size_t)(t + 1) * kstep;
;             const char* a2 = last ? nA : cA + (size_t)(t + 2) * kstep; const char* b2 = last ? nB : cB + (size_t)(t + 2) * kstep;
;             const char* a3 = a2 + kstep; const char* b3 = b2 + kstep;
;             if (last && has_next) S.a_ready(nxt);
;             if constexpr (SP2) {
;             PG8_LDB(B0, 0, 0); PG8_LDB(B1, 0, 1); PG8_SCHED; PG8_LDA(At, 0, 0); PG8_STAGEA(PG8_SA(1, 1), a1 + hstep, voffA);
;             PG8_WAIT_V(8); PG8_WAIT_L(0); PG8_BAR; PG8_MMA(0, 0, At, B0); PG8_MMA(0, 1, At, B1); PG8_BAR; PG8_SCHED;
;     ...
;             PG8_LDA(At, 1, 1); PG8_STAGE(PG8_SB(1, 0), b3, voffB); PG8_STAGE(PG8_SB(1, 1), b3 + hstep, voffB); PG8_STAGEA(PG8_SA(1, 0), a3, voffA);
;             PG8_WAIT_V(8); PG8_WAIT_L(0); PG8_BAR; PG8_MMA(1, 0, At, B0); PG8_MMA(1, 1, At, B1); PG8_BAR; PG8_SCHED;
	s_setprio 0
	s_add_i32 s42, s70, s60
	v_lshl_add_u64 v[190:191], v[190:191], 0, s[8:9]
	s_mov_b32 m0, s42
	ds_read_b128 v[186:189], v203 offset:49152
	ds_read_b128 v[208:211], v203 offset:50176
	ds_read_b128 v[212:215], v203 offset:51200
	ds_read_b128 v[216:219], v203 offset:52224
	ds_read_b128 v[220:223], v203 offset:53248
	ds_read_b128 v[224:227], v203 offset:54272
	ds_read_b128 v[228:231], v203 offset:55296
	ds_read_b128 v[232:235], v203 offset:56320
	global_load_lds_dwordx4 v[190:191], off
	s_add_i32 m0, s42, 0x2000
	s_add_u32 s40, s40, 0x40080
	v_lshl_add_u64 v[190:191], v[236:237], 0, s[8:9]
	s_addc_u32 s41, s41, 0
	s_add_i32 s42, s71, s60
	global_load_lds_dwordx4 v[190:191], off
	v_lshl_add_u64 v[190:191], s[40:41], 0, v[0:1]
	s_mov_b32 m0, s42
	s_nop 0
	global_load_lds_dwordx4 v[190:191], off
	v_lshl_add_u64 v[190:191], s[40:41], 0, v[174:175]
	s_add_i32 m0, s42, 0x2000
	s_nop 0
	global_load_lds_dwordx4 v[190:191], off
	v_lshl_add_u64 v[190:191], v[238:239], 0, s[8:9]
	s_mov_b32 m0, s72
	s_nop 0
	global_load_lds_dwordx4 v[190:191], off
	v_lshl_add_u64 v[190:191], v[240:241], 0, s[8:9]
	s_mov_b32 m0, s73
	s_nop 0
	global_load_lds_dwordx4 v[190:191], off
	s_waitcnt vmcnt(8)
	s_waitcnt lgkmcnt(0)
	s_setprio 1
	s_barrier
	v_mfma_f32_16x16x32_bf16 v[62:65], v[74:77], v[186:189], v[62:65]
	v_mfma_f32_16x16x32_bf16 v[58:61], v[90:93], v[186:189], v[58:61]
	v_mfma_f32_16x16x32_bf16 v[46:49], v[74:77], v[212:215], v[46:49]
	v_mfma_f32_16x16x32_bf16 v[42:45], v[90:93], v[212:215], v[42:45]
	v_mfma_f32_16x16x32_bf16 v[30:33], v[74:77], v[220:223], v[30:33]
	v_mfma_f32_16x16x32_bf16 v[26:29], v[90:93], v[220:223], v[26:29]
	v_mfma_f32_16x16x32_bf16 v[14:17], v[74:77], v[228:231], v[14:17]
	v_mfma_f32_16x16x32_bf16 v[10:13], v[90:93], v[228:231], v[10:13]
	v_mfma_f32_16x16x32_bf16 v[62:65], v[78:81], v[208:211], v[62:65]
	v_mfma_f32_16x16x32_bf16 v[58:61], v[94:97], v[208:211], v[58:61]
	v_mfma_f32_16x16x32_bf16 v[46:49], v[78:81], v[216:219], v[46:49]
	v_mfma_f32_16x16x32_bf16 v[42:45], v[94:97], v[216:219], v[42:45]
	v_mfma_f32_16x16x32_bf16 v[30:33], v[78:81], v[224:227], v[30:33]
	v_mfma_f32_16x16x32_bf16 v[26:29], v[94:97], v[224:227], v[26:29]
	v_mfma_f32_16x16x32_bf16 v[14:17], v[78:81], v[232:235], v[14:17]
	v_mfma_f32_16x16x32_bf16 v[10:13], v[94:97], v[232:235], v[10:13]
	s_setprio 0
	s_setprio 1
	v_mfma_f32_16x16x32_bf16 v[54:57], v[146:149], v[186:189], v[54:57]
	v_mfma_f32_16x16x32_bf16 v[50:53], v[154:157], v[186:189], v[50:53]
	v_mfma_f32_16x16x32_bf16 v[38:41], v[146:149], v[212:215], v[38:41]
	v_mfma_f32_16x16x32_bf16 v[34:37], v[154:157], v[212:215], v[34:37]
	v_mfma_f32_16x16x32_bf16 v[22:25], v[146:149], v[220:223], v[22:25]
	v_mfma_f32_16x16x32_bf16 v[18:21], v[154:157], v[220:223], v[18:21]
	v_mfma_f32_16x16x32_bf16 v[6:9], v[146:149], v[228:231], v[6:9]
	v_mfma_f32_16x16x32_bf16 v[2:5], v[154:157], v[228:231], v[2:5]
	v_mfma_f32_16x16x32_bf16 v[54:57], v[150:153], v[208:211], v[54:57]
	v_mfma_f32_16x16x32_bf16 v[50:53], v[158:161], v[208:211], v[50:53]
	v_mfma_f32_16x16x32_bf16 v[38:41], v[150:153], v[216:219], v[38:41]
	v_mfma_f32_16x16x32_bf16 v[34:37], v[158:161], v[216:219], v[34:37]
	v_mfma_f32_16x16x32_bf16 v[22:25], v[150:153], v[224:227], v[22:25]
	v_mfma_f32_16x16x32_bf16 v[18:21], v[158:161], v[224:227], v[18:21]
	v_mfma_f32_16x16x32_bf16 v[6:9], v[150:153], v[232:235], v[6:9]
	v_mfma_f32_16x16x32_bf16 v[2:5], v[158:161], v[232:235], v[2:5]
	s_barrier
	s_setprio 0
	s_add_i32 vcc_lo, vcc_lo, 2
	s_add_u32 s0, s0, 0x100
	s_addc_u32 s1, s1, 0
	s_add_u32 s58, s58, 0x100
	s_addc_u32 s59, s59, 0
.LBB0_186:
	s_add_u32 s40, s0, 0xfffc0080
	s_addc_u32 s41, s1, -1
	s_add_i32 s70, 0, 0x10000
	s_cmp_eq_u32 vcc_lo, 12
	s_cselect_b32 s43, s16, s41
	s_cselect_b32 s42, s17, s40
	s_cselect_b32 s41, s51, s59
	s_cselect_b32 s40, s53, s58
	s_add_i32 vcc_hi, 0, 0x14000
	v_add_u32_e32 v94, s70, v201
	v_add_u32_e32 v158, vcc_hi, v201
	ds_read_b128 v[74:77], v94
	ds_read_b128 v[78:81], v94 offset:1024
	ds_read_b128 v[90:93], v94 offset:2048
	ds_read_b128 v[94:97], v94 offset:3072
	ds_read_b128 v[146:149], v158
	ds_read_b128 v[150:153], v158 offset:1024
	ds_read_b128 v[154:157], v158 offset:2048
	ds_read_b128 v[158:161], v158 offset:3072
	v_lshl_add_u64 v[190:191], s[0:1], 0, v[182:183]
	s_add_i32 m0, s61, 0xc000
	ds_read_b128 v[186:189], v203
	ds_read_b128 v[208:211], v203 offset:1024
	ds_read_b128 v[212:215], v203 offset:2048
	ds_read_b128 v[216:219], v203 offset:3072
	ds_read_b128 v[220:223], v203 offset:4096
	ds_read_b128 v[224:227], v203 offset:5120
	ds_read_b128 v[228:231], v203 offset:6144
	ds_read_b128 v[232:235], v203 offset:7168
	global_load_lds_dwordx4 v[190:191], off
	v_lshl_add_u64 v[190:191], s[0:1], 0, v[184:185]
	s_add_i32 m0, s61, 0xe000
	s_nop 0
	global_load_lds_dwordx4 v[190:191], off
	s_waitcnt vmcnt(8)
	s_waitcnt lgkmcnt(0)
	s_setprio 1
	s_barrier
; #define PG8_STAGE(bufoff, gbase, voff) do { _Pragma("unroll") for (int _i = 0; _i < 2; ++_i) \
;         __builtin_amdgcn_global_load_lds((const unsigned*)((const char*)(gbase) + (voff)[_i]), (PG8_LAS unsigned*)(lds + (bufoff) + ldsw + _i * 8192), 16, 0, 0); } while (0)
; #define PG8_STAGEA(bufoff, gbase, voff) do { _Pragma("unroll") for (int _i = 0; _i < 2; ++_i) \
;         __builtin_amdgcn_global_load_lds((const unsigned*)((const char*)(gbase) + (voff)[_i]), (PG8_LAS unsigned*)(lds + (bufoff) + ldsw + _i * 8192), 16, 0, A_AUX); } while (0)
; #define PG8_LDA(dst, b, h) do { _Pragma("unroll") for (int m = 0; m < 4; ++m) _Pragma("unroll") for (int k = 0; k < 2; ++k) dst[m][k] = *(const PG8_LAS bf16x8*)(lds + PG8_SA(b, h) + aoff + m * 2048 + k * 1024); } while (0)
; #define PG8_MMA(ai, bj, At, Bt) do { __builtin_amdgcn_s_setprio(1); _Pragma("unroll") for (int m = 0; m < 4; ++m) _Pragma("unroll") for (int n = 0; n < 2; ++n) _Pragma("unroll") for (int k = 0; k < 2; ++k) \
;         acc[ai][bj][m][n] = __builtin_amdgcn_mfma_f32_16x16x32_bf16(Bt[n][k], At[m][k], acc[ai][bj][m][n], 0, 0, 0); __builtin_amdgcn_s_setprio(0); } while (0)
; #define PG8_WAIT_V(n) asm volatile("s_waitcnt vmcnt(" #n ")" ::: "memory")
; #define PG8_WAIT_L(n) asm volatile("s_waitcnt lgkmcnt(" #n ")" ::: "memory")
; #define PG8_BAR __builtin_amdgcn_s_barrier()
; #define PG8_SCHED __builtin_amdgcn_sched_barrier(0)
;     ...
;             PG8_WAIT_V(8); PG8_WAIT_L(0); PG8_BAR; PG8_MMA(0, 0, At, B0); PG8_MMA(0, 1, At, B1); PG8_BAR; PG8_SCHED;
;             PG8_LDA(At, 0, 1); PG8_STAGE(PG8_SB(0, 0), b2, voffB); PG8_STAGE(PG8_SB(0, 1), b2 + hstep, voffB); PG8_STAGEA(PG8_SA(0, 0), a2, voffA);
;             PG8_WAIT_V(8); PG8_WAIT_L(0); PG8_BAR; PG8_MMA(1, 0, At, B0); PG8_MMA(1, 1, At, B1); PG8_BAR; PG8_SCHED;
	v_mfma_f32_16x16x32_bf16 v[142:145], v[74:77], v[186:189], v[142:145]
	v_mfma_f32_16x16x32_bf16 v[138:141], v[90:93], v[186:189], v[138:141]
	v_mfma_f32_16x16x32_bf16 v[126:129], v[74:77], v[212:215], v[126:129]
	v_mfma_f32_16x16x32_bf16 v[122:125], v[90:93], v[212:215], v[122:125]
	v_mfma_f32_16x16x32_bf16 v[110:113], v[74:77], v[220:223], v[110:113]
	v_mfma_f32_16x16x32_bf16 v[106:109], v[90:93], v[220:223], v[106:109]
	v_mfma_f32_16x16x32_bf16 v[86:89], v[74:77], v[228:231], v[86:89]
	v_mfma_f32_16x16x32_bf16 v[82:85], v[90:93], v[228:231], v[82:85]
	v_mfma_f32_16x16x32_bf16 v[142:145], v[78:81], v[208:211], v[142:145]
	v_mfma_f32_16x16x32_bf16 v[138:141], v[94:97], v[208:211], v[138:141]
	v_mfma_f32_16x16x32_bf16 v[126:129], v[78:81], v[216:219], v[126:129]
	v_mfma_f32_16x16x32_bf16 v[122:125], v[94:97], v[216:219], v[122:125]
	v_mfma_f32_16x16x32_bf16 v[110:113], v[78:81], v[224:227], v[110:113]
	v_mfma_f32_16x16x32_bf16 v[106:109], v[94:97], v[224:227], v[106:109]
	v_mfma_f32_16x16x32_bf16 v[86:89], v[78:81], v[232:235], v[86:89]
	v_mfma_f32_16x16x32_bf16 v[82:85], v[94:97], v[232:235], v[82:85]
	s_setprio 0
	s_setprio 1
	v_mfma_f32_16x16x32_bf16 v[134:137], v[146:149], v[186:189], v[134:137]
	v_mfma_f32_16x16x32_bf16 v[130:133], v[154:157], v[186:189], v[130:133]
	v_mfma_f32_16x16x32_bf16 v[118:121], v[146:149], v[212:215], v[118:121]
	v_mfma_f32_16x16x32_bf16 v[114:117], v[154:157], v[212:215], v[114:117]
	v_mfma_f32_16x16x32_bf16 v[102:105], v[146:149], v[220:223], v[102:105]
	v_mfma_f32_16x16x32_bf16 v[98:101], v[154:157], v[220:223], v[98:101]
	v_mfma_f32_16x16x32_bf16 v[70:73], v[146:149], v[228:231], v[70:73]
	v_mfma_f32_16x16x32_bf16 v[66:69], v[154:157], v[228:231], v[66:69]
	v_mfma_f32_16x16x32_bf16 v[134:137], v[150:153], v[208:211], v[134:137]
	v_mfma_f32_16x16x32_bf16 v[130:133], v[158:161], v[208:211], v[130:133]
	v_mfma_f32_16x16x32_bf16 v[118:121], v[150:153], v[216:219], v[118:121]
	v_mfma_f32_16x16x32_bf16 v[114:117], v[158:161], v[216:219], v[114:117]
	v_mfma_f32_16x16x32_bf16 v[102:105], v[150:153], v[224:227], v[102:105]
	v_mfma_f32_16x16x32_bf16 v[98:101], v[158:161], v[224:227], v[98:101]
	v_mfma_f32_16x16x32_bf16 v[70:73], v[150:153], v[232:235], v[70:73]
	v_mfma_f32_16x16x32_bf16 v[66:69], v[158:161], v[232:235], v[66:69]
	s_barrier
	s_setprio 0
	s_add_i32 s70, s70, s60
	v_lshl_add_u64 v[190:191], s[40:41], 0, v[0:1]
	s_mov_b32 m0, s70
	ds_read_b128 v[186:189], v203 offset:16384
	ds_read_b128 v[208:211], v203 offset:17408
	ds_read_b128 v[212:215], v203 offset:18432
	ds_read_b128 v[216:219], v203 offset:19456
	ds_read_b128 v[220:223], v203 offset:20480
	ds_read_b128 v[224:227], v203 offset:21504
	ds_read_b128 v[228:231], v203 offset:22528
	ds_read_b128 v[232:235], v203 offset:23552
	global_load_lds_dwordx4 v[190:191], off
	s_add_i32 m0, s70, 0x2000
	s_add_u32 s70, s40, 0x40000
	v_lshl_add_u64 v[236:237], s[40:41], 0, v[174:175]
	s_addc_u32 s71, s41, 0
	s_add_i32 vcc_hi, vcc_hi, s60
	global_load_lds_dwordx4 v[236:237], off
	v_lshl_add_u64 v[238:239], s[70:71], 0, v[0:1]
	s_mov_b32 m0, vcc_hi
	v_lshl_add_u64 v[240:241], s[42:43], 0, v[176:177]
	global_load_lds_dwordx4 v[238:239], off
	v_lshl_add_u64 v[238:239], s[70:71], 0, v[174:175]
	s_add_i32 m0, vcc_hi, 0x2000
	s_nop 0
	global_load_lds_dwordx4 v[238:239], off
	v_lshl_add_u64 v[238:239], s[42:43], 0, v[178:179]
	s_mov_b32 m0, s61
	s_nop 0
	global_load_lds_dwordx4 v[238:239], off
	s_mov_b32 m0, s62
	s_nop 0
	global_load_lds_dwordx4 v[240:241], off
	s_waitcnt vmcnt(8)
	s_waitcnt lgkmcnt(0)
	s_setprio 1
	s_barrier
	v_mfma_f32_16x16x32_bf16 v[62:65], v[74:77], v[186:189], v[62:65]
	v_mfma_f32_16x16x32_bf16 v[58:61], v[90:93], v[186:189], v[58:61]
	v_mfma_f32_16x16x32_bf16 v[46:49], v[74:77], v[212:215], v[46:49]
	v_mfma_f32_16x16x32_bf16 v[42:45], v[90:93], v[212:215], v[42:45]
	v_mfma_f32_16x16x32_bf16 v[30:33], v[74:77], v[220:223], v[30:33]
	v_mfma_f32_16x16x32_bf16 v[26:29], v[90:93], v[220:223], v[26:29]
	v_mfma_f32_16x16x32_bf16 v[14:17], v[74:77], v[228:231], v[14:17]
	v_mfma_f32_16x16x32_bf16 v[10:13], v[90:93], v[228:231], v[10:13]
	v_mfma_f32_16x16x32_bf16 v[62:65], v[78:81], v[208:211], v[62:65]
	v_mfma_f32_16x16x32_bf16 v[58:61], v[94:97], v[208:211], v[58:61]
	v_mfma_f32_16x16x32_bf16 v[46:49], v[78:81], v[216:219], v[46:49]
	v_mfma_f32_16x16x32_bf16 v[42:45], v[94:97], v[216:219], v[42:45]
	v_mfma_f32_16x16x32_bf16 v[30:33], v[78:81], v[224:227], v[30:33]
	v_mfma_f32_16x16x32_bf16 v[26:29], v[94:97], v[224:227], v[26:29]
	v_mfma_f32_16x16x32_bf16 v[14:17], v[78:81], v[232:235], v[14:17]
	v_mfma_f32_16x16x32_bf16 v[10:13], v[94:97], v[232:235], v[10:13]
	s_setprio 0
	s_setprio 1
	v_mfma_f32_16x16x32_bf16 v[54:57], v[146:149], v[186:189], v[54:57]
	v_mfma_f32_16x16x32_bf16 v[50:53], v[154:157], v[186:189], v[50:53]
	v_mfma_f32_16x16x32_bf16 v[38:41], v[146:149], v[212:215], v[38:41]
	v_mfma_f32_16x16x32_bf16 v[34:37], v[154:157], v[212:215], v[34:37]
	v_mfma_f32_16x16x32_bf16 v[22:25], v[146:149], v[220:223], v[22:25]
	v_mfma_f32_16x16x32_bf16 v[18:21], v[154:157], v[220:223], v[18:21]
	v_mfma_f32_16x16x32_bf16 v[6:9], v[146:149], v[228:231], v[6:9]
	v_mfma_f32_16x16x32_bf16 v[2:5], v[154:157], v[228:231], v[2:5]
	v_mfma_f32_16x16x32_bf16 v[54:57], v[150:153], v[208:211], v[54:57]
	v_mfma_f32_16x16x32_bf16 v[50:53], v[158:161], v[208:211], v[50:53]
	v_mfma_f32_16x16x32_bf16 v[38:41], v[150:153], v[216:219], v[38:41]
	v_mfma_f32_16x16x32_bf16 v[34:37], v[158:161], v[216:219], v[34:37]
	v_mfma_f32_16x16x32_bf16 v[22:25], v[150:153], v[224:227], v[22:25]
	v_mfma_f32_16x16x32_bf16 v[18:21], v[158:161], v[224:227], v[18:21]
	v_mfma_f32_16x16x32_bf16 v[6:9], v[150:153], v[232:235], v[6:9]
	v_mfma_f32_16x16x32_bf16 v[2:5], v[158:161], v[232:235], v[2:5]
	s_barrier
; #define PG8_STAGEA(bufoff, gbase, voff) do { _Pragma("unroll") for (int _i = 0; _i < 2; ++_i) \
;         __builtin_amdgcn_global_load_lds((const unsigned*)((const char*)(gbase) + (voff)[_i]), (PG8_LAS unsigned*)(lds + (bufoff) + ldsw + _i * 8192), 16, 0, A_AUX); } while (0)
; #define PG8_LDA(dst, b, h) do { _Pragma("unroll") for (int m = 0; m < 4; ++m) _Pragma("unroll") for (int k = 0; k < 2; ++k) dst[m][k] = *(const PG8_LAS bf16x8*)(lds + PG8_SA(b, h) + aoff + m * 2048 + k * 1024); } while (0)
; #define PG8_LDB(dst, b, h) do { _Pragma("unroll") for (int n = 0; n < 2; ++n) _Pragma("unroll") for (int k = 0; k < 2; ++k) dst[n][k] = *(const PG8_LAS bf16x8*)(lds + PG8_SB(b, h) + boff + n * 2048 + k * 1024); } while (0)
; #define PG8_MMA(ai, bj, At, Bt) do { __builtin_amdgcn_s_setprio(1); _Pragma("unroll") for (int m = 0; m < 4; ++m) _Pragma("unroll") for (int n = 0; n < 2; ++n) _Pragma("unroll") for (int k = 0; k < 2; ++k) \
;         acc[ai][bj][m][n] = __builtin_amdgcn_mfma_f32_16x16x32_bf16(Bt[n][k], At[m][k], acc[ai][bj][m][n], 0, 0, 0); __builtin_amdgcn_s_setprio(0); } while (0)
; #define PG8_WAIT_V(n) asm volatile("s_waitcnt vmcnt(" #n ")" ::: "memory")
; #define PG8_WAIT_L(n) asm volatile("s_waitcnt lgkmcnt(" #n ")" ::: "memory")
; #define PG8_BAR __builtin_amdgcn_s_barrier()
; #define PG8_SCHED __builtin_amdgcn_sched_barrier(0)
;     ...
;             PG8_LDB(B0, 1, 0); PG8_LDB(B1, 1, 1); PG8_SCHED; PG8_LDA(At, 1, 0); PG8_STAGEA(PG8_SA(0, 1), a2 + hstep, voffA);
;             PG8_WAIT_V(8); PG8_WAIT_L(0); PG8_BAR; PG8_MMA(0, 0, At, B0); PG8_MMA(0, 1, At, B1); PG8_BAR; PG8_SCHED;
	s_setprio 0
	s_add_i32 s70, 0, 0x18000
	s_add_i32 s71, 0, 0x1c000
	v_add_u32_e32 v94, s70, v201
	v_add_u32_e32 v158, s71, v201
	ds_read_b128 v[74:77], v94
	ds_read_b128 v[78:81], v94 offset:1024
	ds_read_b128 v[90:93], v94 offset:2048
	ds_read_b128 v[94:97], v94 offset:3072
	ds_read_b128 v[146:149], v158
	ds_read_b128 v[150:153], v158 offset:1024
	ds_read_b128 v[154:157], v158 offset:2048
	ds_read_b128 v[158:161], v158 offset:3072
	s_add_u32 s42, s42, 0x40000
	s_addc_u32 s43, s43, 0
	s_mov_b32 m0, s63
	v_lshl_add_u64 v[242:243], s[42:43], 0, v[178:179]
	ds_read_b128 v[186:189], v203 offset:32768
	ds_read_b128 v[208:211], v203 offset:33792
	ds_read_b128 v[212:215], v203 offset:34816
	ds_read_b128 v[216:219], v203 offset:35840
	ds_read_b128 v[220:223], v203 offset:36864
	ds_read_b128 v[224:227], v203 offset:37888
	ds_read_b128 v[228:231], v203 offset:38912
	ds_read_b128 v[232:235], v203 offset:39936
	global_load_lds_dwordx4 v[242:243], off
	v_lshl_add_u64 v[242:243], s[42:43], 0, v[176:177]
	s_mov_b32 m0, s64
	s_nop 0
	global_load_lds_dwordx4 v[242:243], off
	s_waitcnt vmcnt(8)
	s_waitcnt lgkmcnt(0)
	s_setprio 1
	s_barrier
	v_mfma_f32_16x16x32_bf16 v[142:145], v[74:77], v[186:189], v[142:145]
	v_mfma_f32_16x16x32_bf16 v[138:141], v[90:93], v[186:189], v[138:141]
	v_mfma_f32_16x16x32_bf16 v[126:129], v[74:77], v[212:215], v[126:129]
	v_mfma_f32_16x16x32_bf16 v[122:125], v[90:93], v[212:215], v[122:125]
	v_mfma_f32_16x16x32_bf16 v[110:113], v[74:77], v[220:223], v[110:113]
	v_mfma_f32_16x16x32_bf16 v[106:109], v[90:93], v[220:223], v[106:109]
	v_mfma_f32_16x16x32_bf16 v[86:89], v[74:77], v[228:231], v[86:89]
	v_mfma_f32_16x16x32_bf16 v[82:85], v[90:93], v[228:231], v[82:85]
	v_mfma_f32_16x16x32_bf16 v[142:145], v[78:81], v[208:211], v[142:145]
	v_mfma_f32_16x16x32_bf16 v[138:141], v[94:97], v[208:211], v[138:141]
	v_mfma_f32_16x16x32_bf16 v[126:129], v[78:81], v[216:219], v[126:129]
	v_mfma_f32_16x16x32_bf16 v[122:125], v[94:97], v[216:219], v[122:125]
	v_mfma_f32_16x16x32_bf16 v[110:113], v[78:81], v[224:227], v[110:113]
	v_mfma_f32_16x16x32_bf16 v[106:109], v[94:97], v[224:227], v[106:109]
	v_mfma_f32_16x16x32_bf16 v[86:89], v[78:81], v[232:235], v[86:89]
	v_mfma_f32_16x16x32_bf16 v[82:85], v[94:97], v[232:235], v[82:85]
	s_setprio 0
	s_setprio 1
	v_mfma_f32_16x16x32_bf16 v[134:137], v[146:149], v[186:189], v[134:137]
	v_mfma_f32_16x16x32_bf16 v[130:133], v[154:157], v[186:189], v[130:133]
	v_mfma_f32_16x16x32_bf16 v[118:121], v[146:149], v[212:215], v[118:121]
	v_mfma_f32_16x16x32_bf16 v[114:117], v[154:157], v[212:215], v[114:117]
	v_mfma_f32_16x16x32_bf16 v[102:105], v[146:149], v[220:223], v[102:105]
	v_mfma_f32_16x16x32_bf16 v[98:101], v[154:157], v[220:223], v[98:101]
	v_mfma_f32_16x16x32_bf16 v[70:73], v[146:149], v[228:231], v[70:73]
	v_mfma_f32_16x16x32_bf16 v[66:69], v[154:157], v[228:231], v[66:69]
	v_mfma_f32_16x16x32_bf16 v[134:137], v[150:153], v[208:211], v[134:137]
	v_mfma_f32_16x16x32_bf16 v[130:133], v[158:161], v[208:211], v[130:133]
	v_mfma_f32_16x16x32_bf16 v[118:121], v[150:153], v[216:219], v[118:121]
	v_mfma_f32_16x16x32_bf16 v[114:117], v[158:161], v[216:219], v[114:117]
	v_mfma_f32_16x16x32_bf16 v[102:105], v[150:153], v[224:227], v[102:105]
	v_mfma_f32_16x16x32_bf16 v[98:101], v[158:161], v[224:227], v[98:101]
	v_mfma_f32_16x16x32_bf16 v[70:73], v[150:153], v[232:235], v[70:73]
	v_mfma_f32_16x16x32_bf16 v[66:69], v[158:161], v[232:235], v[66:69]
	s_barrier
; #define PG8_STAGE(bufoff, gbase, voff) do { _Pragma("unroll") for (int _i = 0; _i < 2; ++_i) \
;         __builtin_amdgcn_global_load_lds((const unsigned*)((const char*)(gbase) + (voff)[_i]), (PG8_LAS unsigned*)(lds + (bufoff) + ldsw + _i * 8192), 16, 0, 0); } while (0)
; #define PG8_STAGEA(bufoff, gbase, voff) do { _Pragma("unroll") for (int _i = 0; _i < 2; ++_i) \
;         __builtin_amdgcn_global_load_lds((const unsigned*)((const char*)(gbase) + (voff)[_i]), (PG8_LAS unsigned*)(lds + (bufoff) + ldsw + _i * 8192), 16, 0, A_AUX); } while (0)
; #define PG8_LDA(dst, b, h) do { _Pragma("unroll") for (int m = 0; m < 4; ++m) _Pragma("unroll") for (int k = 0; k < 2; ++k) dst[m][k] = *(const PG8_LAS bf16x8*)(lds + PG8_SA(b, h) + aoff + m * 2048 + k * 1024); } while (0)
; #define PG8_MMA(ai, bj, At, Bt) do { __builtin_amdgcn_s_setprio(1); _Pragma("unroll") for (int m = 0; m < 4; ++m) _Pragma("unroll") for (int n = 0; n < 2; ++n) _Pragma("unroll") for (int k = 0; k < 2; ++k) \
;         acc[ai][bj][m][n] = __builtin_amdgcn_mfma_f32_16x16x32_bf16(Bt[n][k], At[m][k], acc[ai][bj][m][n], 0, 0, 0); __builtin_amdgcn_s_setprio(0); } while (0)
; #define PG8_WAIT_V(n) asm volatile("s_waitcnt vmcnt(" #n ")" ::: "memory")
; #define PG8_WAIT_L(n) asm volatile("s_waitcnt lgkmcnt(" #n ")" ::: "memory")
; #define PG8_BAR __builtin_amdgcn_s_barrier()
; #define PG8_SCHED __builtin_amdgcn_sched_barrier(0)
;     ...
;             PG8_LDA(At, 1, 1); PG8_STAGE(PG8_SB(1, 0), b3, voffB); PG8_STAGE(PG8_SB(1, 1), b3 + hstep, voffB); PG8_STAGEA(PG8_SA(1, 0), a3, voffA);
;             PG8_WAIT_V(8); PG8_WAIT_L(0); PG8_BAR; PG8_MMA(1, 0, At, B0); PG8_MMA(1, 1, At, B1); PG8_BAR; PG8_SCHED;
;     ...
;         if constexpr (ALIGN_EPI) { if (wr == 0) PG8_BAR; }
	s_setprio 0
	s_add_i32 s42, s70, s60
	v_lshl_add_u64 v[190:191], v[190:191], 0, s[8:9]
	s_mov_b32 m0, s42
	ds_read_b128 v[186:189], v203 offset:49152
	ds_read_b128 v[208:211], v203 offset:50176
	ds_read_b128 v[212:215], v203 offset:51200
	ds_read_b128 v[216:219], v203 offset:52224
	ds_read_b128 v[220:223], v203 offset:53248
	ds_read_b128 v[224:227], v203 offset:54272
	ds_read_b128 v[228:231], v203 offset:55296
	ds_read_b128 v[232:235], v203 offset:56320
	global_load_lds_dwordx4 v[190:191], off
	s_add_i32 m0, s42, 0x2000
	s_add_u32 s40, s40, 0x40080
	v_lshl_add_u64 v[190:191], v[236:237], 0, s[8:9]
	s_addc_u32 s41, s41, 0
	s_add_i32 s42, s71, s60
	global_load_lds_dwordx4 v[190:191], off
	v_lshl_add_u64 v[190:191], s[40:41], 0, v[0:1]
	s_mov_b32 m0, s42
	s_nop 0
	global_load_lds_dwordx4 v[190:191], off
	v_lshl_add_u64 v[190:191], s[40:41], 0, v[174:175]
	s_add_i32 m0, s42, 0x2000
	s_nop 0
	global_load_lds_dwordx4 v[190:191], off
	v_lshl_add_u64 v[190:191], v[238:239], 0, s[8:9]
	s_mov_b32 m0, s72
	s_nop 0
	global_load_lds_dwordx4 v[190:191], off
	v_lshl_add_u64 v[190:191], v[240:241], 0, s[8:9]
	s_mov_b32 m0, s73
	s_nop 0
	global_load_lds_dwordx4 v[190:191], off
	s_waitcnt vmcnt(8)
	s_waitcnt lgkmcnt(0)
	s_setprio 1
	s_barrier
	v_mfma_f32_16x16x32_bf16 v[62:65], v[74:77], v[186:189], v[62:65]
	v_mfma_f32_16x16x32_bf16 v[58:61], v[90:93], v[186:189], v[58:61]
	v_mfma_f32_16x16x32_bf16 v[46:49], v[74:77], v[212:215], v[46:49]
	v_mfma_f32_16x16x32_bf16 v[42:45], v[90:93], v[212:215], v[42:45]
	v_mfma_f32_16x16x32_bf16 v[30:33], v[74:77], v[220:223], v[30:33]
	v_mfma_f32_16x16x32_bf16 v[26:29], v[90:93], v[220:223], v[26:29]
	v_mfma_f32_16x16x32_bf16 v[14:17], v[74:77], v[228:231], v[14:17]
	v_mfma_f32_16x16x32_bf16 v[10:13], v[90:93], v[228:231], v[10:13]
	v_mfma_f32_16x16x32_bf16 v[62:65], v[78:81], v[208:211], v[62:65]
	v_mfma_f32_16x16x32_bf16 v[58:61], v[94:97], v[208:211], v[58:61]
	v_mfma_f32_16x16x32_bf16 v[46:49], v[78:81], v[216:219], v[46:49]
	v_mfma_f32_16x16x32_bf16 v[42:45], v[94:97], v[216:219], v[42:45]
	v_mfma_f32_16x16x32_bf16 v[30:33], v[78:81], v[224:227], v[30:33]
	v_mfma_f32_16x16x32_bf16 v[26:29], v[94:97], v[224:227], v[26:29]
	v_mfma_f32_16x16x32_bf16 v[14:17], v[78:81], v[232:235], v[14:17]
	v_mfma_f32_16x16x32_bf16 v[10:13], v[94:97], v[232:235], v[10:13]
	s_setprio 0
	s_setprio 1
	v_mfma_f32_16x16x32_bf16 v[54:57], v[146:149], v[186:189], v[54:57]
	v_mfma_f32_16x16x32_bf16 v[50:53], v[154:157], v[186:189], v[50:53]
	v_mfma_f32_16x16x32_bf16 v[38:41], v[146:149], v[212:215], v[38:41]
	v_mfma_f32_16x16x32_bf16 v[34:37], v[154:157], v[212:215], v[34:37]
	v_mfma_f32_16x16x32_bf16 v[22:25], v[146:149], v[220:223], v[22:25]
	v_mfma_f32_16x16x32_bf16 v[18:21], v[154:157], v[220:223], v[18:21]
	v_mfma_f32_16x16x32_bf16 v[6:9], v[146:149], v[228:231], v[6:9]
	v_mfma_f32_16x16x32_bf16 v[2:5], v[154:157], v[228:231], v[2:5]
	v_mfma_f32_16x16x32_bf16 v[54:57], v[150:153], v[208:211], v[54:57]
	v_mfma_f32_16x16x32_bf16 v[50:53], v[158:161], v[208:211], v[50:53]
	v_mfma_f32_16x16x32_bf16 v[38:41], v[150:153], v[216:219], v[38:41]
	v_mfma_f32_16x16x32_bf16 v[34:37], v[158:161], v[216:219], v[34:37]
	v_mfma_f32_16x16x32_bf16 v[22:25], v[150:153], v[224:227], v[22:25]
	v_mfma_f32_16x16x32_bf16 v[18:21], v[158:161], v[224:227], v[18:21]
	v_mfma_f32_16x16x32_bf16 v[6:9], v[150:153], v[232:235], v[6:9]
	v_mfma_f32_16x16x32_bf16 v[2:5], v[158:161], v[232:235], v[2:5]
	s_barrier
	s_setprio 0
	s_add_i32 vcc_lo, vcc_lo, 2
	s_add_u32 s0, s0, 0x100
	s_addc_u32 s1, s1, 0
	s_add_u32 s58, s58, 0x100
	s_addc_u32 s59, s59, 0
	s_cmp_gt_u32 vcc_lo, 13
	s_cbranch_scc0 .LBB0_186
	s_and_b64 vcc, exec, s[46:47]
	s_cbranch_vccz .LBB0_189
	s_barrier

; #define PG8_STAGE(bufoff, gbase, voff) do { _Pragma("unroll") for (int _i = 0; _i < 2; ++_i) \
;         __builtin_amdgcn_global_load_lds((const unsigned*)((const char*)(gbase) + (voff)[_i]), (PG8_LAS unsigned*)(lds + (bufoff) + ldsw + _i * 8192), 16, 0, 0); } while (0)
; #define PG8_STAGEA(bufoff, gbase, voff) do { _Pragma("unroll") for (int _i = 0; _i < 2; ++_i) \
;         __builtin_amdgcn_global_load_lds((const unsigned*)((const char*)(gbase) + (voff)[_i]), (PG8_LAS unsigned*)(lds + (bufoff) + ldsw + _i * 8192), 16, 0, A_AUX); } while (0)
; #define PG8_LDA(dst, b, h) do { _Pragma("unroll") for (int m = 0; m < 4; ++m) _Pragma("unroll") for (int k = 0; k < 2; ++k) dst[m][k] = *(const PG8_LAS bf16x8*)(lds + PG8_SA(b, h) + aoff + m * 2048 + k * 1024); } while (0)
; #define PG8_LDB(dst, b, h) do { _Pragma("unroll") for (int n = 0; n < 2; ++n) _Pragma("unroll") for (int k = 0; k < 2; ++k) dst[n][k] = *(const PG8_LAS bf16x8*)(lds + PG8_SB(b, h) + boff + n * 2048 + k * 1024); } while (0)
; #define PG8_WAIT_V(n) asm volatile("s_waitcnt vmcnt(" #n ")" ::: "memory")
; #define PG8_WAIT_L(n) asm volatile("s_waitcnt lgkmcnt(" #n ")" ::: "memory")
; #define PG8_BAR __builtin_amdgcn_s_barrier()
;     ...
;         const bool has_next = S.next(ui + 1, nxt);
;         const char* nA = has_next ? (const char*)g.A + (size_t)nxt.pm * tstep : cA; const char* nB = has_next ? (const char*)g.Bt + (size_t)nxt.pn * tstep : cB;
;         for (int t = 0; t < nt; t += 2) {
;             const bool last = (t == nt - 2);
;             const char* a1 = cA + (size_t)(t + 1) * kstep;
;             const char* a2 = last ? nA : cA + (size_t)(t + 2) * kstep; const char* b2 = last ? nB : cB + (size_t)(t + 2) * kstep;
;             const char* a3 = a2 + kstep; const char* b3 = b2 + kstep;
;             if (last && has_next) S.a_ready(nxt);
;             if constexpr (SP2) {
;             PG8_LDB(B0, 0, 0); PG8_LDB(B1, 0, 1); PG8_SCHED; PG8_LDA(At, 0, 0); PG8_STAGEA(PG8_SA(1, 1), a1 + hstep, voffA);
;             PG8_WAIT_V(8); PG8_WAIT_L(0); PG8_BAR; PG8_MMA(0, 0, At, B0); PG8_MMA(0, 1, At, B1); PG8_BAR; PG8_SCHED;
;             PG8_LDA(At, 0, 1); PG8_STAGE(PG8_SB(0, 0), b2, voffB); PG8_STAGE(PG8_SB(0, 1), b2 + hstep, voffB); PG8_STAGEA(PG8_SA(0, 0), a2, voffA);
;             PG8_WAIT_V(8); PG8_WAIT_L(0); PG8_BAR; PG8_MMA(1, 0, At, B0); PG8_MMA(1, 1, At, B1); PG8_BAR; PG8_SCHED;
.LBB0_442:
	s_ashr_i32 s43, s42, 31
	s_lshl_b64 s[16:17], s[42:43], 19
	s_add_u32 s44, s24, s16
	s_addc_u32 s45, s25, s17
	s_and_b64 s[16:17], s[38:39], exec
	s_cselect_b32 s16, s45, s49
	s_cselect_b32 s17, s44, s48
	s_ashr_i32 s41, s40, 31
	s_lshl_b64 s[46:47], s[40:41], 19
	s_add_u32 s46, s23, s46
	s_addc_u32 s47, s54, s47
	s_and_b64 s[52:53], s[38:39], exec
	s_cselect_b32 s41, s47, s51
	s_cselect_b32 s43, s46, s50
	s_add_u32 s48, s48, 0x40080
	s_addc_u32 s49, s49, 0
	s_add_u32 s65, s50, 0x100
	s_addc_u32 s72, s51, 0
	s_mov_b32 s73, -2
	s_add_u32 s50, s48, 0xfffc0080
	s_addc_u32 s51, s49, -1
	s_add_i32 s70, 0, 0x10000
	s_cmp_eq_u32 s73, 12
	s_cselect_b32 s53, s16, s51
	s_cselect_b32 s52, s17, s50
	v_add_u32_e32 v140, s70, v143
	s_cselect_b32 s51, s41, s72
	s_cselect_b32 s50, s43, s65
	s_add_i32 s76, 0, 0x14000
	ds_read_b128 v[146:149], v140
	ds_read_b128 v[150:153], v140 offset:1024
	ds_read_b128 v[154:157], v140 offset:2048
	ds_read_b128 v[158:161], v140 offset:3072
	v_add_u32_e32 v140, s76, v143
	ds_read_b128 v[174:177], v140
	ds_read_b128 v[178:181], v140 offset:1024
	ds_read_b128 v[182:185], v140 offset:2048
	ds_read_b128 v[186:189], v140 offset:3072
	v_lshl_add_u64 v[140:141], s[48:49], 0, v[136:137]
	s_add_i32 m0, s56, 0xc000
	ds_read_b128 v[200:203], v145
	ds_read_b128 v[208:211], v145 offset:1024
	ds_read_b128 v[212:215], v145 offset:2048
	ds_read_b128 v[216:219], v145 offset:3072
	ds_read_b128 v[220:223], v145 offset:4096
	ds_read_b128 v[224:227], v145 offset:5120
	ds_read_b128 v[228:231], v145 offset:6144
	ds_read_b128 v[232:235], v145 offset:7168
	global_load_lds_dwordx4 v[140:141], off
	v_lshl_add_u64 v[140:141], s[48:49], 0, v[138:139]
	s_add_i32 m0, s56, 0xe000
	s_nop 0
	global_load_lds_dwordx4 v[140:141], off
	s_waitcnt vmcnt(8)
	s_waitcnt lgkmcnt(0)
	s_setprio 1
	s_barrier
	v_mfma_f32_16x16x32_bf16 v[126:129], v[146:149], v[200:203], 0
	v_mfma_f32_16x16x32_bf16 v[122:125], v[154:157], v[200:203], 0
	v_mfma_f32_16x16x32_bf16 v[114:117], v[146:149], v[212:215], 0
	v_mfma_f32_16x16x32_bf16 v[106:109], v[154:157], v[212:215], 0
	v_mfma_f32_16x16x32_bf16 v[98:101], v[146:149], v[220:223], 0
	v_mfma_f32_16x16x32_bf16 v[90:93], v[154:157], v[220:223], 0
	v_mfma_f32_16x16x32_bf16 v[82:85], v[146:149], v[228:231], 0
	v_mfma_f32_16x16x32_bf16 v[74:77], v[154:157], v[228:231], 0
	v_mfma_f32_16x16x32_bf16 v[126:129], v[150:153], v[208:211], v[126:129]
	v_mfma_f32_16x16x32_bf16 v[122:125], v[158:161], v[208:211], v[122:125]
	v_mfma_f32_16x16x32_bf16 v[114:117], v[150:153], v[216:219], v[114:117]
	v_mfma_f32_16x16x32_bf16 v[106:109], v[158:161], v[216:219], v[106:109]
	v_mfma_f32_16x16x32_bf16 v[98:101], v[150:153], v[224:227], v[98:101]
	v_mfma_f32_16x16x32_bf16 v[90:93], v[158:161], v[224:227], v[90:93]
	v_mfma_f32_16x16x32_bf16 v[82:85], v[150:153], v[232:235], v[82:85]
	v_mfma_f32_16x16x32_bf16 v[74:77], v[158:161], v[232:235], v[74:77]
	s_setprio 0
	s_setprio 1
	v_mfma_f32_16x16x32_bf16 v[118:121], v[174:177], v[200:203], 0
	v_mfma_f32_16x16x32_bf16 v[110:113], v[182:185], v[200:203], 0
	v_mfma_f32_16x16x32_bf16 v[102:105], v[174:177], v[212:215], 0
	v_mfma_f32_16x16x32_bf16 v[94:97], v[182:185], v[212:215], 0
	v_mfma_f32_16x16x32_bf16 v[86:89], v[174:177], v[220:223], 0
	v_mfma_f32_16x16x32_bf16 v[78:81], v[182:185], v[220:223], 0
	v_mfma_f32_16x16x32_bf16 v[70:73], v[174:177], v[228:231], 0
	v_mfma_f32_16x16x32_bf16 v[66:69], v[182:185], v[228:231], 0
	v_mfma_f32_16x16x32_bf16 v[118:121], v[178:181], v[208:211], v[118:121]
	v_mfma_f32_16x16x32_bf16 v[110:113], v[186:189], v[208:211], v[110:113]
	v_mfma_f32_16x16x32_bf16 v[102:105], v[178:181], v[216:219], v[102:105]
	v_mfma_f32_16x16x32_bf16 v[94:97], v[186:189], v[216:219], v[94:97]
	v_mfma_f32_16x16x32_bf16 v[86:89], v[178:181], v[224:227], v[86:89]
	v_mfma_f32_16x16x32_bf16 v[78:81], v[186:189], v[224:227], v[78:81]
	v_mfma_f32_16x16x32_bf16 v[70:73], v[178:181], v[232:235], v[70:73]
	v_mfma_f32_16x16x32_bf16 v[66:69], v[186:189], v[232:235], v[66:69]
	s_barrier
	s_setprio 0
	s_add_i32 s70, s70, s55
	v_lshl_add_u64 v[140:141], s[50:51], 0, v[0:1]
	s_mov_b32 m0, s70
	ds_read_b128 v[200:203], v145 offset:16384
	ds_read_b128 v[208:211], v145 offset:17408
	ds_read_b128 v[212:215], v145 offset:18432
	ds_read_b128 v[216:219], v145 offset:19456
	ds_read_b128 v[220:223], v145 offset:20480
	ds_read_b128 v[224:227], v145 offset:21504
	ds_read_b128 v[228:231], v145 offset:22528
	ds_read_b128 v[232:235], v145 offset:23552
	global_load_lds_dwordx4 v[140:141], off
	s_add_i32 m0, s70, 0x2000
	s_add_u32 s70, s50, 0x40000
	v_lshl_add_u64 v[190:191], s[50:51], 0, v[130:131]
	s_addc_u32 s71, s51, 0
	s_add_i32 s76, s76, s55
	global_load_lds_dwordx4 v[190:191], off
	v_lshl_add_u64 v[236:237], s[70:71], 0, v[0:1]
	s_mov_b32 m0, s76
	v_lshl_add_u64 v[238:239], s[52:53], 0, v[132:133]
	global_load_lds_dwordx4 v[236:237], off
	v_lshl_add_u64 v[236:237], s[70:71], 0, v[130:131]
	s_add_i32 m0, s76, 0x2000
	s_nop 0
	global_load_lds_dwordx4 v[236:237], off
	v_lshl_add_u64 v[236:237], s[52:53], 0, v[134:135]
	s_mov_b32 m0, s56
	s_nop 0
	global_load_lds_dwordx4 v[236:237], off
	s_mov_b32 m0, s57
	s_nop 0
	global_load_lds_dwordx4 v[238:239], off
	s_waitcnt vmcnt(8)
	s_waitcnt lgkmcnt(0)
	s_setprio 1
	s_barrier
; #define PG8_STAGEA(bufoff, gbase, voff) do { _Pragma("unroll") for (int _i = 0; _i < 2; ++_i) \
;         __builtin_amdgcn_global_load_lds((const unsigned*)((const char*)(gbase) + (voff)[_i]), (PG8_LAS unsigned*)(lds + (bufoff) + ldsw + _i * 8192), 16, 0, A_AUX); } while (0)
; #define PG8_LDA(dst, b, h) do { _Pragma("unroll") for (int m = 0; m < 4; ++m) _Pragma("unroll") for (int k = 0; k < 2; ++k) dst[m][k] = *(const PG8_LAS bf16x8*)(lds + PG8_SA(b, h) + aoff + m * 2048 + k * 1024); } while (0)
; #define PG8_LDB(dst, b, h) do { _Pragma("unroll") for (int n = 0; n < 2; ++n) _Pragma("unroll") for (int k = 0; k < 2; ++k) dst[n][k] = *(const PG8_LAS bf16x8*)(lds + PG8_SB(b, h) + boff + n * 2048 + k * 1024); } while (0)
; #define PG8_MMA(ai, bj, At, Bt) do { __builtin_amdgcn_s_setprio(1); _Pragma("unroll") for (int m = 0; m < 4; ++m) _Pragma("unroll") for (int n = 0; n < 2; ++n) _Pragma("unroll") for (int k = 0; k < 2; ++k) \
;         acc[ai][bj][m][n] = __builtin_amdgcn_mfma_f32_16x16x32_bf16(Bt[n][k], At[m][k], acc[ai][bj][m][n], 0, 0, 0); __builtin_amdgcn_s_setprio(0); } while (0)
; #define PG8_WAIT_V(n) asm volatile("s_waitcnt vmcnt(" #n ")" ::: "memory")
; #define PG8_WAIT_L(n) asm volatile("s_waitcnt lgkmcnt(" #n ")" ::: "memory")
; #define PG8_BAR __builtin_amdgcn_s_barrier()
; #define PG8_SCHED __builtin_amdgcn_sched_barrier(0)
;     ...
;             PG8_WAIT_V(8); PG8_WAIT_L(0); PG8_BAR; PG8_MMA(1, 0, At, B0); PG8_MMA(1, 1, At, B1); PG8_BAR; PG8_SCHED;
;             PG8_LDB(B0, 1, 0); PG8_LDB(B1, 1, 1); PG8_SCHED; PG8_LDA(At, 1, 0); PG8_STAGEA(PG8_SA(0, 1), a2 + hstep, voffA);
;             PG8_WAIT_V(8); PG8_WAIT_L(0); PG8_BAR; PG8_MMA(0, 0, At, B0); PG8_MMA(0, 1, At, B1); PG8_BAR; PG8_SCHED;
	v_mfma_f32_16x16x32_bf16 v[62:65], v[146:149], v[200:203], 0
	v_mfma_f32_16x16x32_bf16 v[58:61], v[154:157], v[200:203], 0
	v_mfma_f32_16x16x32_bf16 v[50:53], v[146:149], v[212:215], 0
	v_mfma_f32_16x16x32_bf16 v[42:45], v[154:157], v[212:215], 0
	v_mfma_f32_16x16x32_bf16 v[34:37], v[146:149], v[220:223], 0
	v_mfma_f32_16x16x32_bf16 v[26:29], v[154:157], v[220:223], 0
	v_mfma_f32_16x16x32_bf16 v[18:21], v[146:149], v[228:231], 0
	v_mfma_f32_16x16x32_bf16 v[10:13], v[154:157], v[228:231], 0
	v_mfma_f32_16x16x32_bf16 v[62:65], v[150:153], v[208:211], v[62:65]
	v_mfma_f32_16x16x32_bf16 v[58:61], v[158:161], v[208:211], v[58:61]
	v_mfma_f32_16x16x32_bf16 v[50:53], v[150:153], v[216:219], v[50:53]
	v_mfma_f32_16x16x32_bf16 v[42:45], v[158:161], v[216:219], v[42:45]
	v_mfma_f32_16x16x32_bf16 v[34:37], v[150:153], v[224:227], v[34:37]
	v_mfma_f32_16x16x32_bf16 v[26:29], v[158:161], v[224:227], v[26:29]
	v_mfma_f32_16x16x32_bf16 v[18:21], v[150:153], v[232:235], v[18:21]
	v_mfma_f32_16x16x32_bf16 v[10:13], v[158:161], v[232:235], v[10:13]
	s_setprio 0
	s_setprio 1
	v_mfma_f32_16x16x32_bf16 v[54:57], v[174:177], v[200:203], 0
	v_mfma_f32_16x16x32_bf16 v[46:49], v[182:185], v[200:203], 0
	v_mfma_f32_16x16x32_bf16 v[38:41], v[174:177], v[212:215], 0
	v_mfma_f32_16x16x32_bf16 v[30:33], v[182:185], v[212:215], 0
	v_mfma_f32_16x16x32_bf16 v[22:25], v[174:177], v[220:223], 0
	v_mfma_f32_16x16x32_bf16 v[14:17], v[182:185], v[220:223], 0
	v_mfma_f32_16x16x32_bf16 v[6:9], v[174:177], v[228:231], 0
	v_mfma_f32_16x16x32_bf16 v[2:5], v[182:185], v[228:231], 0
	v_mfma_f32_16x16x32_bf16 v[54:57], v[178:181], v[208:211], v[54:57]
	v_mfma_f32_16x16x32_bf16 v[46:49], v[186:189], v[208:211], v[46:49]
	v_mfma_f32_16x16x32_bf16 v[38:41], v[178:181], v[216:219], v[38:41]
	v_mfma_f32_16x16x32_bf16 v[30:33], v[186:189], v[216:219], v[30:33]
	v_mfma_f32_16x16x32_bf16 v[22:25], v[178:181], v[224:227], v[22:25]
	v_mfma_f32_16x16x32_bf16 v[14:17], v[186:189], v[224:227], v[14:17]
	v_mfma_f32_16x16x32_bf16 v[6:9], v[178:181], v[232:235], v[6:9]
	v_mfma_f32_16x16x32_bf16 v[2:5], v[186:189], v[232:235], v[2:5]
	s_barrier
	s_setprio 0
	s_add_i32 s70, 0, 0x18000
	s_add_i32 s71, 0, 0x1c000
	v_add_u32_e32 v158, s70, v143
	v_add_u32_e32 v186, s71, v143
	ds_read_b128 v[146:149], v158
	ds_read_b128 v[150:153], v158 offset:1024
	ds_read_b128 v[154:157], v158 offset:2048
	ds_read_b128 v[158:161], v158 offset:3072
	ds_read_b128 v[174:177], v186
	ds_read_b128 v[178:181], v186 offset:1024
	ds_read_b128 v[182:185], v186 offset:2048
	ds_read_b128 v[186:189], v186 offset:3072
	s_add_u32 s52, s52, 0x40000
	s_addc_u32 s53, s53, 0
	s_mov_b32 m0, s58
	v_lshl_add_u64 v[240:241], s[52:53], 0, v[134:135]
	ds_read_b128 v[200:203], v145 offset:32768
	ds_read_b128 v[208:211], v145 offset:33792
	ds_read_b128 v[212:215], v145 offset:34816
	ds_read_b128 v[216:219], v145 offset:35840
	ds_read_b128 v[220:223], v145 offset:36864
	ds_read_b128 v[224:227], v145 offset:37888
	ds_read_b128 v[228:231], v145 offset:38912
	ds_read_b128 v[232:235], v145 offset:39936
	global_load_lds_dwordx4 v[240:241], off
	v_lshl_add_u64 v[240:241], s[52:53], 0, v[132:133]
	s_mov_b32 m0, s59
	s_nop 0
	global_load_lds_dwordx4 v[240:241], off
	s_waitcnt vmcnt(8)
	s_waitcnt lgkmcnt(0)
	s_setprio 1
	s_barrier
	v_mfma_f32_16x16x32_bf16 v[126:129], v[146:149], v[200:203], v[126:129]
	v_mfma_f32_16x16x32_bf16 v[122:125], v[154:157], v[200:203], v[122:125]
	v_mfma_f32_16x16x32_bf16 v[114:117], v[146:149], v[212:215], v[114:117]
	v_mfma_f32_16x16x32_bf16 v[106:109], v[154:157], v[212:215], v[106:109]
	v_mfma_f32_16x16x32_bf16 v[98:101], v[146:149], v[220:223], v[98:101]
	v_mfma_f32_16x16x32_bf16 v[90:93], v[154:157], v[220:223], v[90:93]
	v_mfma_f32_16x16x32_bf16 v[82:85], v[146:149], v[228:231], v[82:85]
	v_mfma_f32_16x16x32_bf16 v[74:77], v[154:157], v[228:231], v[74:77]
	v_mfma_f32_16x16x32_bf16 v[126:129], v[150:153], v[208:211], v[126:129]
	v_mfma_f32_16x16x32_bf16 v[122:125], v[158:161], v[208:211], v[122:125]
	v_mfma_f32_16x16x32_bf16 v[114:117], v[150:153], v[216:219], v[114:117]
	v_mfma_f32_16x16x32_bf16 v[106:109], v[158:161], v[216:219], v[106:109]
	v_mfma_f32_16x16x32_bf16 v[98:101], v[150:153], v[224:227], v[98:101]
	v_mfma_f32_16x16x32_bf16 v[90:93], v[158:161], v[224:227], v[90:93]
	v_mfma_f32_16x16x32_bf16 v[82:85], v[150:153], v[232:235], v[82:85]
	v_mfma_f32_16x16x32_bf16 v[74:77], v[158:161], v[232:235], v[74:77]
	s_setprio 0
	s_setprio 1
	v_mfma_f32_16x16x32_bf16 v[118:121], v[174:177], v[200:203], v[118:121]
	v_mfma_f32_16x16x32_bf16 v[110:113], v[182:185], v[200:203], v[110:113]
	v_mfma_f32_16x16x32_bf16 v[102:105], v[174:177], v[212:215], v[102:105]
	v_mfma_f32_16x16x32_bf16 v[94:97], v[182:185], v[212:215], v[94:97]
	v_mfma_f32_16x16x32_bf16 v[86:89], v[174:177], v[220:223], v[86:89]
	v_mfma_f32_16x16x32_bf16 v[78:81], v[182:185], v[220:223], v[78:81]
	v_mfma_f32_16x16x32_bf16 v[70:73], v[174:177], v[228:231], v[70:73]
	v_mfma_f32_16x16x32_bf16 v[66:69], v[182:185], v[228:231], v[66:69]
	v_mfma_f32_16x16x32_bf16 v[118:121], v[178:181], v[208:211], v[118:121]
	v_mfma_f32_16x16x32_bf16 v[110:113], v[186:189], v[208:211], v[110:113]
	v_mfma_f32_16x16x32_bf16 v[102:105], v[178:181], v[216:219], v[102:105]
	v_mfma_f32_16x16x32_bf16 v[94:97], v[186:189], v[216:219], v[94:97]
	v_mfma_f32_16x16x32_bf16 v[86:89], v[178:181], v[224:227], v[86:89]
	v_mfma_f32_16x16x32_bf16 v[78:81], v[186:189], v[224:227], v[78:81]
	v_mfma_f32_16x16x32_bf16 v[70:73], v[178:181], v[232:235], v[70:73]
	v_mfma_f32_16x16x32_bf16 v[66:69], v[186:189], v[232:235], v[66:69]
	s_barrier
; #define PG8_STAGE(bufoff, gbase, voff) do { _Pragma("unroll") for (int _i = 0; _i < 2; ++_i) \
;         __builtin_amdgcn_global_load_lds((const unsigned*)((const char*)(gbase) + (voff)[_i]), (PG8_LAS unsigned*)(lds + (bufoff) + ldsw + _i * 8192), 16, 0, 0); } while (0)
; #define PG8_STAGEA(bufoff, gbase, voff) do { _Pragma("unroll") for (int _i = 0; _i < 2; ++_i) \
;         __builtin_amdgcn_global_load_lds((const unsigned*)((const char*)(gbase) + (voff)[_i]), (PG8_LAS unsigned*)(lds + (bufoff) + ldsw + _i * 8192), 16, 0, A_AUX); } while (0)
; #define PG8_LDA(dst, b, h) do { _Pragma("unroll") for (int m = 0; m < 4; ++m) _Pragma("unroll") for (int k = 0; k < 2; ++k) dst[m][k] = *(const PG8_LAS bf16x8*)(lds + PG8_SA(b, h) + aoff + m * 2048 + k * 1024); } while (0)
; #define PG8_LDB(dst, b, h) do { _Pragma("unroll") for (int n = 0; n < 2; ++n) _Pragma("unroll") for (int k = 0; k < 2; ++k) dst[n][k] = *(const PG8_LAS bf16x8*)(lds + PG8_SB(b, h) + boff + n * 2048 + k * 1024); } while (0)
; #define PG8_MMA(ai, bj, At, Bt) do { __builtin_amdgcn_s_setprio(1); _Pragma("unroll") for (int m = 0; m < 4; ++m) _Pragma("unroll") for (int n = 0; n < 2; ++n) _Pragma("unroll") for (int k = 0; k < 2; ++k) \
;         acc[ai][bj][m][n] = __builtin_amdgcn_mfma_f32_16x16x32_bf16(Bt[n][k], At[m][k], acc[ai][bj][m][n], 0, 0, 0); __builtin_amdgcn_s_setprio(0); } while (0)
; #define PG8_BAR __builtin_amdgcn_s_barrier()
;     ...
;         for (int t = 0; t < nt; t += 2) {
;             const bool last = (t == nt - 2);
;             const char* a1 = cA + (size_t)(t + 1) * kstep;
;             const char* a2 = last ? nA : cA + (size_t)(t + 2) * kstep; const char* b2 = last ? nB : cB + (size_t)(t + 2) * kstep;
;             const char* a3 = a2 + kstep; const char* b3 = b2 + kstep;
;             if (last && has_next) S.a_ready(nxt);
;             if constexpr (SP2) {
;             PG8_LDB(B0, 0, 0); PG8_LDB(B1, 0, 1); PG8_SCHED; PG8_LDA(At, 0, 0); PG8_STAGEA(PG8_SA(1, 1), a1 + hstep, voffA);
;             PG8_WAIT_V(8); PG8_WAIT_L(0); PG8_BAR; PG8_MMA(0, 0, At, B0); PG8_MMA(0, 1, At, B1); PG8_BAR; PG8_SCHED;
;     ...
;             PG8_LDA(At, 1, 1); PG8_STAGE(PG8_SB(1, 0), b3, voffB); PG8_STAGE(PG8_SB(1, 1), b3 + hstep, voffB); PG8_STAGEA(PG8_SA(1, 0), a3, voffA);
;             PG8_WAIT_V(8); PG8_WAIT_L(0); PG8_BAR; PG8_MMA(1, 0, At, B0); PG8_MMA(1, 1, At, B1); PG8_BAR; PG8_SCHED;
	s_setprio 0
	s_add_i32 s52, s70, s55
	v_lshl_add_u64 v[140:141], v[140:141], 0, s[8:9]
	s_mov_b32 m0, s52
	ds_read_b128 v[200:203], v145 offset:49152
	ds_read_b128 v[208:211], v145 offset:50176
	ds_read_b128 v[212:215], v145 offset:51200
	ds_read_b128 v[216:219], v145 offset:52224
	ds_read_b128 v[220:223], v145 offset:53248
	ds_read_b128 v[224:227], v145 offset:54272
	ds_read_b128 v[228:231], v145 offset:55296
	ds_read_b128 v[232:235], v145 offset:56320
	global_load_lds_dwordx4 v[140:141], off
	s_add_i32 m0, s52, 0x2000
	s_add_u32 s50, s50, 0x40080
	v_lshl_add_u64 v[140:141], v[190:191], 0, s[8:9]
	s_addc_u32 s51, s51, 0
	s_add_i32 s52, s71, s55
	global_load_lds_dwordx4 v[140:141], off
	v_lshl_add_u64 v[140:141], s[50:51], 0, v[0:1]
	s_mov_b32 m0, s52
	s_nop 0
	global_load_lds_dwordx4 v[140:141], off
	v_lshl_add_u64 v[140:141], s[50:51], 0, v[130:131]
	s_add_i32 m0, s52, 0x2000
	s_nop 0
	global_load_lds_dwordx4 v[140:141], off
	v_lshl_add_u64 v[140:141], v[236:237], 0, s[8:9]
	s_mov_b32 m0, s60
	s_nop 0
	global_load_lds_dwordx4 v[140:141], off
	v_lshl_add_u64 v[140:141], v[238:239], 0, s[8:9]
	s_mov_b32 m0, s61
	s_nop 0
	global_load_lds_dwordx4 v[140:141], off
	s_waitcnt vmcnt(8)
	s_waitcnt lgkmcnt(0)
	s_setprio 1
	s_barrier
	v_mfma_f32_16x16x32_bf16 v[62:65], v[146:149], v[200:203], v[62:65]
	v_mfma_f32_16x16x32_bf16 v[58:61], v[154:157], v[200:203], v[58:61]
	v_mfma_f32_16x16x32_bf16 v[50:53], v[146:149], v[212:215], v[50:53]
	v_mfma_f32_16x16x32_bf16 v[42:45], v[154:157], v[212:215], v[42:45]
	v_mfma_f32_16x16x32_bf16 v[34:37], v[146:149], v[220:223], v[34:37]
	v_mfma_f32_16x16x32_bf16 v[26:29], v[154:157], v[220:223], v[26:29]
	v_mfma_f32_16x16x32_bf16 v[18:21], v[146:149], v[228:231], v[18:21]
	v_mfma_f32_16x16x32_bf16 v[10:13], v[154:157], v[228:231], v[10:13]
	v_mfma_f32_16x16x32_bf16 v[62:65], v[150:153], v[208:211], v[62:65]
	v_mfma_f32_16x16x32_bf16 v[58:61], v[158:161], v[208:211], v[58:61]
	v_mfma_f32_16x16x32_bf16 v[50:53], v[150:153], v[216:219], v[50:53]
	v_mfma_f32_16x16x32_bf16 v[42:45], v[158:161], v[216:219], v[42:45]
	v_mfma_f32_16x16x32_bf16 v[34:37], v[150:153], v[224:227], v[34:37]
	v_mfma_f32_16x16x32_bf16 v[26:29], v[158:161], v[224:227], v[26:29]
	v_mfma_f32_16x16x32_bf16 v[18:21], v[150:153], v[232:235], v[18:21]
	v_mfma_f32_16x16x32_bf16 v[10:13], v[158:161], v[232:235], v[10:13]
	s_setprio 0
	s_setprio 1
	v_mfma_f32_16x16x32_bf16 v[54:57], v[174:177], v[200:203], v[54:57]
	v_mfma_f32_16x16x32_bf16 v[46:49], v[182:185], v[200:203], v[46:49]
	v_mfma_f32_16x16x32_bf16 v[38:41], v[174:177], v[212:215], v[38:41]
	v_mfma_f32_16x16x32_bf16 v[30:33], v[182:185], v[212:215], v[30:33]
	v_mfma_f32_16x16x32_bf16 v[22:25], v[174:177], v[220:223], v[22:25]
	v_mfma_f32_16x16x32_bf16 v[14:17], v[182:185], v[220:223], v[14:17]
	v_mfma_f32_16x16x32_bf16 v[6:9], v[174:177], v[228:231], v[6:9]
	v_mfma_f32_16x16x32_bf16 v[2:5], v[182:185], v[228:231], v[2:5]
	v_mfma_f32_16x16x32_bf16 v[54:57], v[178:181], v[208:211], v[54:57]
	v_mfma_f32_16x16x32_bf16 v[46:49], v[186:189], v[208:211], v[46:49]
	v_mfma_f32_16x16x32_bf16 v[38:41], v[178:181], v[216:219], v[38:41]
	v_mfma_f32_16x16x32_bf16 v[30:33], v[186:189], v[216:219], v[30:33]
	v_mfma_f32_16x16x32_bf16 v[22:25], v[178:181], v[224:227], v[22:25]
	v_mfma_f32_16x16x32_bf16 v[14:17], v[186:189], v[224:227], v[14:17]
	v_mfma_f32_16x16x32_bf16 v[6:9], v[178:181], v[232:235], v[6:9]
	v_mfma_f32_16x16x32_bf16 v[2:5], v[186:189], v[232:235], v[2:5]
	s_barrier
	s_setprio 0
	s_add_i32 s73, s73, 2
	s_add_u32 s48, s48, 0x100
	s_addc_u32 s49, s49, 0
	s_add_u32 s65, s65, 0x100
	s_addc_u32 s72, s72, 0
.LBB0_443:
	s_add_u32 s50, s48, 0xfffc0080
	s_addc_u32 s51, s49, -1
	s_add_i32 s70, 0, 0x10000
	s_cmp_eq_u32 s73, 12
	s_cselect_b32 s53, s16, s51
	s_cselect_b32 s52, s17, s50
	v_add_u32_e32 v140, s70, v143
	s_cselect_b32 s51, s41, s72
	s_cselect_b32 s50, s43, s65
	s_add_i32 s76, 0, 0x14000
	ds_read_b128 v[146:149], v140
	ds_read_b128 v[150:153], v140 offset:1024
	ds_read_b128 v[154:157], v140 offset:2048
	ds_read_b128 v[158:161], v140 offset:3072
	v_add_u32_e32 v140, s76, v143
	ds_read_b128 v[174:177], v140
	ds_read_b128 v[178:181], v140 offset:1024
	ds_read_b128 v[182:185], v140 offset:2048
	ds_read_b128 v[186:189], v140 offset:3072
	v_lshl_add_u64 v[140:141], s[48:49], 0, v[136:137]
	s_add_i32 m0, s56, 0xc000
	ds_read_b128 v[200:203], v145
	ds_read_b128 v[208:211], v145 offset:1024
	ds_read_b128 v[212:215], v145 offset:2048
	ds_read_b128 v[216:219], v145 offset:3072
	ds_read_b128 v[220:223], v145 offset:4096
	ds_read_b128 v[224:227], v145 offset:5120
	ds_read_b128 v[228:231], v145 offset:6144
	ds_read_b128 v[232:235], v145 offset:7168
	global_load_lds_dwordx4 v[140:141], off
	v_lshl_add_u64 v[140:141], s[48:49], 0, v[138:139]
	s_add_i32 m0, s56, 0xe000
	s_nop 0
	global_load_lds_dwordx4 v[140:141], off
	s_waitcnt vmcnt(8)
	s_waitcnt lgkmcnt(0)
	s_setprio 1
	s_barrier
; #define PG8_STAGE(bufoff, gbase, voff) do { _Pragma("unroll") for (int _i = 0; _i < 2; ++_i) \
;         __builtin_amdgcn_global_load_lds((const unsigned*)((const char*)(gbase) + (voff)[_i]), (PG8_LAS unsigned*)(lds + (bufoff) + ldsw + _i * 8192), 16, 0, 0); } while (0)
; #define PG8_STAGEA(bufoff, gbase, voff) do { _Pragma("unroll") for (int _i = 0; _i < 2; ++_i) \
;         __builtin_amdgcn_global_load_lds((const unsigned*)((const char*)(gbase) + (voff)[_i]), (PG8_LAS unsigned*)(lds + (bufoff) + ldsw + _i * 8192), 16, 0, A_AUX); } while (0)
; #define PG8_LDA(dst, b, h) do { _Pragma("unroll") for (int m = 0; m < 4; ++m) _Pragma("unroll") for (int k = 0; k < 2; ++k) dst[m][k] = *(const PG8_LAS bf16x8*)(lds + PG8_SA(b, h) + aoff + m * 2048 + k * 1024); } while (0)
; #define PG8_MMA(ai, bj, At, Bt) do { __builtin_amdgcn_s_setprio(1); _Pragma("unroll") for (int m = 0; m < 4; ++m) _Pragma("unroll") for (int n = 0; n < 2; ++n) _Pragma("unroll") for (int k = 0; k < 2; ++k) \
;         acc[ai][bj][m][n] = __builtin_amdgcn_mfma_f32_16x16x32_bf16(Bt[n][k], At[m][k], acc[ai][bj][m][n], 0, 0, 0); __builtin_amdgcn_s_setprio(0); } while (0)
; #define PG8_WAIT_V(n) asm volatile("s_waitcnt vmcnt(" #n ")" ::: "memory")
; #define PG8_WAIT_L(n) asm volatile("s_waitcnt lgkmcnt(" #n ")" ::: "memory")
; #define PG8_BAR __builtin_amdgcn_s_barrier()
; #define PG8_SCHED __builtin_amdgcn_sched_barrier(0)
;     ...
;             PG8_WAIT_V(8); PG8_WAIT_L(0); PG8_BAR; PG8_MMA(0, 0, At, B0); PG8_MMA(0, 1, At, B1); PG8_BAR; PG8_SCHED;
;             PG8_LDA(At, 0, 1); PG8_STAGE(PG8_SB(0, 0), b2, voffB); PG8_STAGE(PG8_SB(0, 1), b2 + hstep, voffB); PG8_STAGEA(PG8_SA(0, 0), a2, voffA);
;             PG8_WAIT_V(8); PG8_WAIT_L(0); PG8_BAR; PG8_MMA(1, 0, At, B0); PG8_MMA(1, 1, At, B1); PG8_BAR; PG8_SCHED;
	v_mfma_f32_16x16x32_bf16 v[126:129], v[146:149], v[200:203], v[126:129]
	v_mfma_f32_16x16x32_bf16 v[122:125], v[154:157], v[200:203], v[122:125]
	v_mfma_f32_16x16x32_bf16 v[114:117], v[146:149], v[212:215], v[114:117]
	v_mfma_f32_16x16x32_bf16 v[106:109], v[154:157], v[212:215], v[106:109]
	v_mfma_f32_16x16x32_bf16 v[98:101], v[146:149], v[220:223], v[98:101]
	v_mfma_f32_16x16x32_bf16 v[90:93], v[154:157], v[220:223], v[90:93]
	v_mfma_f32_16x16x32_bf16 v[82:85], v[146:149], v[228:231], v[82:85]
	v_mfma_f32_16x16x32_bf16 v[74:77], v[154:157], v[228:231], v[74:77]
	v_mfma_f32_16x16x32_bf16 v[126:129], v[150:153], v[208:211], v[126:129]
	v_mfma_f32_16x16x32_bf16 v[122:125], v[158:161], v[208:211], v[122:125]
	v_mfma_f32_16x16x32_bf16 v[114:117], v[150:153], v[216:219], v[114:117]
	v_mfma_f32_16x16x32_bf16 v[106:109], v[158:161], v[216:219], v[106:109]
	v_mfma_f32_16x16x32_bf16 v[98:101], v[150:153], v[224:227], v[98:101]
	v_mfma_f32_16x16x32_bf16 v[90:93], v[158:161], v[224:227], v[90:93]
	v_mfma_f32_16x16x32_bf16 v[82:85], v[150:153], v[232:235], v[82:85]
	v_mfma_f32_16x16x32_bf16 v[74:77], v[158:161], v[232:235], v[74:77]
	s_setprio 0
	s_setprio 1
	v_mfma_f32_16x16x32_bf16 v[118:121], v[174:177], v[200:203], v[118:121]
	v_mfma_f32_16x16x32_bf16 v[110:113], v[182:185], v[200:203], v[110:113]
	v_mfma_f32_16x16x32_bf16 v[102:105], v[174:177], v[212:215], v[102:105]
	v_mfma_f32_16x16x32_bf16 v[94:97], v[182:185], v[212:215], v[94:97]
	v_mfma_f32_16x16x32_bf16 v[86:89], v[174:177], v[220:223], v[86:89]
	v_mfma_f32_16x16x32_bf16 v[78:81], v[182:185], v[220:223], v[78:81]
	v_mfma_f32_16x16x32_bf16 v[70:73], v[174:177], v[228:231], v[70:73]
	v_mfma_f32_16x16x32_bf16 v[66:69], v[182:185], v[228:231], v[66:69]
	v_mfma_f32_16x16x32_bf16 v[118:121], v[178:181], v[208:211], v[118:121]
	v_mfma_f32_16x16x32_bf16 v[110:113], v[186:189], v[208:211], v[110:113]
	v_mfma_f32_16x16x32_bf16 v[102:105], v[178:181], v[216:219], v[102:105]
	v_mfma_f32_16x16x32_bf16 v[94:97], v[186:189], v[216:219], v[94:97]
	v_mfma_f32_16x16x32_bf16 v[86:89], v[178:181], v[224:227], v[86:89]
	v_mfma_f32_16x16x32_bf16 v[78:81], v[186:189], v[224:227], v[78:81]
	v_mfma_f32_16x16x32_bf16 v[70:73], v[178:181], v[232:235], v[70:73]
	v_mfma_f32_16x16x32_bf16 v[66:69], v[186:189], v[232:235], v[66:69]
	s_barrier
	s_setprio 0
	s_add_i32 s70, s70, s55
	v_lshl_add_u64 v[140:141], s[50:51], 0, v[0:1]
	s_mov_b32 m0, s70
	ds_read_b128 v[200:203], v145 offset:16384
	ds_read_b128 v[208:211], v145 offset:17408
	ds_read_b128 v[212:215], v145 offset:18432
	ds_read_b128 v[216:219], v145 offset:19456
	ds_read_b128 v[220:223], v145 offset:20480
	ds_read_b128 v[224:227], v145 offset:21504
	ds_read_b128 v[228:231], v145 offset:22528
	ds_read_b128 v[232:235], v145 offset:23552
	global_load_lds_dwordx4 v[140:141], off
	s_add_i32 m0, s70, 0x2000
	s_add_u32 s70, s50, 0x40000
	v_lshl_add_u64 v[190:191], s[50:51], 0, v[130:131]
	s_addc_u32 s71, s51, 0
	s_add_i32 s76, s76, s55
	global_load_lds_dwordx4 v[190:191], off
	v_lshl_add_u64 v[236:237], s[70:71], 0, v[0:1]
	s_mov_b32 m0, s76
	v_lshl_add_u64 v[238:239], s[52:53], 0, v[132:133]
	global_load_lds_dwordx4 v[236:237], off
	v_lshl_add_u64 v[236:237], s[70:71], 0, v[130:131]
	s_add_i32 m0, s76, 0x2000
	s_nop 0
	global_load_lds_dwordx4 v[236:237], off
	v_lshl_add_u64 v[236:237], s[52:53], 0, v[134:135]
	s_mov_b32 m0, s56
	s_nop 0
	global_load_lds_dwordx4 v[236:237], off
	s_mov_b32 m0, s57
	s_nop 0
	global_load_lds_dwordx4 v[238:239], off
	s_waitcnt vmcnt(8)
	s_waitcnt lgkmcnt(0)
	s_setprio 1
	s_barrier
	v_mfma_f32_16x16x32_bf16 v[62:65], v[146:149], v[200:203], v[62:65]
	v_mfma_f32_16x16x32_bf16 v[58:61], v[154:157], v[200:203], v[58:61]
	v_mfma_f32_16x16x32_bf16 v[50:53], v[146:149], v[212:215], v[50:53]
	v_mfma_f32_16x16x32_bf16 v[42:45], v[154:157], v[212:215], v[42:45]
	v_mfma_f32_16x16x32_bf16 v[34:37], v[146:149], v[220:223], v[34:37]
	v_mfma_f32_16x16x32_bf16 v[26:29], v[154:157], v[220:223], v[26:29]
	v_mfma_f32_16x16x32_bf16 v[18:21], v[146:149], v[228:231], v[18:21]
	v_mfma_f32_16x16x32_bf16 v[10:13], v[154:157], v[228:231], v[10:13]
	v_mfma_f32_16x16x32_bf16 v[62:65], v[150:153], v[208:211], v[62:65]
	v_mfma_f32_16x16x32_bf16 v[58:61], v[158:161], v[208:211], v[58:61]
	v_mfma_f32_16x16x32_bf16 v[50:53], v[150:153], v[216:219], v[50:53]
	v_mfma_f32_16x16x32_bf16 v[42:45], v[158:161], v[216:219], v[42:45]
	v_mfma_f32_16x16x32_bf16 v[34:37], v[150:153], v[224:227], v[34:37]
	v_mfma_f32_16x16x32_bf16 v[26:29], v[158:161], v[224:227], v[26:29]
	v_mfma_f32_16x16x32_bf16 v[18:21], v[150:153], v[232:235], v[18:21]
	v_mfma_f32_16x16x32_bf16 v[10:13], v[158:161], v[232:235], v[10:13]
	s_setprio 0
	s_setprio 1
	v_mfma_f32_16x16x32_bf16 v[54:57], v[174:177], v[200:203], v[54:57]
	v_mfma_f32_16x16x32_bf16 v[46:49], v[182:185], v[200:203], v[46:49]
	v_mfma_f32_16x16x32_bf16 v[38:41], v[174:177], v[212:215], v[38:41]
	v_mfma_f32_16x16x32_bf16 v[30:33], v[182:185], v[212:215], v[30:33]
	v_mfma_f32_16x16x32_bf16 v[22:25], v[174:177], v[220:223], v[22:25]
	v_mfma_f32_16x16x32_bf16 v[14:17], v[182:185], v[220:223], v[14:17]
	v_mfma_f32_16x16x32_bf16 v[6:9], v[174:177], v[228:231], v[6:9]
	v_mfma_f32_16x16x32_bf16 v[2:5], v[182:185], v[228:231], v[2:5]
	v_mfma_f32_16x16x32_bf16 v[54:57], v[178:181], v[208:211], v[54:57]
	v_mfma_f32_16x16x32_bf16 v[46:49], v[186:189], v[208:211], v[46:49]
	v_mfma_f32_16x16x32_bf16 v[38:41], v[178:181], v[216:219], v[38:41]
	v_mfma_f32_16x16x32_bf16 v[30:33], v[186:189], v[216:219], v[30:33]
	v_mfma_f32_16x16x32_bf16 v[22:25], v[178:181], v[224:227], v[22:25]
	v_mfma_f32_16x16x32_bf16 v[14:17], v[186:189], v[224:227], v[14:17]
	v_mfma_f32_16x16x32_bf16 v[6:9], v[178:181], v[232:235], v[6:9]
	v_mfma_f32_16x16x32_bf16 v[2:5], v[186:189], v[232:235], v[2:5]
	s_barrier
; #define PG8_STAGEA(bufoff, gbase, voff) do { _Pragma("unroll") for (int _i = 0; _i < 2; ++_i) \
;         __builtin_amdgcn_global_load_lds((const unsigned*)((const char*)(gbase) + (voff)[_i]), (PG8_LAS unsigned*)(lds + (bufoff) + ldsw + _i * 8192), 16, 0, A_AUX); } while (0)
; #define PG8_LDA(dst, b, h) do { _Pragma("unroll") for (int m = 0; m < 4; ++m) _Pragma("unroll") for (int k = 0; k < 2; ++k) dst[m][k] = *(const PG8_LAS bf16x8*)(lds + PG8_SA(b, h) + aoff + m * 2048 + k * 1024); } while (0)
; #define PG8_LDB(dst, b, h) do { _Pragma("unroll") for (int n = 0; n < 2; ++n) _Pragma("unroll") for (int k = 0; k < 2; ++k) dst[n][k] = *(const PG8_LAS bf16x8*)(lds + PG8_SB(b, h) + boff + n * 2048 + k * 1024); } while (0)
; #define PG8_MMA(ai, bj, At, Bt) do { __builtin_amdgcn_s_setprio(1); _Pragma("unroll") for (int m = 0; m < 4; ++m) _Pragma("unroll") for (int n = 0; n < 2; ++n) _Pragma("unroll") for (int k = 0; k < 2; ++k) \
;         acc[ai][bj][m][n] = __builtin_amdgcn_mfma_f32_16x16x32_bf16(Bt[n][k], At[m][k], acc[ai][bj][m][n], 0, 0, 0); __builtin_amdgcn_s_setprio(0); } while (0)
; #define PG8_WAIT_V(n) asm volatile("s_waitcnt vmcnt(" #n ")" ::: "memory")
; #define PG8_WAIT_L(n) asm volatile("s_waitcnt lgkmcnt(" #n ")" ::: "memory")
; #define PG8_BAR __builtin_amdgcn_s_barrier()
; #define PG8_SCHED __builtin_amdgcn_sched_barrier(0)
;     ...
;             PG8_LDB(B0, 1, 0); PG8_LDB(B1, 1, 1); PG8_SCHED; PG8_LDA(At, 1, 0); PG8_STAGEA(PG8_SA(0, 1), a2 + hstep, voffA);
;             PG8_WAIT_V(8); PG8_WAIT_L(0); PG8_BAR; PG8_MMA(0, 0, At, B0); PG8_MMA(0, 1, At, B1); PG8_BAR; PG8_SCHED;
	s_setprio 0
	s_add_i32 s70, 0, 0x18000
	s_add_i32 s71, 0, 0x1c000
	v_add_u32_e32 v158, s70, v143
	v_add_u32_e32 v186, s71, v143
	ds_read_b128 v[146:149], v158
	ds_read_b128 v[150:153], v158 offset:1024
	ds_read_b128 v[154:157], v158 offset:2048
	ds_read_b128 v[158:161], v158 offset:3072
	ds_read_b128 v[174:177], v186
	ds_read_b128 v[178:181], v186 offset:1024
	ds_read_b128 v[182:185], v186 offset:2048
	ds_read_b128 v[186:189], v186 offset:3072
	s_add_u32 s52, s52, 0x40000
	s_addc_u32 s53, s53, 0
	s_mov_b32 m0, s58
	v_lshl_add_u64 v[240:241], s[52:53], 0, v[134:135]
	ds_read_b128 v[200:203], v145 offset:32768
	ds_read_b128 v[208:211], v145 offset:33792
	ds_read_b128 v[212:215], v145 offset:34816
	ds_read_b128 v[216:219], v145 offset:35840
	ds_read_b128 v[220:223], v145 offset:36864
	ds_read_b128 v[224:227], v145 offset:37888
	ds_read_b128 v[228:231], v145 offset:38912
	ds_read_b128 v[232:235], v145 offset:39936
	global_load_lds_dwordx4 v[240:241], off
	v_lshl_add_u64 v[240:241], s[52:53], 0, v[132:133]
	s_mov_b32 m0, s59
	s_nop 0
	global_load_lds_dwordx4 v[240:241], off
	s_waitcnt vmcnt(8)
	s_waitcnt lgkmcnt(0)
	s_setprio 1
	s_barrier
	v_mfma_f32_16x16x32_bf16 v[126:129], v[146:149], v[200:203], v[126:129]
	v_mfma_f32_16x16x32_bf16 v[122:125], v[154:157], v[200:203], v[122:125]
	v_mfma_f32_16x16x32_bf16 v[114:117], v[146:149], v[212:215], v[114:117]
	v_mfma_f32_16x16x32_bf16 v[106:109], v[154:157], v[212:215], v[106:109]
	v_mfma_f32_16x16x32_bf16 v[98:101], v[146:149], v[220:223], v[98:101]
	v_mfma_f32_16x16x32_bf16 v[90:93], v[154:157], v[220:223], v[90:93]
	v_mfma_f32_16x16x32_bf16 v[82:85], v[146:149], v[228:231], v[82:85]
	v_mfma_f32_16x16x32_bf16 v[74:77], v[154:157], v[228:231], v[74:77]
	v_mfma_f32_16x16x32_bf16 v[126:129], v[150:153], v[208:211], v[126:129]
	v_mfma_f32_16x16x32_bf16 v[122:125], v[158:161], v[208:211], v[122:125]
	v_mfma_f32_16x16x32_bf16 v[114:117], v[150:153], v[216:219], v[114:117]
	v_mfma_f32_16x16x32_bf16 v[106:109], v[158:161], v[216:219], v[106:109]
	v_mfma_f32_16x16x32_bf16 v[98:101], v[150:153], v[224:227], v[98:101]
	v_mfma_f32_16x16x32_bf16 v[90:93], v[158:161], v[224:227], v[90:93]
	v_mfma_f32_16x16x32_bf16 v[82:85], v[150:153], v[232:235], v[82:85]
	v_mfma_f32_16x16x32_bf16 v[74:77], v[158:161], v[232:235], v[74:77]
	s_setprio 0
	s_setprio 1
	v_mfma_f32_16x16x32_bf16 v[118:121], v[174:177], v[200:203], v[118:121]
	v_mfma_f32_16x16x32_bf16 v[110:113], v[182:185], v[200:203], v[110:113]
	v_mfma_f32_16x16x32_bf16 v[102:105], v[174:177], v[212:215], v[102:105]
	v_mfma_f32_16x16x32_bf16 v[94:97], v[182:185], v[212:215], v[94:97]
	v_mfma_f32_16x16x32_bf16 v[86:89], v[174:177], v[220:223], v[86:89]
	v_mfma_f32_16x16x32_bf16 v[78:81], v[182:185], v[220:223], v[78:81]
	v_mfma_f32_16x16x32_bf16 v[70:73], v[174:177], v[228:231], v[70:73]
	v_mfma_f32_16x16x32_bf16 v[66:69], v[182:185], v[228:231], v[66:69]
	v_mfma_f32_16x16x32_bf16 v[118:121], v[178:181], v[208:211], v[118:121]
	v_mfma_f32_16x16x32_bf16 v[110:113], v[186:189], v[208:211], v[110:113]
	v_mfma_f32_16x16x32_bf16 v[102:105], v[178:181], v[216:219], v[102:105]
	v_mfma_f32_16x16x32_bf16 v[94:97], v[186:189], v[216:219], v[94:97]
	v_mfma_f32_16x16x32_bf16 v[86:89], v[178:181], v[224:227], v[86:89]
	v_mfma_f32_16x16x32_bf16 v[78:81], v[186:189], v[224:227], v[78:81]
	v_mfma_f32_16x16x32_bf16 v[70:73], v[178:181], v[232:235], v[70:73]
	v_mfma_f32_16x16x32_bf16 v[66:69], v[186:189], v[232:235], v[66:69]
	s_barrier
; #define PG8_STAGE(bufoff, gbase, voff) do { _Pragma("unroll") for (int _i = 0; _i < 2; ++_i) \
;         __builtin_amdgcn_global_load_lds((const unsigned*)((const char*)(gbase) + (voff)[_i]), (PG8_LAS unsigned*)(lds + (bufoff) + ldsw + _i * 8192), 16, 0, 0); } while (0)
; #define PG8_STAGEA(bufoff, gbase, voff) do { _Pragma("unroll") for (int _i = 0; _i < 2; ++_i) \
;         __builtin_amdgcn_global_load_lds((const unsigned*)((const char*)(gbase) + (voff)[_i]), (PG8_LAS unsigned*)(lds + (bufoff) + ldsw + _i * 8192), 16, 0, A_AUX); } while (0)
; #define PG8_LDA(dst, b, h) do { _Pragma("unroll") for (int m = 0; m < 4; ++m) _Pragma("unroll") for (int k = 0; k < 2; ++k) dst[m][k] = *(const PG8_LAS bf16x8*)(lds + PG8_SA(b, h) + aoff + m * 2048 + k * 1024); } while (0)
; #define PG8_MMA(ai, bj, At, Bt) do { __builtin_amdgcn_s_setprio(1); _Pragma("unroll") for (int m = 0; m < 4; ++m) _Pragma("unroll") for (int n = 0; n < 2; ++n) _Pragma("unroll") for (int k = 0; k < 2; ++k) \
;         acc[ai][bj][m][n] = __builtin_amdgcn_mfma_f32_16x16x32_bf16(Bt[n][k], At[m][k], acc[ai][bj][m][n], 0, 0, 0); __builtin_amdgcn_s_setprio(0); } while (0)
; #define PG8_WAIT_V(n) asm volatile("s_waitcnt vmcnt(" #n ")" ::: "memory")
; #define PG8_WAIT_L(n) asm volatile("s_waitcnt lgkmcnt(" #n ")" ::: "memory")
; #define PG8_BAR __builtin_amdgcn_s_barrier()
; #define PG8_SCHED __builtin_amdgcn_sched_barrier(0)
;     ...
;             PG8_LDA(At, 1, 1); PG8_STAGE(PG8_SB(1, 0), b3, voffB); PG8_STAGE(PG8_SB(1, 1), b3 + hstep, voffB); PG8_STAGEA(PG8_SA(1, 0), a3, voffA);
;             PG8_WAIT_V(8); PG8_WAIT_L(0); PG8_BAR; PG8_MMA(1, 0, At, B0); PG8_MMA(1, 1, At, B1); PG8_BAR; PG8_SCHED;
;     ...
;         if constexpr (ALIGN_EPI) { if (wr == 0) PG8_BAR; }
	s_setprio 0
	s_add_i32 s52, s70, s55
	v_lshl_add_u64 v[140:141], v[140:141], 0, s[8:9]
	s_mov_b32 m0, s52
	ds_read_b128 v[200:203], v145 offset:49152
	ds_read_b128 v[208:211], v145 offset:50176
	ds_read_b128 v[212:215], v145 offset:51200
	ds_read_b128 v[216:219], v145 offset:52224
	ds_read_b128 v[220:223], v145 offset:53248
	ds_read_b128 v[224:227], v145 offset:54272
	ds_read_b128 v[228:231], v145 offset:55296
	ds_read_b128 v[232:235], v145 offset:56320
	global_load_lds_dwordx4 v[140:141], off
	s_add_i32 m0, s52, 0x2000
	s_add_u32 s50, s50, 0x40080
	v_lshl_add_u64 v[140:141], v[190:191], 0, s[8:9]
	s_addc_u32 s51, s51, 0
	s_add_i32 s52, s71, s55
	global_load_lds_dwordx4 v[140:141], off
	v_lshl_add_u64 v[140:141], s[50:51], 0, v[0:1]
	s_mov_b32 m0, s52
	s_nop 0
	global_load_lds_dwordx4 v[140:141], off
	v_lshl_add_u64 v[140:141], s[50:51], 0, v[130:131]
	s_add_i32 m0, s52, 0x2000
	s_nop 0
	global_load_lds_dwordx4 v[140:141], off
	v_lshl_add_u64 v[140:141], v[236:237], 0, s[8:9]
	s_mov_b32 m0, s60
	s_nop 0
	global_load_lds_dwordx4 v[140:141], off
	v_lshl_add_u64 v[140:141], v[238:239], 0, s[8:9]
	s_mov_b32 m0, s61
	s_nop 0
	global_load_lds_dwordx4 v[140:141], off
	s_waitcnt vmcnt(8)
	s_waitcnt lgkmcnt(0)
	s_setprio 1
	s_barrier
	v_mfma_f32_16x16x32_bf16 v[62:65], v[146:149], v[200:203], v[62:65]
	v_mfma_f32_16x16x32_bf16 v[58:61], v[154:157], v[200:203], v[58:61]
	v_mfma_f32_16x16x32_bf16 v[50:53], v[146:149], v[212:215], v[50:53]
	v_mfma_f32_16x16x32_bf16 v[42:45], v[154:157], v[212:215], v[42:45]
	v_mfma_f32_16x16x32_bf16 v[34:37], v[146:149], v[220:223], v[34:37]
	v_mfma_f32_16x16x32_bf16 v[26:29], v[154:157], v[220:223], v[26:29]
	v_mfma_f32_16x16x32_bf16 v[18:21], v[146:149], v[228:231], v[18:21]
	v_mfma_f32_16x16x32_bf16 v[10:13], v[154:157], v[228:231], v[10:13]
	v_mfma_f32_16x16x32_bf16 v[62:65], v[150:153], v[208:211], v[62:65]
	v_mfma_f32_16x16x32_bf16 v[58:61], v[158:161], v[208:211], v[58:61]
	v_mfma_f32_16x16x32_bf16 v[50:53], v[150:153], v[216:219], v[50:53]
	v_mfma_f32_16x16x32_bf16 v[42:45], v[158:161], v[216:219], v[42:45]
	v_mfma_f32_16x16x32_bf16 v[34:37], v[150:153], v[224:227], v[34:37]
	v_mfma_f32_16x16x32_bf16 v[26:29], v[158:161], v[224:227], v[26:29]
	v_mfma_f32_16x16x32_bf16 v[18:21], v[150:153], v[232:235], v[18:21]
	v_mfma_f32_16x16x32_bf16 v[10:13], v[158:161], v[232:235], v[10:13]
	s_setprio 0
	s_setprio 1
	v_mfma_f32_16x16x32_bf16 v[54:57], v[174:177], v[200:203], v[54:57]
	v_mfma_f32_16x16x32_bf16 v[46:49], v[182:185], v[200:203], v[46:49]
	v_mfma_f32_16x16x32_bf16 v[38:41], v[174:177], v[212:215], v[38:41]
	v_mfma_f32_16x16x32_bf16 v[30:33], v[182:185], v[212:215], v[30:33]
	v_mfma_f32_16x16x32_bf16 v[22:25], v[174:177], v[220:223], v[22:25]
	v_mfma_f32_16x16x32_bf16 v[14:17], v[182:185], v[220:223], v[14:17]
	v_mfma_f32_16x16x32_bf16 v[6:9], v[174:177], v[228:231], v[6:9]
	v_mfma_f32_16x16x32_bf16 v[2:5], v[182:185], v[228:231], v[2:5]
	v_mfma_f32_16x16x32_bf16 v[54:57], v[178:181], v[208:211], v[54:57]
	v_mfma_f32_16x16x32_bf16 v[46:49], v[186:189], v[208:211], v[46:49]
	v_mfma_f32_16x16x32_bf16 v[38:41], v[178:181], v[216:219], v[38:41]
	v_mfma_f32_16x16x32_bf16 v[30:33], v[186:189], v[216:219], v[30:33]
	v_mfma_f32_16x16x32_bf16 v[22:25], v[178:181], v[224:227], v[22:25]
	v_mfma_f32_16x16x32_bf16 v[14:17], v[186:189], v[224:227], v[14:17]
	v_mfma_f32_16x16x32_bf16 v[6:9], v[178:181], v[232:235], v[6:9]
	v_mfma_f32_16x16x32_bf16 v[2:5], v[186:189], v[232:235], v[2:5]
	s_barrier
	s_setprio 0
	s_add_i32 s73, s73, 2
	s_add_u32 s48, s48, 0x100
	s_addc_u32 s49, s49, 0
	s_add_u32 s65, s65, 0x100
	s_addc_u32 s72, s72, 0
	s_cmp_gt_u32 s73, 13
	s_cbranch_scc0 .LBB0_443
	s_and_b64 vcc, exec, s[36:37]
	s_cbranch_vccz .LBB0_446
	s_barrier

; #define PG8_STAGE(bufoff, gbase, voff) do { _Pragma("unroll") for (int _i = 0; _i < 2; ++_i) \
;         __builtin_amdgcn_global_load_lds((const unsigned*)((const char*)(gbase) + (voff)[_i]), (PG8_LAS unsigned*)(lds + (bufoff) + ldsw + _i * 8192), 16, 0, 0); } while (0)
; #define PG8_STAGEA(bufoff, gbase, voff) do { _Pragma("unroll") for (int _i = 0; _i < 2; ++_i) \
;         __builtin_amdgcn_global_load_lds((const unsigned*)((const char*)(gbase) + (voff)[_i]), (PG8_LAS unsigned*)(lds + (bufoff) + ldsw + _i * 8192), 16, 0, A_AUX); } while (0)
; #define PG8_LDA(dst, b, h) do { _Pragma("unroll") for (int m = 0; m < 4; ++m) _Pragma("unroll") for (int k = 0; k < 2; ++k) dst[m][k] = *(const PG8_LAS bf16x8*)(lds + PG8_SA(b, h) + aoff + m * 2048 + k * 1024); } while (0)
; #define PG8_LDB(dst, b, h) do { _Pragma("unroll") for (int n = 0; n < 2; ++n) _Pragma("unroll") for (int k = 0; k < 2; ++k) dst[n][k] = *(const PG8_LAS bf16x8*)(lds + PG8_SB(b, h) + boff + n * 2048 + k * 1024); } while (0)
; #define PG8_WAIT_V(n) asm volatile("s_waitcnt vmcnt(" #n ")" ::: "memory")
; #define PG8_WAIT_L(n) asm volatile("s_waitcnt lgkmcnt(" #n ")" ::: "memory")
; #define PG8_BAR __builtin_amdgcn_s_barrier()
;     ...
;         const bool has_next = S.next(ui + 1, nxt);
;         const char* nA = has_next ? (const char*)g.A + (size_t)nxt.pm * tstep : cA; const char* nB = has_next ? (const char*)g.Bt + (size_t)nxt.pn * tstep : cB;
;         for (int t = 0; t < nt; t += 2) {
;             const bool last = (t == nt - 2);
;             const char* a1 = cA + (size_t)(t + 1) * kstep;
;             const char* a2 = last ? nA : cA + (size_t)(t + 2) * kstep; const char* b2 = last ? nB : cB + (size_t)(t + 2) * kstep;
;             const char* a3 = a2 + kstep; const char* b3 = b2 + kstep;
;             if (last && has_next) S.a_ready(nxt);
;             if constexpr (SP2) {
;             PG8_LDB(B0, 0, 0); PG8_LDB(B1, 0, 1); PG8_SCHED; PG8_LDA(At, 0, 0); PG8_STAGEA(PG8_SA(1, 1), a1 + hstep, voffA);
;             PG8_WAIT_V(8); PG8_WAIT_L(0); PG8_BAR; PG8_MMA(0, 0, At, B0); PG8_MMA(0, 1, At, B1); PG8_BAR; PG8_SCHED;
;             PG8_LDA(At, 0, 1); PG8_STAGE(PG8_SB(0, 0), b2, voffB); PG8_STAGE(PG8_SB(0, 1), b2 + hstep, voffB); PG8_STAGEA(PG8_SA(0, 0), a2, voffA);
;             PG8_WAIT_V(8); PG8_WAIT_L(0); PG8_BAR; PG8_MMA(1, 0, At, B0); PG8_MMA(1, 1, At, B1); PG8_BAR; PG8_SCHED;
.LBB0_579:
	s_ashr_i32 s45, s44, 31
	s_lshl_b64 s[16:17], s[44:45], 19
	s_add_u32 s46, s97, s16
	s_addc_u32 s47, s29, s17
	s_and_b64 s[16:17], s[40:41], exec
	s_cselect_b32 s16, s47, s51
	s_cselect_b32 s17, s46, s50
	s_ashr_i32 s43, s42, 31
	s_lshl_b64 s[48:49], s[42:43], 19
	s_add_u32 s48, s23, s48
	s_addc_u32 s49, s56, s49
	s_and_b64 s[54:55], s[40:41], exec
	s_cselect_b32 s43, s49, s53
	s_cselect_b32 s45, s48, s52
	s_add_u32 s50, s50, 0x40080
	s_addc_u32 s51, s51, 0
	s_add_u32 s73, s52, 0x100
	s_addc_u32 s76, s53, 0
	s_mov_b32 vcc_lo, -2
	s_add_u32 s52, s50, 0xfffc0080
	s_addc_u32 s53, s51, -1
	s_add_i32 s70, 0, 0x10000
	s_cmp_eq_u32 vcc_lo, 12
	s_cselect_b32 s55, s16, s53
	s_cselect_b32 s54, s17, s52
	v_add_u32_e32 v140, s70, v143
	s_cselect_b32 s53, s43, s76
	s_cselect_b32 s52, s45, s73
	s_add_i32 vcc_hi, 0, 0x14000
	ds_read_b128 v[146:149], v140
	ds_read_b128 v[150:153], v140 offset:1024
	ds_read_b128 v[154:157], v140 offset:2048
	ds_read_b128 v[158:161], v140 offset:3072
	v_add_u32_e32 v140, vcc_hi, v143
	ds_read_b128 v[174:177], v140
	ds_read_b128 v[178:181], v140 offset:1024
	ds_read_b128 v[182:185], v140 offset:2048
	ds_read_b128 v[186:189], v140 offset:3072
	v_lshl_add_u64 v[140:141], s[50:51], 0, v[136:137]
	s_add_i32 m0, s58, 0xc000
	ds_read_b128 v[200:203], v145
	ds_read_b128 v[208:211], v145 offset:1024
	ds_read_b128 v[212:215], v145 offset:2048
	ds_read_b128 v[216:219], v145 offset:3072
	ds_read_b128 v[220:223], v145 offset:4096
	ds_read_b128 v[224:227], v145 offset:5120
	ds_read_b128 v[228:231], v145 offset:6144
	ds_read_b128 v[232:235], v145 offset:7168
	global_load_lds_dwordx4 v[140:141], off
	v_lshl_add_u64 v[140:141], s[50:51], 0, v[138:139]
	s_add_i32 m0, s58, 0xe000
	s_nop 0
	global_load_lds_dwordx4 v[140:141], off
	s_waitcnt vmcnt(8)
	s_waitcnt lgkmcnt(0)
	s_setprio 1
	s_barrier
	v_mfma_f32_16x16x32_bf16 v[126:129], v[146:149], v[200:203], 0
	v_mfma_f32_16x16x32_bf16 v[122:125], v[154:157], v[200:203], 0
	v_mfma_f32_16x16x32_bf16 v[110:113], v[146:149], v[212:215], 0
	v_mfma_f32_16x16x32_bf16 v[106:109], v[154:157], v[212:215], 0
	v_mfma_f32_16x16x32_bf16 v[94:97], v[146:149], v[220:223], 0
	v_mfma_f32_16x16x32_bf16 v[90:93], v[154:157], v[220:223], 0
	v_mfma_f32_16x16x32_bf16 v[78:81], v[146:149], v[228:231], 0
	v_mfma_f32_16x16x32_bf16 v[74:77], v[154:157], v[228:231], 0
	v_mfma_f32_16x16x32_bf16 v[126:129], v[150:153], v[208:211], v[126:129]
	v_mfma_f32_16x16x32_bf16 v[122:125], v[158:161], v[208:211], v[122:125]
	v_mfma_f32_16x16x32_bf16 v[110:113], v[150:153], v[216:219], v[110:113]
	v_mfma_f32_16x16x32_bf16 v[106:109], v[158:161], v[216:219], v[106:109]
	v_mfma_f32_16x16x32_bf16 v[94:97], v[150:153], v[224:227], v[94:97]
	v_mfma_f32_16x16x32_bf16 v[90:93], v[158:161], v[224:227], v[90:93]
	v_mfma_f32_16x16x32_bf16 v[78:81], v[150:153], v[232:235], v[78:81]
	v_mfma_f32_16x16x32_bf16 v[74:77], v[158:161], v[232:235], v[74:77]
	s_setprio 0
	s_setprio 1
	v_mfma_f32_16x16x32_bf16 v[118:121], v[174:177], v[200:203], 0
	v_mfma_f32_16x16x32_bf16 v[114:117], v[182:185], v[200:203], 0
	v_mfma_f32_16x16x32_bf16 v[102:105], v[174:177], v[212:215], 0
	v_mfma_f32_16x16x32_bf16 v[98:101], v[182:185], v[212:215], 0
	v_mfma_f32_16x16x32_bf16 v[86:89], v[174:177], v[220:223], 0
	v_mfma_f32_16x16x32_bf16 v[82:85], v[182:185], v[220:223], 0
	v_mfma_f32_16x16x32_bf16 v[70:73], v[174:177], v[228:231], 0
	v_mfma_f32_16x16x32_bf16 v[66:69], v[182:185], v[228:231], 0
	v_mfma_f32_16x16x32_bf16 v[118:121], v[178:181], v[208:211], v[118:121]
	v_mfma_f32_16x16x32_bf16 v[114:117], v[186:189], v[208:211], v[114:117]
	v_mfma_f32_16x16x32_bf16 v[102:105], v[178:181], v[216:219], v[102:105]
	v_mfma_f32_16x16x32_bf16 v[98:101], v[186:189], v[216:219], v[98:101]
	v_mfma_f32_16x16x32_bf16 v[86:89], v[178:181], v[224:227], v[86:89]
	v_mfma_f32_16x16x32_bf16 v[82:85], v[186:189], v[224:227], v[82:85]
	v_mfma_f32_16x16x32_bf16 v[70:73], v[178:181], v[232:235], v[70:73]
	v_mfma_f32_16x16x32_bf16 v[66:69], v[186:189], v[232:235], v[66:69]
	s_barrier
	s_setprio 0
	s_add_i32 s70, s70, s57
	v_lshl_add_u64 v[140:141], s[52:53], 0, v[0:1]
	s_mov_b32 m0, s70
	ds_read_b128 v[200:203], v145 offset:16384
	ds_read_b128 v[208:211], v145 offset:17408
	ds_read_b128 v[212:215], v145 offset:18432
	ds_read_b128 v[216:219], v145 offset:19456
	ds_read_b128 v[220:223], v145 offset:20480
	ds_read_b128 v[224:227], v145 offset:21504
	ds_read_b128 v[228:231], v145 offset:22528
	ds_read_b128 v[232:235], v145 offset:23552
	global_load_lds_dwordx4 v[140:141], off
	s_add_i32 m0, s70, 0x2000
	s_add_u32 s70, s52, 0x40000
	v_lshl_add_u64 v[190:191], s[52:53], 0, v[130:131]
	s_addc_u32 s71, s53, 0
	s_add_i32 vcc_hi, vcc_hi, s57
	global_load_lds_dwordx4 v[190:191], off
	v_lshl_add_u64 v[236:237], s[70:71], 0, v[0:1]
	s_mov_b32 m0, vcc_hi
	v_lshl_add_u64 v[238:239], s[54:55], 0, v[132:133]
	global_load_lds_dwordx4 v[236:237], off
	v_lshl_add_u64 v[236:237], s[70:71], 0, v[130:131]
	s_add_i32 m0, vcc_hi, 0x2000
	s_nop 0
	global_load_lds_dwordx4 v[236:237], off
	v_lshl_add_u64 v[236:237], s[54:55], 0, v[134:135]
	s_mov_b32 m0, s58
	s_nop 0
	global_load_lds_dwordx4 v[236:237], off
	s_mov_b32 m0, s59
	s_nop 0
	global_load_lds_dwordx4 v[238:239], off
	s_waitcnt vmcnt(8)
	s_waitcnt lgkmcnt(0)
	s_setprio 1
	s_barrier
; #define PG8_STAGEA(bufoff, gbase, voff) do { _Pragma("unroll") for (int _i = 0; _i < 2; ++_i) \
;         __builtin_amdgcn_global_load_lds((const unsigned*)((const char*)(gbase) + (voff)[_i]), (PG8_LAS unsigned*)(lds + (bufoff) + ldsw + _i * 8192), 16, 0, A_AUX); } while (0)
; #define PG8_LDA(dst, b, h) do { _Pragma("unroll") for (int m = 0; m < 4; ++m) _Pragma("unroll") for (int k = 0; k < 2; ++k) dst[m][k] = *(const PG8_LAS bf16x8*)(lds + PG8_SA(b, h) + aoff + m * 2048 + k * 1024); } while (0)
; #define PG8_LDB(dst, b, h) do { _Pragma("unroll") for (int n = 0; n < 2; ++n) _Pragma("unroll") for (int k = 0; k < 2; ++k) dst[n][k] = *(const PG8_LAS bf16x8*)(lds + PG8_SB(b, h) + boff + n * 2048 + k * 1024); } while (0)
; #define PG8_MMA(ai, bj, At, Bt) do { __builtin_amdgcn_s_setprio(1); _Pragma("unroll") for (int m = 0; m < 4; ++m) _Pragma("unroll") for (int n = 0; n < 2; ++n) _Pragma("unroll") for (int k = 0; k < 2; ++k) \
;         acc[ai][bj][m][n] = __builtin_amdgcn_mfma_f32_16x16x32_bf16(Bt[n][k], At[m][k], acc[ai][bj][m][n], 0, 0, 0); __builtin_amdgcn_s_setprio(0); } while (0)
; #define PG8_WAIT_V(n) asm volatile("s_waitcnt vmcnt(" #n ")" ::: "memory")
; #define PG8_WAIT_L(n) asm volatile("s_waitcnt lgkmcnt(" #n ")" ::: "memory")
; #define PG8_BAR __builtin_amdgcn_s_barrier()
; #define PG8_SCHED __builtin_amdgcn_sched_barrier(0)
;     ...
;             PG8_WAIT_V(8); PG8_WAIT_L(0); PG8_BAR; PG8_MMA(1, 0, At, B0); PG8_MMA(1, 1, At, B1); PG8_BAR; PG8_SCHED;
;             PG8_LDB(B0, 1, 0); PG8_LDB(B1, 1, 1); PG8_SCHED; PG8_LDA(At, 1, 0); PG8_STAGEA(PG8_SA(0, 1), a2 + hstep, voffA);
;             PG8_WAIT_V(8); PG8_WAIT_L(0); PG8_BAR; PG8_MMA(0, 0, At, B0); PG8_MMA(0, 1, At, B1); PG8_BAR; PG8_SCHED;
	v_mfma_f32_16x16x32_bf16 v[62:65], v[146:149], v[200:203], 0
	v_mfma_f32_16x16x32_bf16 v[58:61], v[154:157], v[200:203], 0
	v_mfma_f32_16x16x32_bf16 v[46:49], v[146:149], v[212:215], 0
	v_mfma_f32_16x16x32_bf16 v[42:45], v[154:157], v[212:215], 0
	v_mfma_f32_16x16x32_bf16 v[30:33], v[146:149], v[220:223], 0
	v_mfma_f32_16x16x32_bf16 v[26:29], v[154:157], v[220:223], 0
	v_mfma_f32_16x16x32_bf16 v[14:17], v[146:149], v[228:231], 0
	v_mfma_f32_16x16x32_bf16 v[10:13], v[154:157], v[228:231], 0
	v_mfma_f32_16x16x32_bf16 v[62:65], v[150:153], v[208:211], v[62:65]
	v_mfma_f32_16x16x32_bf16 v[58:61], v[158:161], v[208:211], v[58:61]
	v_mfma_f32_16x16x32_bf16 v[46:49], v[150:153], v[216:219], v[46:49]
	v_mfma_f32_16x16x32_bf16 v[42:45], v[158:161], v[216:219], v[42:45]
	v_mfma_f32_16x16x32_bf16 v[30:33], v[150:153], v[224:227], v[30:33]
	v_mfma_f32_16x16x32_bf16 v[26:29], v[158:161], v[224:227], v[26:29]
	v_mfma_f32_16x16x32_bf16 v[14:17], v[150:153], v[232:235], v[14:17]
	v_mfma_f32_16x16x32_bf16 v[10:13], v[158:161], v[232:235], v[10:13]
	s_setprio 0
	s_setprio 1
	v_mfma_f32_16x16x32_bf16 v[54:57], v[174:177], v[200:203], 0
	v_mfma_f32_16x16x32_bf16 v[50:53], v[182:185], v[200:203], 0
	v_mfma_f32_16x16x32_bf16 v[38:41], v[174:177], v[212:215], 0
	v_mfma_f32_16x16x32_bf16 v[34:37], v[182:185], v[212:215], 0
	v_mfma_f32_16x16x32_bf16 v[22:25], v[174:177], v[220:223], 0
	v_mfma_f32_16x16x32_bf16 v[18:21], v[182:185], v[220:223], 0
	v_mfma_f32_16x16x32_bf16 v[6:9], v[174:177], v[228:231], 0
	v_mfma_f32_16x16x32_bf16 v[2:5], v[182:185], v[228:231], 0
	v_mfma_f32_16x16x32_bf16 v[54:57], v[178:181], v[208:211], v[54:57]
	v_mfma_f32_16x16x32_bf16 v[50:53], v[186:189], v[208:211], v[50:53]
	v_mfma_f32_16x16x32_bf16 v[38:41], v[178:181], v[216:219], v[38:41]
	v_mfma_f32_16x16x32_bf16 v[34:37], v[186:189], v[216:219], v[34:37]
	v_mfma_f32_16x16x32_bf16 v[22:25], v[178:181], v[224:227], v[22:25]
	v_mfma_f32_16x16x32_bf16 v[18:21], v[186:189], v[224:227], v[18:21]
	v_mfma_f32_16x16x32_bf16 v[6:9], v[178:181], v[232:235], v[6:9]
	v_mfma_f32_16x16x32_bf16 v[2:5], v[186:189], v[232:235], v[2:5]
	s_barrier
	s_setprio 0
	s_add_i32 s70, 0, 0x18000
	s_add_i32 s71, 0, 0x1c000
	v_add_u32_e32 v158, s70, v143
	v_add_u32_e32 v186, s71, v143
	ds_read_b128 v[146:149], v158
	ds_read_b128 v[150:153], v158 offset:1024
	ds_read_b128 v[154:157], v158 offset:2048
	ds_read_b128 v[158:161], v158 offset:3072
	ds_read_b128 v[174:177], v186
	ds_read_b128 v[178:181], v186 offset:1024
	ds_read_b128 v[182:185], v186 offset:2048
	ds_read_b128 v[186:189], v186 offset:3072
	s_add_u32 s54, s54, 0x40000
	s_addc_u32 s55, s55, 0
	s_mov_b32 m0, s60
	v_lshl_add_u64 v[240:241], s[54:55], 0, v[134:135]
	ds_read_b128 v[200:203], v145 offset:32768
	ds_read_b128 v[208:211], v145 offset:33792
	ds_read_b128 v[212:215], v145 offset:34816
	ds_read_b128 v[216:219], v145 offset:35840
	ds_read_b128 v[220:223], v145 offset:36864
	ds_read_b128 v[224:227], v145 offset:37888
	ds_read_b128 v[228:231], v145 offset:38912
	ds_read_b128 v[232:235], v145 offset:39936
	global_load_lds_dwordx4 v[240:241], off
	v_lshl_add_u64 v[240:241], s[54:55], 0, v[132:133]
	s_mov_b32 m0, s61
	s_nop 0
	global_load_lds_dwordx4 v[240:241], off
	s_waitcnt vmcnt(8)
	s_waitcnt lgkmcnt(0)
	s_setprio 1
	s_barrier
	v_mfma_f32_16x16x32_bf16 v[126:129], v[146:149], v[200:203], v[126:129]
	v_mfma_f32_16x16x32_bf16 v[122:125], v[154:157], v[200:203], v[122:125]
	v_mfma_f32_16x16x32_bf16 v[110:113], v[146:149], v[212:215], v[110:113]
	v_mfma_f32_16x16x32_bf16 v[106:109], v[154:157], v[212:215], v[106:109]
	v_mfma_f32_16x16x32_bf16 v[94:97], v[146:149], v[220:223], v[94:97]
	v_mfma_f32_16x16x32_bf16 v[90:93], v[154:157], v[220:223], v[90:93]
	v_mfma_f32_16x16x32_bf16 v[78:81], v[146:149], v[228:231], v[78:81]
	v_mfma_f32_16x16x32_bf16 v[74:77], v[154:157], v[228:231], v[74:77]
	v_mfma_f32_16x16x32_bf16 v[126:129], v[150:153], v[208:211], v[126:129]
	v_mfma_f32_16x16x32_bf16 v[122:125], v[158:161], v[208:211], v[122:125]
	v_mfma_f32_16x16x32_bf16 v[110:113], v[150:153], v[216:219], v[110:113]
	v_mfma_f32_16x16x32_bf16 v[106:109], v[158:161], v[216:219], v[106:109]
	v_mfma_f32_16x16x32_bf16 v[94:97], v[150:153], v[224:227], v[94:97]
	v_mfma_f32_16x16x32_bf16 v[90:93], v[158:161], v[224:227], v[90:93]
	v_mfma_f32_16x16x32_bf16 v[78:81], v[150:153], v[232:235], v[78:81]
	v_mfma_f32_16x16x32_bf16 v[74:77], v[158:161], v[232:235], v[74:77]
	s_setprio 0
	s_setprio 1
	v_mfma_f32_16x16x32_bf16 v[118:121], v[174:177], v[200:203], v[118:121]
	v_mfma_f32_16x16x32_bf16 v[114:117], v[182:185], v[200:203], v[114:117]
	v_mfma_f32_16x16x32_bf16 v[102:105], v[174:177], v[212:215], v[102:105]
	v_mfma_f32_16x16x32_bf16 v[98:101], v[182:185], v[212:215], v[98:101]
	v_mfma_f32_16x16x32_bf16 v[86:89], v[174:177], v[220:223], v[86:89]
	v_mfma_f32_16x16x32_bf16 v[82:85], v[182:185], v[220:223], v[82:85]
	v_mfma_f32_16x16x32_bf16 v[70:73], v[174:177], v[228:231], v[70:73]
	v_mfma_f32_16x16x32_bf16 v[66:69], v[182:185], v[228:231], v[66:69]
	v_mfma_f32_16x16x32_bf16 v[118:121], v[178:181], v[208:211], v[118:121]
	v_mfma_f32_16x16x32_bf16 v[114:117], v[186:189], v[208:211], v[114:117]
	v_mfma_f32_16x16x32_bf16 v[102:105], v[178:181], v[216:219], v[102:105]
	v_mfma_f32_16x16x32_bf16 v[98:101], v[186:189], v[216:219], v[98:101]
	v_mfma_f32_16x16x32_bf16 v[86:89], v[178:181], v[224:227], v[86:89]
	v_mfma_f32_16x16x32_bf16 v[82:85], v[186:189], v[224:227], v[82:85]
	v_mfma_f32_16x16x32_bf16 v[70:73], v[178:181], v[232:235], v[70:73]
	v_mfma_f32_16x16x32_bf16 v[66:69], v[186:189], v[232:235], v[66:69]
	s_barrier
; #define PG8_STAGE(bufoff, gbase, voff) do { _Pragma("unroll") for (int _i = 0; _i < 2; ++_i) \
;         __builtin_amdgcn_global_load_lds((const unsigned*)((const char*)(gbase) + (voff)[_i]), (PG8_LAS unsigned*)(lds + (bufoff) + ldsw + _i * 8192), 16, 0, 0); } while (0)
; #define PG8_STAGEA(bufoff, gbase, voff) do { _Pragma("unroll") for (int _i = 0; _i < 2; ++_i) \
;         __builtin_amdgcn_global_load_lds((const unsigned*)((const char*)(gbase) + (voff)[_i]), (PG8_LAS unsigned*)(lds + (bufoff) + ldsw + _i * 8192), 16, 0, A_AUX); } while (0)
; #define PG8_LDA(dst, b, h) do { _Pragma("unroll") for (int m = 0; m < 4; ++m) _Pragma("unroll") for (int k = 0; k < 2; ++k) dst[m][k] = *(const PG8_LAS bf16x8*)(lds + PG8_SA(b, h) + aoff + m * 2048 + k * 1024); } while (0)
; #define PG8_LDB(dst, b, h) do { _Pragma("unroll") for (int n = 0; n < 2; ++n) _Pragma("unroll") for (int k = 0; k < 2; ++k) dst[n][k] = *(const PG8_LAS bf16x8*)(lds + PG8_SB(b, h) + boff + n * 2048 + k * 1024); } while (0)
; #define PG8_MMA(ai, bj, At, Bt) do { __builtin_amdgcn_s_setprio(1); _Pragma("unroll") for (int m = 0; m < 4; ++m) _Pragma("unroll") for (int n = 0; n < 2; ++n) _Pragma("unroll") for (int k = 0; k < 2; ++k) \
;         acc[ai][bj][m][n] = __builtin_amdgcn_mfma_f32_16x16x32_bf16(Bt[n][k], At[m][k], acc[ai][bj][m][n], 0, 0, 0); __builtin_amdgcn_s_setprio(0); } while (0)
; #define PG8_BAR __builtin_amdgcn_s_barrier()
;     ...
;         for (int t = 0; t < nt; t += 2) {
;             const bool last = (t == nt - 2);
;             const char* a1 = cA + (size_t)(t + 1) * kstep;
;             const char* a2 = last ? nA : cA + (size_t)(t + 2) * kstep; const char* b2 = last ? nB : cB + (size_t)(t + 2) * kstep;
;             const char* a3 = a2 + kstep; const char* b3 = b2 + kstep;
;             if (last && has_next) S.a_ready(nxt);
;             if constexpr (SP2) {
;             PG8_LDB(B0, 0, 0); PG8_LDB(B1, 0, 1); PG8_SCHED; PG8_LDA(At, 0, 0); PG8_STAGEA(PG8_SA(1, 1), a1 + hstep, voffA);
;             PG8_WAIT_V(8); PG8_WAIT_L(0); PG8_BAR; PG8_MMA(0, 0, At, B0); PG8_MMA(0, 1, At, B1); PG8_BAR; PG8_SCHED;
;     ...
;             PG8_LDA(At, 1, 1); PG8_STAGE(PG8_SB(1, 0), b3, voffB); PG8_STAGE(PG8_SB(1, 1), b3 + hstep, voffB); PG8_STAGEA(PG8_SA(1, 0), a3, voffA);
;             PG8_WAIT_V(8); PG8_WAIT_L(0); PG8_BAR; PG8_MMA(1, 0, At, B0); PG8_MMA(1, 1, At, B1); PG8_BAR; PG8_SCHED;
	s_setprio 0
	s_add_i32 s54, s70, s57
	v_lshl_add_u64 v[140:141], v[140:141], 0, s[8:9]
	s_mov_b32 m0, s54
	ds_read_b128 v[200:203], v145 offset:49152
	ds_read_b128 v[208:211], v145 offset:50176
	ds_read_b128 v[212:215], v145 offset:51200
	ds_read_b128 v[216:219], v145 offset:52224
	ds_read_b128 v[220:223], v145 offset:53248
	ds_read_b128 v[224:227], v145 offset:54272
	ds_read_b128 v[228:231], v145 offset:55296
	ds_read_b128 v[232:235], v145 offset:56320
	global_load_lds_dwordx4 v[140:141], off
	s_add_i32 m0, s54, 0x2000
	s_add_u32 s52, s52, 0x40080
	v_lshl_add_u64 v[140:141], v[190:191], 0, s[8:9]
	s_addc_u32 s53, s53, 0
	s_add_i32 s54, s71, s57
	global_load_lds_dwordx4 v[140:141], off
	v_lshl_add_u64 v[140:141], s[52:53], 0, v[0:1]
	s_mov_b32 m0, s54
	s_nop 0
	global_load_lds_dwordx4 v[140:141], off
	v_lshl_add_u64 v[140:141], s[52:53], 0, v[130:131]
	s_add_i32 m0, s54, 0x2000
	s_nop 0
	global_load_lds_dwordx4 v[140:141], off
	v_lshl_add_u64 v[140:141], v[236:237], 0, s[8:9]
	s_mov_b32 m0, s62
	s_nop 0
	global_load_lds_dwordx4 v[140:141], off
	v_lshl_add_u64 v[140:141], v[238:239], 0, s[8:9]
	s_mov_b32 m0, s63
	s_nop 0
	global_load_lds_dwordx4 v[140:141], off
	s_waitcnt vmcnt(8)
	s_waitcnt lgkmcnt(0)
	s_setprio 1
	s_barrier
	v_mfma_f32_16x16x32_bf16 v[62:65], v[146:149], v[200:203], v[62:65]
	v_mfma_f32_16x16x32_bf16 v[58:61], v[154:157], v[200:203], v[58:61]
	v_mfma_f32_16x16x32_bf16 v[46:49], v[146:149], v[212:215], v[46:49]
	v_mfma_f32_16x16x32_bf16 v[42:45], v[154:157], v[212:215], v[42:45]
	v_mfma_f32_16x16x32_bf16 v[30:33], v[146:149], v[220:223], v[30:33]
	v_mfma_f32_16x16x32_bf16 v[26:29], v[154:157], v[220:223], v[26:29]
	v_mfma_f32_16x16x32_bf16 v[14:17], v[146:149], v[228:231], v[14:17]
	v_mfma_f32_16x16x32_bf16 v[10:13], v[154:157], v[228:231], v[10:13]
	v_mfma_f32_16x16x32_bf16 v[62:65], v[150:153], v[208:211], v[62:65]
	v_mfma_f32_16x16x32_bf16 v[58:61], v[158:161], v[208:211], v[58:61]
	v_mfma_f32_16x16x32_bf16 v[46:49], v[150:153], v[216:219], v[46:49]
	v_mfma_f32_16x16x32_bf16 v[42:45], v[158:161], v[216:219], v[42:45]
	v_mfma_f32_16x16x32_bf16 v[30:33], v[150:153], v[224:227], v[30:33]
	v_mfma_f32_16x16x32_bf16 v[26:29], v[158:161], v[224:227], v[26:29]
	v_mfma_f32_16x16x32_bf16 v[14:17], v[150:153], v[232:235], v[14:17]
	v_mfma_f32_16x16x32_bf16 v[10:13], v[158:161], v[232:235], v[10:13]
	s_setprio 0
	s_setprio 1
	v_mfma_f32_16x16x32_bf16 v[54:57], v[174:177], v[200:203], v[54:57]
	v_mfma_f32_16x16x32_bf16 v[50:53], v[182:185], v[200:203], v[50:53]
	v_mfma_f32_16x16x32_bf16 v[38:41], v[174:177], v[212:215], v[38:41]
	v_mfma_f32_16x16x32_bf16 v[34:37], v[182:185], v[212:215], v[34:37]
	v_mfma_f32_16x16x32_bf16 v[22:25], v[174:177], v[220:223], v[22:25]
	v_mfma_f32_16x16x32_bf16 v[18:21], v[182:185], v[220:223], v[18:21]
	v_mfma_f32_16x16x32_bf16 v[6:9], v[174:177], v[228:231], v[6:9]
	v_mfma_f32_16x16x32_bf16 v[2:5], v[182:185], v[228:231], v[2:5]
	v_mfma_f32_16x16x32_bf16 v[54:57], v[178:181], v[208:211], v[54:57]
	v_mfma_f32_16x16x32_bf16 v[50:53], v[186:189], v[208:211], v[50:53]
	v_mfma_f32_16x16x32_bf16 v[38:41], v[178:181], v[216:219], v[38:41]
	v_mfma_f32_16x16x32_bf16 v[34:37], v[186:189], v[216:219], v[34:37]
	v_mfma_f32_16x16x32_bf16 v[22:25], v[178:181], v[224:227], v[22:25]
	v_mfma_f32_16x16x32_bf16 v[18:21], v[186:189], v[224:227], v[18:21]
	v_mfma_f32_16x16x32_bf16 v[6:9], v[178:181], v[232:235], v[6:9]
	v_mfma_f32_16x16x32_bf16 v[2:5], v[186:189], v[232:235], v[2:5]
	s_barrier
	s_setprio 0
	s_add_i32 vcc_lo, vcc_lo, 2
	s_add_u32 s50, s50, 0x100
	s_addc_u32 s51, s51, 0
	s_add_u32 s73, s73, 0x100
	s_addc_u32 s76, s76, 0
.LBB0_580:
	s_add_u32 s52, s50, 0xfffc0080
	s_addc_u32 s53, s51, -1
	s_add_i32 s70, 0, 0x10000
	s_cmp_eq_u32 vcc_lo, 12
	s_cselect_b32 s55, s16, s53
	s_cselect_b32 s54, s17, s52
	v_add_u32_e32 v140, s70, v143
	s_cselect_b32 s53, s43, s76
	s_cselect_b32 s52, s45, s73
	s_add_i32 vcc_hi, 0, 0x14000
	ds_read_b128 v[146:149], v140
	ds_read_b128 v[150:153], v140 offset:1024
	ds_read_b128 v[154:157], v140 offset:2048
	ds_read_b128 v[158:161], v140 offset:3072
	v_add_u32_e32 v140, vcc_hi, v143
	ds_read_b128 v[174:177], v140
	ds_read_b128 v[178:181], v140 offset:1024
	ds_read_b128 v[182:185], v140 offset:2048
	ds_read_b128 v[186:189], v140 offset:3072
	v_lshl_add_u64 v[140:141], s[50:51], 0, v[136:137]
	s_add_i32 m0, s58, 0xc000
	ds_read_b128 v[200:203], v145
	ds_read_b128 v[208:211], v145 offset:1024
	ds_read_b128 v[212:215], v145 offset:2048
	ds_read_b128 v[216:219], v145 offset:3072
	ds_read_b128 v[220:223], v145 offset:4096
	ds_read_b128 v[224:227], v145 offset:5120
	ds_read_b128 v[228:231], v145 offset:6144
	ds_read_b128 v[232:235], v145 offset:7168
	global_load_lds_dwordx4 v[140:141], off
	v_lshl_add_u64 v[140:141], s[50:51], 0, v[138:139]
	s_add_i32 m0, s58, 0xe000
	s_nop 0
	global_load_lds_dwordx4 v[140:141], off
	s_waitcnt vmcnt(8)
	s_waitcnt lgkmcnt(0)
	s_setprio 1
	s_barrier
; #define PG8_STAGE(bufoff, gbase, voff) do { _Pragma("unroll") for (int _i = 0; _i < 2; ++_i) \
;         __builtin_amdgcn_global_load_lds((const unsigned*)((const char*)(gbase) + (voff)[_i]), (PG8_LAS unsigned*)(lds + (bufoff) + ldsw + _i * 8192), 16, 0, 0); } while (0)
; #define PG8_STAGEA(bufoff, gbase, voff) do { _Pragma("unroll") for (int _i = 0; _i < 2; ++_i) \
;         __builtin_amdgcn_global_load_lds((const unsigned*)((const char*)(gbase) + (voff)[_i]), (PG8_LAS unsigned*)(lds + (bufoff) + ldsw + _i * 8192), 16, 0, A_AUX); } while (0)
; #define PG8_LDA(dst, b, h) do { _Pragma("unroll") for (int m = 0; m < 4; ++m) _Pragma("unroll") for (int k = 0; k < 2; ++k) dst[m][k] = *(const PG8_LAS bf16x8*)(lds + PG8_SA(b, h) + aoff + m * 2048 + k * 1024); } while (0)
; #define PG8_MMA(ai, bj, At, Bt) do { __builtin_amdgcn_s_setprio(1); _Pragma("unroll") for (int m = 0; m < 4; ++m) _Pragma("unroll") for (int n = 0; n < 2; ++n) _Pragma("unroll") for (int k = 0; k < 2; ++k) \
;         acc[ai][bj][m][n] = __builtin_amdgcn_mfma_f32_16x16x32_bf16(Bt[n][k], At[m][k], acc[ai][bj][m][n], 0, 0, 0); __builtin_amdgcn_s_setprio(0); } while (0)
; #define PG8_WAIT_V(n) asm volatile("s_waitcnt vmcnt(" #n ")" ::: "memory")
; #define PG8_WAIT_L(n) asm volatile("s_waitcnt lgkmcnt(" #n ")" ::: "memory")
; #define PG8_BAR __builtin_amdgcn_s_barrier()
; #define PG8_SCHED __builtin_amdgcn_sched_barrier(0)
;     ...
;             PG8_WAIT_V(8); PG8_WAIT_L(0); PG8_BAR; PG8_MMA(0, 0, At, B0); PG8_MMA(0, 1, At, B1); PG8_BAR; PG8_SCHED;
;             PG8_LDA(At, 0, 1); PG8_STAGE(PG8_SB(0, 0), b2, voffB); PG8_STAGE(PG8_SB(0, 1), b2 + hstep, voffB); PG8_STAGEA(PG8_SA(0, 0), a2, voffA);
;             PG8_WAIT_V(8); PG8_WAIT_L(0); PG8_BAR; PG8_MMA(1, 0, At, B0); PG8_MMA(1, 1, At, B1); PG8_BAR; PG8_SCHED;
	v_mfma_f32_16x16x32_bf16 v[126:129], v[146:149], v[200:203], v[126:129]
	v_mfma_f32_16x16x32_bf16 v[122:125], v[154:157], v[200:203], v[122:125]
	v_mfma_f32_16x16x32_bf16 v[110:113], v[146:149], v[212:215], v[110:113]
	v_mfma_f32_16x16x32_bf16 v[106:109], v[154:157], v[212:215], v[106:109]
	v_mfma_f32_16x16x32_bf16 v[94:97], v[146:149], v[220:223], v[94:97]
	v_mfma_f32_16x16x32_bf16 v[90:93], v[154:157], v[220:223], v[90:93]
	v_mfma_f32_16x16x32_bf16 v[78:81], v[146:149], v[228:231], v[78:81]
	v_mfma_f32_16x16x32_bf16 v[74:77], v[154:157], v[228:231], v[74:77]
	v_mfma_f32_16x16x32_bf16 v[126:129], v[150:153], v[208:211], v[126:129]
	v_mfma_f32_16x16x32_bf16 v[122:125], v[158:161], v[208:211], v[122:125]
	v_mfma_f32_16x16x32_bf16 v[110:113], v[150:153], v[216:219], v[110:113]
	v_mfma_f32_16x16x32_bf16 v[106:109], v[158:161], v[216:219], v[106:109]
	v_mfma_f32_16x16x32_bf16 v[94:97], v[150:153], v[224:227], v[94:97]
	v_mfma_f32_16x16x32_bf16 v[90:93], v[158:161], v[224:227], v[90:93]
	v_mfma_f32_16x16x32_bf16 v[78:81], v[150:153], v[232:235], v[78:81]
	v_mfma_f32_16x16x32_bf16 v[74:77], v[158:161], v[232:235], v[74:77]
	s_setprio 0
	s_setprio 1
	v_mfma_f32_16x16x32_bf16 v[118:121], v[174:177], v[200:203], v[118:121]
	v_mfma_f32_16x16x32_bf16 v[114:117], v[182:185], v[200:203], v[114:117]
	v_mfma_f32_16x16x32_bf16 v[102:105], v[174:177], v[212:215], v[102:105]
	v_mfma_f32_16x16x32_bf16 v[98:101], v[182:185], v[212:215], v[98:101]
	v_mfma_f32_16x16x32_bf16 v[86:89], v[174:177], v[220:223], v[86:89]
	v_mfma_f32_16x16x32_bf16 v[82:85], v[182:185], v[220:223], v[82:85]
	v_mfma_f32_16x16x32_bf16 v[70:73], v[174:177], v[228:231], v[70:73]
	v_mfma_f32_16x16x32_bf16 v[66:69], v[182:185], v[228:231], v[66:69]
	v_mfma_f32_16x16x32_bf16 v[118:121], v[178:181], v[208:211], v[118:121]
	v_mfma_f32_16x16x32_bf16 v[114:117], v[186:189], v[208:211], v[114:117]
	v_mfma_f32_16x16x32_bf16 v[102:105], v[178:181], v[216:219], v[102:105]
	v_mfma_f32_16x16x32_bf16 v[98:101], v[186:189], v[216:219], v[98:101]
	v_mfma_f32_16x16x32_bf16 v[86:89], v[178:181], v[224:227], v[86:89]
	v_mfma_f32_16x16x32_bf16 v[82:85], v[186:189], v[224:227], v[82:85]
	v_mfma_f32_16x16x32_bf16 v[70:73], v[178:181], v[232:235], v[70:73]
	v_mfma_f32_16x16x32_bf16 v[66:69], v[186:189], v[232:235], v[66:69]
	s_barrier
	s_setprio 0
	s_add_i32 s70, s70, s57
	v_lshl_add_u64 v[140:141], s[52:53], 0, v[0:1]
	s_mov_b32 m0, s70
	ds_read_b128 v[200:203], v145 offset:16384
	ds_read_b128 v[208:211], v145 offset:17408
	ds_read_b128 v[212:215], v145 offset:18432
	ds_read_b128 v[216:219], v145 offset:19456
	ds_read_b128 v[220:223], v145 offset:20480
	ds_read_b128 v[224:227], v145 offset:21504
	ds_read_b128 v[228:231], v145 offset:22528
	ds_read_b128 v[232:235], v145 offset:23552
	global_load_lds_dwordx4 v[140:141], off
	s_add_i32 m0, s70, 0x2000
	s_add_u32 s70, s52, 0x40000
	v_lshl_add_u64 v[190:191], s[52:53], 0, v[130:131]
	s_addc_u32 s71, s53, 0
	s_add_i32 vcc_hi, vcc_hi, s57
	global_load_lds_dwordx4 v[190:191], off
	v_lshl_add_u64 v[236:237], s[70:71], 0, v[0:1]
	s_mov_b32 m0, vcc_hi
	v_lshl_add_u64 v[238:239], s[54:55], 0, v[132:133]
	global_load_lds_dwordx4 v[236:237], off
	v_lshl_add_u64 v[236:237], s[70:71], 0, v[130:131]
	s_add_i32 m0, vcc_hi, 0x2000
	s_nop 0
	global_load_lds_dwordx4 v[236:237], off
	v_lshl_add_u64 v[236:237], s[54:55], 0, v[134:135]
	s_mov_b32 m0, s58
	s_nop 0
	global_load_lds_dwordx4 v[236:237], off
	s_mov_b32 m0, s59
	s_nop 0
	global_load_lds_dwordx4 v[238:239], off
	s_waitcnt vmcnt(8)
	s_waitcnt lgkmcnt(0)
	s_setprio 1
	s_barrier
	v_mfma_f32_16x16x32_bf16 v[62:65], v[146:149], v[200:203], v[62:65]
	v_mfma_f32_16x16x32_bf16 v[58:61], v[154:157], v[200:203], v[58:61]
	v_mfma_f32_16x16x32_bf16 v[46:49], v[146:149], v[212:215], v[46:49]
	v_mfma_f32_16x16x32_bf16 v[42:45], v[154:157], v[212:215], v[42:45]
	v_mfma_f32_16x16x32_bf16 v[30:33], v[146:149], v[220:223], v[30:33]
	v_mfma_f32_16x16x32_bf16 v[26:29], v[154:157], v[220:223], v[26:29]
	v_mfma_f32_16x16x32_bf16 v[14:17], v[146:149], v[228:231], v[14:17]
	v_mfma_f32_16x16x32_bf16 v[10:13], v[154:157], v[228:231], v[10:13]
	v_mfma_f32_16x16x32_bf16 v[62:65], v[150:153], v[208:211], v[62:65]
	v_mfma_f32_16x16x32_bf16 v[58:61], v[158:161], v[208:211], v[58:61]
	v_mfma_f32_16x16x32_bf16 v[46:49], v[150:153], v[216:219], v[46:49]
	v_mfma_f32_16x16x32_bf16 v[42:45], v[158:161], v[216:219], v[42:45]
	v_mfma_f32_16x16x32_bf16 v[30:33], v[150:153], v[224:227], v[30:33]
	v_mfma_f32_16x16x32_bf16 v[26:29], v[158:161], v[224:227], v[26:29]
	v_mfma_f32_16x16x32_bf16 v[14:17], v[150:153], v[232:235], v[14:17]
	v_mfma_f32_16x16x32_bf16 v[10:13], v[158:161], v[232:235], v[10:13]
	s_setprio 0
	s_setprio 1
	v_mfma_f32_16x16x32_bf16 v[54:57], v[174:177], v[200:203], v[54:57]
	v_mfma_f32_16x16x32_bf16 v[50:53], v[182:185], v[200:203], v[50:53]
	v_mfma_f32_16x16x32_bf16 v[38:41], v[174:177], v[212:215], v[38:41]
	v_mfma_f32_16x16x32_bf16 v[34:37], v[182:185], v[212:215], v[34:37]
	v_mfma_f32_16x16x32_bf16 v[22:25], v[174:177], v[220:223], v[22:25]
	v_mfma_f32_16x16x32_bf16 v[18:21], v[182:185], v[220:223], v[18:21]
	v_mfma_f32_16x16x32_bf16 v[6:9], v[174:177], v[228:231], v[6:9]
	v_mfma_f32_16x16x32_bf16 v[2:5], v[182:185], v[228:231], v[2:5]
	v_mfma_f32_16x16x32_bf16 v[54:57], v[178:181], v[208:211], v[54:57]
	v_mfma_f32_16x16x32_bf16 v[50:53], v[186:189], v[208:211], v[50:53]
	v_mfma_f32_16x16x32_bf16 v[38:41], v[178:181], v[216:219], v[38:41]
	v_mfma_f32_16x16x32_bf16 v[34:37], v[186:189], v[216:219], v[34:37]
	v_mfma_f32_16x16x32_bf16 v[22:25], v[178:181], v[224:227], v[22:25]
	v_mfma_f32_16x16x32_bf16 v[18:21], v[186:189], v[224:227], v[18:21]
	v_mfma_f32_16x16x32_bf16 v[6:9], v[178:181], v[232:235], v[6:9]
	v_mfma_f32_16x16x32_bf16 v[2:5], v[186:189], v[232:235], v[2:5]
	s_barrier
; #define PG8_STAGEA(bufoff, gbase, voff) do { _Pragma("unroll") for (int _i = 0; _i < 2; ++_i) \
;         __builtin_amdgcn_global_load_lds((const unsigned*)((const char*)(gbase) + (voff)[_i]), (PG8_LAS unsigned*)(lds + (bufoff) + ldsw + _i * 8192), 16, 0, A_AUX); } while (0)
; #define PG8_LDA(dst, b, h) do { _Pragma("unroll") for (int m = 0; m < 4; ++m) _Pragma("unroll") for (int k = 0; k < 2; ++k) dst[m][k] = *(const PG8_LAS bf16x8*)(lds + PG8_SA(b, h) + aoff + m * 2048 + k * 1024); } while (0)
; #define PG8_LDB(dst, b, h) do { _Pragma("unroll") for (int n = 0; n < 2; ++n) _Pragma("unroll") for (int k = 0; k < 2; ++k) dst[n][k] = *(const PG8_LAS bf16x8*)(lds + PG8_SB(b, h) + boff + n * 2048 + k * 1024); } while (0)
; #define PG8_MMA(ai, bj, At, Bt) do { __builtin_amdgcn_s_setprio(1); _Pragma("unroll") for (int m = 0; m < 4; ++m) _Pragma("unroll") for (int n = 0; n < 2; ++n) _Pragma("unroll") for (int k = 0; k < 2; ++k) \
;         acc[ai][bj][m][n] = __builtin_amdgcn_mfma_f32_16x16x32_bf16(Bt[n][k], At[m][k], acc[ai][bj][m][n], 0, 0, 0); __builtin_amdgcn_s_setprio(0); } while (0)
; #define PG8_WAIT_V(n) asm volatile("s_waitcnt vmcnt(" #n ")" ::: "memory")
; #define PG8_WAIT_L(n) asm volatile("s_waitcnt lgkmcnt(" #n ")" ::: "memory")
; #define PG8_BAR __builtin_amdgcn_s_barrier()
; #define PG8_SCHED __builtin_amdgcn_sched_barrier(0)
;     ...
;             PG8_LDB(B0, 1, 0); PG8_LDB(B1, 1, 1); PG8_SCHED; PG8_LDA(At, 1, 0); PG8_STAGEA(PG8_SA(0, 1), a2 + hstep, voffA);
;             PG8_WAIT_V(8); PG8_WAIT_L(0); PG8_BAR; PG8_MMA(0, 0, At, B0); PG8_MMA(0, 1, At, B1); PG8_BAR; PG8_SCHED;
	s_setprio 0
	s_add_i32 s70, 0, 0x18000
	s_add_i32 s71, 0, 0x1c000
	v_add_u32_e32 v158, s70, v143
	v_add_u32_e32 v186, s71, v143
	ds_read_b128 v[146:149], v158
	ds_read_b128 v[150:153], v158 offset:1024
	ds_read_b128 v[154:157], v158 offset:2048
	ds_read_b128 v[158:161], v158 offset:3072
	ds_read_b128 v[174:177], v186
	ds_read_b128 v[178:181], v186 offset:1024
	ds_read_b128 v[182:185], v186 offset:2048
	ds_read_b128 v[186:189], v186 offset:3072
	s_add_u32 s54, s54, 0x40000
	s_addc_u32 s55, s55, 0
	s_mov_b32 m0, s60
	v_lshl_add_u64 v[240:241], s[54:55], 0, v[134:135]
	ds_read_b128 v[200:203], v145 offset:32768
	ds_read_b128 v[208:211], v145 offset:33792
	ds_read_b128 v[212:215], v145 offset:34816
	ds_read_b128 v[216:219], v145 offset:35840
	ds_read_b128 v[220:223], v145 offset:36864
	ds_read_b128 v[224:227], v145 offset:37888
	ds_read_b128 v[228:231], v145 offset:38912
	ds_read_b128 v[232:235], v145 offset:39936
	global_load_lds_dwordx4 v[240:241], off
	v_lshl_add_u64 v[240:241], s[54:55], 0, v[132:133]
	s_mov_b32 m0, s61
	s_nop 0
	global_load_lds_dwordx4 v[240:241], off
	s_waitcnt vmcnt(8)
	s_waitcnt lgkmcnt(0)
	s_setprio 1
	s_barrier
	v_mfma_f32_16x16x32_bf16 v[126:129], v[146:149], v[200:203], v[126:129]
	v_mfma_f32_16x16x32_bf16 v[122:125], v[154:157], v[200:203], v[122:125]
	v_mfma_f32_16x16x32_bf16 v[110:113], v[146:149], v[212:215], v[110:113]
	v_mfma_f32_16x16x32_bf16 v[106:109], v[154:157], v[212:215], v[106:109]
	v_mfma_f32_16x16x32_bf16 v[94:97], v[146:149], v[220:223], v[94:97]
	v_mfma_f32_16x16x32_bf16 v[90:93], v[154:157], v[220:223], v[90:93]
	v_mfma_f32_16x16x32_bf16 v[78:81], v[146:149], v[228:231], v[78:81]
	v_mfma_f32_16x16x32_bf16 v[74:77], v[154:157], v[228:231], v[74:77]
	v_mfma_f32_16x16x32_bf16 v[126:129], v[150:153], v[208:211], v[126:129]
	v_mfma_f32_16x16x32_bf16 v[122:125], v[158:161], v[208:211], v[122:125]
	v_mfma_f32_16x16x32_bf16 v[110:113], v[150:153], v[216:219], v[110:113]
	v_mfma_f32_16x16x32_bf16 v[106:109], v[158:161], v[216:219], v[106:109]
	v_mfma_f32_16x16x32_bf16 v[94:97], v[150:153], v[224:227], v[94:97]
	v_mfma_f32_16x16x32_bf16 v[90:93], v[158:161], v[224:227], v[90:93]
	v_mfma_f32_16x16x32_bf16 v[78:81], v[150:153], v[232:235], v[78:81]
	v_mfma_f32_16x16x32_bf16 v[74:77], v[158:161], v[232:235], v[74:77]
	s_setprio 0
	s_setprio 1
	v_mfma_f32_16x16x32_bf16 v[118:121], v[174:177], v[200:203], v[118:121]
	v_mfma_f32_16x16x32_bf16 v[114:117], v[182:185], v[200:203], v[114:117]
	v_mfma_f32_16x16x32_bf16 v[102:105], v[174:177], v[212:215], v[102:105]
	v_mfma_f32_16x16x32_bf16 v[98:101], v[182:185], v[212:215], v[98:101]
	v_mfma_f32_16x16x32_bf16 v[86:89], v[174:177], v[220:223], v[86:89]
	v_mfma_f32_16x16x32_bf16 v[82:85], v[182:185], v[220:223], v[82:85]
	v_mfma_f32_16x16x32_bf16 v[70:73], v[174:177], v[228:231], v[70:73]
	v_mfma_f32_16x16x32_bf16 v[66:69], v[182:185], v[228:231], v[66:69]
	v_mfma_f32_16x16x32_bf16 v[118:121], v[178:181], v[208:211], v[118:121]
	v_mfma_f32_16x16x32_bf16 v[114:117], v[186:189], v[208:211], v[114:117]
	v_mfma_f32_16x16x32_bf16 v[102:105], v[178:181], v[216:219], v[102:105]
	v_mfma_f32_16x16x32_bf16 v[98:101], v[186:189], v[216:219], v[98:101]
	v_mfma_f32_16x16x32_bf16 v[86:89], v[178:181], v[224:227], v[86:89]
	v_mfma_f32_16x16x32_bf16 v[82:85], v[186:189], v[224:227], v[82:85]
	v_mfma_f32_16x16x32_bf16 v[70:73], v[178:181], v[232:235], v[70:73]
	v_mfma_f32_16x16x32_bf16 v[66:69], v[186:189], v[232:235], v[66:69]
	s_barrier
; #define PG8_STAGE(bufoff, gbase, voff) do { _Pragma("unroll") for (int _i = 0; _i < 2; ++_i) \
;         __builtin_amdgcn_global_load_lds((const unsigned*)((const char*)(gbase) + (voff)[_i]), (PG8_LAS unsigned*)(lds + (bufoff) + ldsw + _i * 8192), 16, 0, 0); } while (0)
; #define PG8_STAGEA(bufoff, gbase, voff) do { _Pragma("unroll") for (int _i = 0; _i < 2; ++_i) \
;         __builtin_amdgcn_global_load_lds((const unsigned*)((const char*)(gbase) + (voff)[_i]), (PG8_LAS unsigned*)(lds + (bufoff) + ldsw + _i * 8192), 16, 0, A_AUX); } while (0)
; #define PG8_LDA(dst, b, h) do { _Pragma("unroll") for (int m = 0; m < 4; ++m) _Pragma("unroll") for (int k = 0; k < 2; ++k) dst[m][k] = *(const PG8_LAS bf16x8*)(lds + PG8_SA(b, h) + aoff + m * 2048 + k * 1024); } while (0)
; #define PG8_MMA(ai, bj, At, Bt) do { __builtin_amdgcn_s_setprio(1); _Pragma("unroll") for (int m = 0; m < 4; ++m) _Pragma("unroll") for (int n = 0; n < 2; ++n) _Pragma("unroll") for (int k = 0; k < 2; ++k) \
;         acc[ai][bj][m][n] = __builtin_amdgcn_mfma_f32_16x16x32_bf16(Bt[n][k], At[m][k], acc[ai][bj][m][n], 0, 0, 0); __builtin_amdgcn_s_setprio(0); } while (0)
; #define PG8_WAIT_V(n) asm volatile("s_waitcnt vmcnt(" #n ")" ::: "memory")
; #define PG8_WAIT_L(n) asm volatile("s_waitcnt lgkmcnt(" #n ")" ::: "memory")
; #define PG8_BAR __builtin_amdgcn_s_barrier()
; #define PG8_SCHED __builtin_amdgcn_sched_barrier(0)
;     ...
;         for (int t = 0; t < nt; t += 2) {
;             const bool last = (t == nt - 2);
;             const char* a1 = cA + (size_t)(t + 1) * kstep;
;             const char* a2 = last ? nA : cA + (size_t)(t + 2) * kstep; const char* b2 = last ? nB : cB + (size_t)(t + 2) * kstep;
;             const char* a3 = a2 + kstep; const char* b3 = b2 + kstep;
;             if (last && has_next) S.a_ready(nxt);
;     ...
;             PG8_LDA(At, 1, 1); PG8_STAGE(PG8_SB(1, 0), b3, voffB); PG8_STAGE(PG8_SB(1, 1), b3 + hstep, voffB); PG8_STAGEA(PG8_SA(1, 0), a3, voffA);
;             PG8_WAIT_V(8); PG8_WAIT_L(0); PG8_BAR; PG8_MMA(1, 0, At, B0); PG8_MMA(1, 1, At, B1); PG8_BAR; PG8_SCHED;
	s_setprio 0
	s_add_i32 s54, s70, s57
	v_lshl_add_u64 v[140:141], v[140:141], 0, s[8:9]
	s_mov_b32 m0, s54
	ds_read_b128 v[200:203], v145 offset:49152
	ds_read_b128 v[208:211], v145 offset:50176
	ds_read_b128 v[212:215], v145 offset:51200
	ds_read_b128 v[216:219], v145 offset:52224
	ds_read_b128 v[220:223], v145 offset:53248
	ds_read_b128 v[224:227], v145 offset:54272
	ds_read_b128 v[228:231], v145 offset:55296
	ds_read_b128 v[232:235], v145 offset:56320
	global_load_lds_dwordx4 v[140:141], off
	s_add_i32 m0, s54, 0x2000
	s_add_u32 s52, s52, 0x40080
	v_lshl_add_u64 v[140:141], v[190:191], 0, s[8:9]
	s_addc_u32 s53, s53, 0
	s_add_i32 s54, s71, s57
	global_load_lds_dwordx4 v[140:141], off
	v_lshl_add_u64 v[140:141], s[52:53], 0, v[0:1]
	s_mov_b32 m0, s54
	s_nop 0
	global_load_lds_dwordx4 v[140:141], off
	v_lshl_add_u64 v[140:141], s[52:53], 0, v[130:131]
	s_add_i32 m0, s54, 0x2000
	s_nop 0
	global_load_lds_dwordx4 v[140:141], off
	v_lshl_add_u64 v[140:141], v[236:237], 0, s[8:9]
	s_mov_b32 m0, s62
	s_nop 0
	global_load_lds_dwordx4 v[140:141], off
	v_lshl_add_u64 v[140:141], v[238:239], 0, s[8:9]
	s_mov_b32 m0, s63
	s_nop 0
	global_load_lds_dwordx4 v[140:141], off
	s_waitcnt vmcnt(8)
	s_waitcnt lgkmcnt(0)
	s_setprio 1
	s_barrier
	v_mfma_f32_16x16x32_bf16 v[62:65], v[146:149], v[200:203], v[62:65]
	v_mfma_f32_16x16x32_bf16 v[58:61], v[154:157], v[200:203], v[58:61]
	v_mfma_f32_16x16x32_bf16 v[46:49], v[146:149], v[212:215], v[46:49]
	v_mfma_f32_16x16x32_bf16 v[42:45], v[154:157], v[212:215], v[42:45]
	v_mfma_f32_16x16x32_bf16 v[30:33], v[146:149], v[220:223], v[30:33]
	v_mfma_f32_16x16x32_bf16 v[26:29], v[154:157], v[220:223], v[26:29]
	v_mfma_f32_16x16x32_bf16 v[14:17], v[146:149], v[228:231], v[14:17]
	v_mfma_f32_16x16x32_bf16 v[10:13], v[154:157], v[228:231], v[10:13]
	v_mfma_f32_16x16x32_bf16 v[62:65], v[150:153], v[208:211], v[62:65]
	v_mfma_f32_16x16x32_bf16 v[58:61], v[158:161], v[208:211], v[58:61]
	v_mfma_f32_16x16x32_bf16 v[46:49], v[150:153], v[216:219], v[46:49]
	v_mfma_f32_16x16x32_bf16 v[42:45], v[158:161], v[216:219], v[42:45]
	v_mfma_f32_16x16x32_bf16 v[30:33], v[150:153], v[224:227], v[30:33]
	v_mfma_f32_16x16x32_bf16 v[26:29], v[158:161], v[224:227], v[26:29]
	v_mfma_f32_16x16x32_bf16 v[14:17], v[150:153], v[232:235], v[14:17]
	v_mfma_f32_16x16x32_bf16 v[10:13], v[158:161], v[232:235], v[10:13]
	s_setprio 0
	s_setprio 1
	v_mfma_f32_16x16x32_bf16 v[54:57], v[174:177], v[200:203], v[54:57]
	v_mfma_f32_16x16x32_bf16 v[50:53], v[182:185], v[200:203], v[50:53]
	v_mfma_f32_16x16x32_bf16 v[38:41], v[174:177], v[212:215], v[38:41]
	v_mfma_f32_16x16x32_bf16 v[34:37], v[182:185], v[212:215], v[34:37]
	v_mfma_f32_16x16x32_bf16 v[22:25], v[174:177], v[220:223], v[22:25]
	v_mfma_f32_16x16x32_bf16 v[18:21], v[182:185], v[220:223], v[18:21]
	v_mfma_f32_16x16x32_bf16 v[6:9], v[174:177], v[228:231], v[6:9]
	v_mfma_f32_16x16x32_bf16 v[2:5], v[182:185], v[228:231], v[2:5]
	v_mfma_f32_16x16x32_bf16 v[54:57], v[178:181], v[208:211], v[54:57]
	v_mfma_f32_16x16x32_bf16 v[50:53], v[186:189], v[208:211], v[50:53]
	v_mfma_f32_16x16x32_bf16 v[38:41], v[178:181], v[216:219], v[38:41]
	v_mfma_f32_16x16x32_bf16 v[34:37], v[186:189], v[216:219], v[34:37]
	v_mfma_f32_16x16x32_bf16 v[22:25], v[178:181], v[224:227], v[22:25]
	v_mfma_f32_16x16x32_bf16 v[18:21], v[186:189], v[224:227], v[18:21]
	v_mfma_f32_16x16x32_bf16 v[6:9], v[178:181], v[232:235], v[6:9]
	v_mfma_f32_16x16x32_bf16 v[2:5], v[186:189], v[232:235], v[2:5]
	s_barrier
	s_setprio 0
	s_add_i32 vcc_lo, vcc_lo, 2
	s_add_u32 s50, s50, 0x100
	s_addc_u32 s51, s51, 0
	s_add_u32 s73, s73, 0x100
	s_addc_u32 s76, s76, 0
	s_cmp_gt_u32 vcc_lo, 13
	s_cbranch_scc0 .LBB0_580
	s_and_b64 vcc, exec, s[36:37]
	s_cbranch_vccz .LBB0_583
	s_barrier

; #define PG8_STAGE(bufoff, gbase, voff) do { _Pragma("unroll") for (int _i = 0; _i < 2; ++_i) \
;         __builtin_amdgcn_global_load_lds((const unsigned*)((const char*)(gbase) + (voff)[_i]), (PG8_LAS unsigned*)(lds + (bufoff) + ldsw + _i * 8192), 16, 0, 0); } while (0)
; #define PG8_STAGEA(bufoff, gbase, voff) do { _Pragma("unroll") for (int _i = 0; _i < 2; ++_i) \
;         __builtin_amdgcn_global_load_lds((const unsigned*)((const char*)(gbase) + (voff)[_i]), (PG8_LAS unsigned*)(lds + (bufoff) + ldsw + _i * 8192), 16, 0, A_AUX); } while (0)
; #define PG8_LDA(dst, b, h) do { _Pragma("unroll") for (int m = 0; m < 4; ++m) _Pragma("unroll") for (int k = 0; k < 2; ++k) dst[m][k] = *(const PG8_LAS bf16x8*)(lds + PG8_SA(b, h) + aoff + m * 2048 + k * 1024); } while (0)
; #define PG8_LDB(dst, b, h) do { _Pragma("unroll") for (int n = 0; n < 2; ++n) _Pragma("unroll") for (int k = 0; k < 2; ++k) dst[n][k] = *(const PG8_LAS bf16x8*)(lds + PG8_SB(b, h) + boff + n * 2048 + k * 1024); } while (0)
; #define PG8_WAIT_V(n) asm volatile("s_waitcnt vmcnt(" #n ")" ::: "memory")
; #define PG8_WAIT_L(n) asm volatile("s_waitcnt lgkmcnt(" #n ")" ::: "memory")
; #define PG8_BAR __builtin_amdgcn_s_barrier()
;     ...
;     for (;;) {
;         const bool has_next = S.next(ui + 1, nxt);
;         const char* nA = has_next ? (const char*)g.A + (size_t)nxt.pm * tstep : cA; const char* nB = has_next ? (const char*)g.Bt + (size_t)nxt.pn * tstep : cB;
;         for (int t = 0; t < nt; t += 2) {
;             const bool last = (t == nt - 2);
;             const char* a1 = cA + (size_t)(t + 1) * kstep;
;             const char* a2 = last ? nA : cA + (size_t)(t + 2) * kstep; const char* b2 = last ? nB : cB + (size_t)(t + 2) * kstep;
;             const char* a3 = a2 + kstep; const char* b3 = b2 + kstep;
;             if (last && has_next) S.a_ready(nxt);
;             if constexpr (SP2) {
;             PG8_LDB(B0, 0, 0); PG8_LDB(B1, 0, 1); PG8_SCHED; PG8_LDA(At, 0, 0); PG8_STAGEA(PG8_SA(1, 1), a1 + hstep, voffA);
;             PG8_WAIT_V(8); PG8_WAIT_L(0); PG8_BAR; PG8_MMA(0, 0, At, B0); PG8_MMA(0, 1, At, B1); PG8_BAR; PG8_SCHED;
;             PG8_LDA(At, 0, 1); PG8_STAGE(PG8_SB(0, 0), b2, voffB); PG8_STAGE(PG8_SB(0, 1), b2 + hstep, voffB); PG8_STAGEA(PG8_SA(0, 0), a2, voffA);
;             PG8_WAIT_V(8); PG8_WAIT_L(0); PG8_BAR; PG8_MMA(1, 0, At, B0); PG8_MMA(1, 1, At, B1); PG8_BAR; PG8_SCHED;
.LBB0_655:
	s_add_u32 s16, s48, 0x100
	s_addc_u32 s17, s49, 0
	s_mov_b32 s73, -2
	s_add_u32 s48, s46, 0x100
	s_addc_u32 s49, s47, 0
	s_add_i32 s70, 0, 0x10000
	s_cmp_eq_u32 s73, 40
	s_cselect_b32 s53, s1, s49
	s_cselect_b32 s52, s0, s48
	v_add_u32_e32 v140, s70, v143
	s_cselect_b32 s51, s45, s17
	s_cselect_b32 s50, s44, s16
	s_add_i32 s71, 0, 0x14000
	ds_read_b128 v[146:149], v140
	ds_read_b128 v[150:153], v140 offset:1024
	ds_read_b128 v[154:157], v140 offset:2048
	ds_read_b128 v[158:161], v140 offset:3072
	v_add_u32_e32 v140, s71, v143
	ds_read_b128 v[174:177], v140
	ds_read_b128 v[178:181], v140 offset:1024
	ds_read_b128 v[182:185], v140 offset:2048
	ds_read_b128 v[186:189], v140 offset:3072
	v_lshl_add_u64 v[140:141], s[46:47], 0, v[136:137]
	s_add_i32 m0, s56, 0xc000
	ds_read_b128 v[200:203], v145
	ds_read_b128 v[208:211], v145 offset:1024
	ds_read_b128 v[212:215], v145 offset:2048
	ds_read_b128 v[216:219], v145 offset:3072
	ds_read_b128 v[220:223], v145 offset:4096
	ds_read_b128 v[224:227], v145 offset:5120
	ds_read_b128 v[228:231], v145 offset:6144
	ds_read_b128 v[232:235], v145 offset:7168
	global_load_lds_dwordx4 v[140:141], off
	v_lshl_add_u64 v[140:141], s[46:47], 0, v[138:139]
	s_add_i32 m0, s56, 0xe000
	s_nop 0
	global_load_lds_dwordx4 v[140:141], off
	s_waitcnt vmcnt(8)
	s_waitcnt lgkmcnt(0)
	s_setprio 1
	s_barrier
	v_mfma_f32_16x16x32_bf16 v[126:129], v[146:149], v[200:203], 0
	v_mfma_f32_16x16x32_bf16 v[122:125], v[154:157], v[200:203], 0
	v_mfma_f32_16x16x32_bf16 v[114:117], v[146:149], v[212:215], 0
	v_mfma_f32_16x16x32_bf16 v[106:109], v[154:157], v[212:215], 0
	v_mfma_f32_16x16x32_bf16 v[98:101], v[146:149], v[220:223], 0
	v_mfma_f32_16x16x32_bf16 v[90:93], v[154:157], v[220:223], 0
	v_mfma_f32_16x16x32_bf16 v[82:85], v[146:149], v[228:231], 0
	v_mfma_f32_16x16x32_bf16 v[74:77], v[154:157], v[228:231], 0
	v_mfma_f32_16x16x32_bf16 v[126:129], v[150:153], v[208:211], v[126:129]
	v_mfma_f32_16x16x32_bf16 v[122:125], v[158:161], v[208:211], v[122:125]
	v_mfma_f32_16x16x32_bf16 v[114:117], v[150:153], v[216:219], v[114:117]
	v_mfma_f32_16x16x32_bf16 v[106:109], v[158:161], v[216:219], v[106:109]
	v_mfma_f32_16x16x32_bf16 v[98:101], v[150:153], v[224:227], v[98:101]
	v_mfma_f32_16x16x32_bf16 v[90:93], v[158:161], v[224:227], v[90:93]
	v_mfma_f32_16x16x32_bf16 v[82:85], v[150:153], v[232:235], v[82:85]
	v_mfma_f32_16x16x32_bf16 v[74:77], v[158:161], v[232:235], v[74:77]
	s_setprio 0
	s_setprio 1
	v_mfma_f32_16x16x32_bf16 v[118:121], v[174:177], v[200:203], 0
	v_mfma_f32_16x16x32_bf16 v[110:113], v[182:185], v[200:203], 0
	v_mfma_f32_16x16x32_bf16 v[102:105], v[174:177], v[212:215], 0
	v_mfma_f32_16x16x32_bf16 v[94:97], v[182:185], v[212:215], 0
	v_mfma_f32_16x16x32_bf16 v[86:89], v[174:177], v[220:223], 0
	v_mfma_f32_16x16x32_bf16 v[78:81], v[182:185], v[220:223], 0
	v_mfma_f32_16x16x32_bf16 v[70:73], v[174:177], v[228:231], 0
	v_mfma_f32_16x16x32_bf16 v[66:69], v[182:185], v[228:231], 0
	v_mfma_f32_16x16x32_bf16 v[118:121], v[178:181], v[208:211], v[118:121]
	v_mfma_f32_16x16x32_bf16 v[110:113], v[186:189], v[208:211], v[110:113]
	v_mfma_f32_16x16x32_bf16 v[102:105], v[178:181], v[216:219], v[102:105]
	v_mfma_f32_16x16x32_bf16 v[94:97], v[186:189], v[216:219], v[94:97]
	v_mfma_f32_16x16x32_bf16 v[86:89], v[178:181], v[224:227], v[86:89]
	v_mfma_f32_16x16x32_bf16 v[78:81], v[186:189], v[224:227], v[78:81]
	v_mfma_f32_16x16x32_bf16 v[70:73], v[178:181], v[232:235], v[70:73]
	v_mfma_f32_16x16x32_bf16 v[66:69], v[186:189], v[232:235], v[66:69]
	s_barrier
	s_setprio 0
	s_add_i32 s46, s70, s55
	v_lshl_add_u64 v[140:141], s[50:51], 0, v[0:1]
	s_mov_b32 m0, s46
	ds_read_b128 v[200:203], v145 offset:16384
	ds_read_b128 v[208:211], v145 offset:17408
	ds_read_b128 v[212:215], v145 offset:18432
	ds_read_b128 v[216:219], v145 offset:19456
	ds_read_b128 v[220:223], v145 offset:20480
	ds_read_b128 v[224:227], v145 offset:21504
	ds_read_b128 v[228:231], v145 offset:22528
	ds_read_b128 v[232:235], v145 offset:23552
	global_load_lds_dwordx4 v[140:141], off
	s_add_i32 m0, s46, 0x2000
	s_add_u32 s46, s50, 0xb0000
	v_lshl_add_u64 v[190:191], s[50:51], 0, v[130:131]
	s_addc_u32 s47, s51, 0
	s_add_i32 s70, s71, s55
	global_load_lds_dwordx4 v[190:191], off
	v_lshl_add_u64 v[236:237], s[46:47], 0, v[0:1]
	s_mov_b32 m0, s70
	v_lshl_add_u64 v[238:239], s[52:53], 0, v[132:133]
	global_load_lds_dwordx4 v[236:237], off
	v_lshl_add_u64 v[236:237], s[46:47], 0, v[130:131]
	s_add_i32 m0, s70, 0x2000
	s_nop 0
	global_load_lds_dwordx4 v[236:237], off
	v_lshl_add_u64 v[236:237], s[52:53], 0, v[134:135]
	s_mov_b32 m0, s56
	s_nop 0
	global_load_lds_dwordx4 v[236:237], off
	s_mov_b32 m0, s57
	s_nop 0
	global_load_lds_dwordx4 v[238:239], off
	s_waitcnt vmcnt(8)
	s_waitcnt lgkmcnt(0)
	s_setprio 1
	s_barrier
; #define PG8_STAGE(bufoff, gbase, voff) do { _Pragma("unroll") for (int _i = 0; _i < 2; ++_i) \
;         __builtin_amdgcn_global_load_lds((const unsigned*)((const char*)(gbase) + (voff)[_i]), (PG8_LAS unsigned*)(lds + (bufoff) + ldsw + _i * 8192), 16, 0, 0); } while (0)
; #define PG8_STAGEA(bufoff, gbase, voff) do { _Pragma("unroll") for (int _i = 0; _i < 2; ++_i) \
;         __builtin_amdgcn_global_load_lds((const unsigned*)((const char*)(gbase) + (voff)[_i]), (PG8_LAS unsigned*)(lds + (bufoff) + ldsw + _i * 8192), 16, 0, A_AUX); } while (0)
; #define PG8_LDA(dst, b, h) do { _Pragma("unroll") for (int m = 0; m < 4; ++m) _Pragma("unroll") for (int k = 0; k < 2; ++k) dst[m][k] = *(const PG8_LAS bf16x8*)(lds + PG8_SA(b, h) + aoff + m * 2048 + k * 1024); } while (0)
; #define PG8_LDB(dst, b, h) do { _Pragma("unroll") for (int n = 0; n < 2; ++n) _Pragma("unroll") for (int k = 0; k < 2; ++k) dst[n][k] = *(const PG8_LAS bf16x8*)(lds + PG8_SB(b, h) + boff + n * 2048 + k * 1024); } while (0)
; #define PG8_MMA(ai, bj, At, Bt) do { __builtin_amdgcn_s_setprio(1); _Pragma("unroll") for (int m = 0; m < 4; ++m) _Pragma("unroll") for (int n = 0; n < 2; ++n) _Pragma("unroll") for (int k = 0; k < 2; ++k) \
;         acc[ai][bj][m][n] = __builtin_amdgcn_mfma_f32_16x16x32_bf16(Bt[n][k], At[m][k], acc[ai][bj][m][n], 0, 0, 0); __builtin_amdgcn_s_setprio(0); } while (0)
; #define PG8_WAIT_V(n) asm volatile("s_waitcnt vmcnt(" #n ")" ::: "memory")
; #define PG8_WAIT_L(n) asm volatile("s_waitcnt lgkmcnt(" #n ")" ::: "memory")
; #define PG8_BAR __builtin_amdgcn_s_barrier()
; #define PG8_SCHED __builtin_amdgcn_sched_barrier(0)
;     ...
;             PG8_LDA(At, 0, 1); PG8_STAGE(PG8_SB(0, 0), b2, voffB); PG8_STAGE(PG8_SB(0, 1), b2 + hstep, voffB); PG8_STAGEA(PG8_SA(0, 0), a2, voffA);
;             PG8_WAIT_V(8); PG8_WAIT_L(0); PG8_BAR; PG8_MMA(1, 0, At, B0); PG8_MMA(1, 1, At, B1); PG8_BAR; PG8_SCHED;
;             PG8_LDB(B0, 1, 0); PG8_LDB(B1, 1, 1); PG8_SCHED; PG8_LDA(At, 1, 0); PG8_STAGEA(PG8_SA(0, 1), a2 + hstep, voffA);
;             PG8_WAIT_V(8); PG8_WAIT_L(0); PG8_BAR; PG8_MMA(0, 0, At, B0); PG8_MMA(0, 1, At, B1); PG8_BAR; PG8_SCHED;
	v_mfma_f32_16x16x32_bf16 v[62:65], v[146:149], v[200:203], 0
	v_mfma_f32_16x16x32_bf16 v[58:61], v[154:157], v[200:203], 0
	v_mfma_f32_16x16x32_bf16 v[50:53], v[146:149], v[212:215], 0
	v_mfma_f32_16x16x32_bf16 v[42:45], v[154:157], v[212:215], 0
	v_mfma_f32_16x16x32_bf16 v[34:37], v[146:149], v[220:223], 0
	v_mfma_f32_16x16x32_bf16 v[26:29], v[154:157], v[220:223], 0
	v_mfma_f32_16x16x32_bf16 v[18:21], v[146:149], v[228:231], 0
	v_mfma_f32_16x16x32_bf16 v[10:13], v[154:157], v[228:231], 0
	v_mfma_f32_16x16x32_bf16 v[62:65], v[150:153], v[208:211], v[62:65]
	v_mfma_f32_16x16x32_bf16 v[58:61], v[158:161], v[208:211], v[58:61]
	v_mfma_f32_16x16x32_bf16 v[50:53], v[150:153], v[216:219], v[50:53]
	v_mfma_f32_16x16x32_bf16 v[42:45], v[158:161], v[216:219], v[42:45]
	v_mfma_f32_16x16x32_bf16 v[34:37], v[150:153], v[224:227], v[34:37]
	v_mfma_f32_16x16x32_bf16 v[26:29], v[158:161], v[224:227], v[26:29]
	v_mfma_f32_16x16x32_bf16 v[18:21], v[150:153], v[232:235], v[18:21]
	v_mfma_f32_16x16x32_bf16 v[10:13], v[158:161], v[232:235], v[10:13]
	s_setprio 0
	s_setprio 1
	v_mfma_f32_16x16x32_bf16 v[54:57], v[174:177], v[200:203], 0
	v_mfma_f32_16x16x32_bf16 v[46:49], v[182:185], v[200:203], 0
	v_mfma_f32_16x16x32_bf16 v[38:41], v[174:177], v[212:215], 0
	v_mfma_f32_16x16x32_bf16 v[30:33], v[182:185], v[212:215], 0
	v_mfma_f32_16x16x32_bf16 v[22:25], v[174:177], v[220:223], 0
	v_mfma_f32_16x16x32_bf16 v[14:17], v[182:185], v[220:223], 0
	v_mfma_f32_16x16x32_bf16 v[6:9], v[174:177], v[228:231], 0
	v_mfma_f32_16x16x32_bf16 v[2:5], v[182:185], v[228:231], 0
	v_mfma_f32_16x16x32_bf16 v[54:57], v[178:181], v[208:211], v[54:57]
	v_mfma_f32_16x16x32_bf16 v[46:49], v[186:189], v[208:211], v[46:49]
	v_mfma_f32_16x16x32_bf16 v[38:41], v[178:181], v[216:219], v[38:41]
	v_mfma_f32_16x16x32_bf16 v[30:33], v[186:189], v[216:219], v[30:33]
	v_mfma_f32_16x16x32_bf16 v[22:25], v[178:181], v[224:227], v[22:25]
	v_mfma_f32_16x16x32_bf16 v[14:17], v[186:189], v[224:227], v[14:17]
	v_mfma_f32_16x16x32_bf16 v[6:9], v[178:181], v[232:235], v[6:9]
	v_mfma_f32_16x16x32_bf16 v[2:5], v[186:189], v[232:235], v[2:5]
	s_barrier
	s_setprio 0
	s_add_i32 s70, 0, 0x18000
	s_add_i32 s71, 0, 0x1c000
	v_add_u32_e32 v158, s70, v143
	v_add_u32_e32 v186, s71, v143
	ds_read_b128 v[146:149], v158
	ds_read_b128 v[150:153], v158 offset:1024
	ds_read_b128 v[154:157], v158 offset:2048
	ds_read_b128 v[158:161], v158 offset:3072
	ds_read_b128 v[174:177], v186
	ds_read_b128 v[178:181], v186 offset:1024
	ds_read_b128 v[182:185], v186 offset:2048
	ds_read_b128 v[186:189], v186 offset:3072
	s_add_u32 s46, s52, 0xb0000
	s_addc_u32 s47, s53, 0
	s_mov_b32 m0, s58
	v_lshl_add_u64 v[240:241], s[46:47], 0, v[134:135]
	ds_read_b128 v[200:203], v145 offset:32768
	ds_read_b128 v[208:211], v145 offset:33792
	ds_read_b128 v[212:215], v145 offset:34816
	ds_read_b128 v[216:219], v145 offset:35840
	ds_read_b128 v[220:223], v145 offset:36864
	ds_read_b128 v[224:227], v145 offset:37888
	ds_read_b128 v[228:231], v145 offset:38912
	ds_read_b128 v[232:235], v145 offset:39936
	global_load_lds_dwordx4 v[240:241], off
	v_lshl_add_u64 v[240:241], s[46:47], 0, v[132:133]
	s_mov_b32 m0, s59
	s_nop 0
	global_load_lds_dwordx4 v[240:241], off
	s_waitcnt vmcnt(8)
	s_waitcnt lgkmcnt(0)
	s_setprio 1
	s_barrier
	v_mfma_f32_16x16x32_bf16 v[126:129], v[146:149], v[200:203], v[126:129]
	v_mfma_f32_16x16x32_bf16 v[122:125], v[154:157], v[200:203], v[122:125]
	v_mfma_f32_16x16x32_bf16 v[114:117], v[146:149], v[212:215], v[114:117]
	v_mfma_f32_16x16x32_bf16 v[106:109], v[154:157], v[212:215], v[106:109]
	v_mfma_f32_16x16x32_bf16 v[98:101], v[146:149], v[220:223], v[98:101]
	v_mfma_f32_16x16x32_bf16 v[90:93], v[154:157], v[220:223], v[90:93]
	v_mfma_f32_16x16x32_bf16 v[82:85], v[146:149], v[228:231], v[82:85]
	v_mfma_f32_16x16x32_bf16 v[74:77], v[154:157], v[228:231], v[74:77]
	v_mfma_f32_16x16x32_bf16 v[126:129], v[150:153], v[208:211], v[126:129]
	v_mfma_f32_16x16x32_bf16 v[122:125], v[158:161], v[208:211], v[122:125]
	v_mfma_f32_16x16x32_bf16 v[114:117], v[150:153], v[216:219], v[114:117]
	v_mfma_f32_16x16x32_bf16 v[106:109], v[158:161], v[216:219], v[106:109]
	v_mfma_f32_16x16x32_bf16 v[98:101], v[150:153], v[224:227], v[98:101]
	v_mfma_f32_16x16x32_bf16 v[90:93], v[158:161], v[224:227], v[90:93]
	v_mfma_f32_16x16x32_bf16 v[82:85], v[150:153], v[232:235], v[82:85]
	v_mfma_f32_16x16x32_bf16 v[74:77], v[158:161], v[232:235], v[74:77]
	s_setprio 0
	s_setprio 1
	v_mfma_f32_16x16x32_bf16 v[118:121], v[174:177], v[200:203], v[118:121]
	v_mfma_f32_16x16x32_bf16 v[110:113], v[182:185], v[200:203], v[110:113]
	v_mfma_f32_16x16x32_bf16 v[102:105], v[174:177], v[212:215], v[102:105]
	v_mfma_f32_16x16x32_bf16 v[94:97], v[182:185], v[212:215], v[94:97]
	v_mfma_f32_16x16x32_bf16 v[86:89], v[174:177], v[220:223], v[86:89]
	v_mfma_f32_16x16x32_bf16 v[78:81], v[182:185], v[220:223], v[78:81]
	v_mfma_f32_16x16x32_bf16 v[70:73], v[174:177], v[228:231], v[70:73]
	v_mfma_f32_16x16x32_bf16 v[66:69], v[182:185], v[228:231], v[66:69]
	v_mfma_f32_16x16x32_bf16 v[118:121], v[178:181], v[208:211], v[118:121]
	v_mfma_f32_16x16x32_bf16 v[110:113], v[186:189], v[208:211], v[110:113]
	v_mfma_f32_16x16x32_bf16 v[102:105], v[178:181], v[216:219], v[102:105]
	v_mfma_f32_16x16x32_bf16 v[94:97], v[186:189], v[216:219], v[94:97]
	v_mfma_f32_16x16x32_bf16 v[86:89], v[178:181], v[224:227], v[86:89]
	v_mfma_f32_16x16x32_bf16 v[78:81], v[186:189], v[224:227], v[78:81]
	v_mfma_f32_16x16x32_bf16 v[70:73], v[178:181], v[232:235], v[70:73]
	v_mfma_f32_16x16x32_bf16 v[66:69], v[186:189], v[232:235], v[66:69]
	s_barrier
; #define PG8_STAGE(bufoff, gbase, voff) do { _Pragma("unroll") for (int _i = 0; _i < 2; ++_i) \
;         __builtin_amdgcn_global_load_lds((const unsigned*)((const char*)(gbase) + (voff)[_i]), (PG8_LAS unsigned*)(lds + (bufoff) + ldsw + _i * 8192), 16, 0, 0); } while (0)
; #define PG8_STAGEA(bufoff, gbase, voff) do { _Pragma("unroll") for (int _i = 0; _i < 2; ++_i) \
;         __builtin_amdgcn_global_load_lds((const unsigned*)((const char*)(gbase) + (voff)[_i]), (PG8_LAS unsigned*)(lds + (bufoff) + ldsw + _i * 8192), 16, 0, A_AUX); } while (0)
; #define PG8_LDA(dst, b, h) do { _Pragma("unroll") for (int m = 0; m < 4; ++m) _Pragma("unroll") for (int k = 0; k < 2; ++k) dst[m][k] = *(const PG8_LAS bf16x8*)(lds + PG8_SA(b, h) + aoff + m * 2048 + k * 1024); } while (0)
; #define PG8_LDB(dst, b, h) do { _Pragma("unroll") for (int n = 0; n < 2; ++n) _Pragma("unroll") for (int k = 0; k < 2; ++k) dst[n][k] = *(const PG8_LAS bf16x8*)(lds + PG8_SB(b, h) + boff + n * 2048 + k * 1024); } while (0)
; #define PG8_WAIT_V(n) asm volatile("s_waitcnt vmcnt(" #n ")" ::: "memory")
; #define PG8_WAIT_L(n) asm volatile("s_waitcnt lgkmcnt(" #n ")" ::: "memory")
; #define PG8_BAR __builtin_amdgcn_s_barrier()
;     ...
;     for (;;) {
;         const bool has_next = S.next(ui + 1, nxt);
;         const char* nA = has_next ? (const char*)g.A + (size_t)nxt.pm * tstep : cA; const char* nB = has_next ? (const char*)g.Bt + (size_t)nxt.pn * tstep : cB;
;         for (int t = 0; t < nt; t += 2) {
;             const bool last = (t == nt - 2);
;             const char* a1 = cA + (size_t)(t + 1) * kstep;
;             const char* a2 = last ? nA : cA + (size_t)(t + 2) * kstep; const char* b2 = last ? nB : cB + (size_t)(t + 2) * kstep;
;             const char* a3 = a2 + kstep; const char* b3 = b2 + kstep;
;             if (last && has_next) S.a_ready(nxt);
;             if constexpr (SP2) {
;             PG8_LDB(B0, 0, 0); PG8_LDB(B1, 0, 1); PG8_SCHED; PG8_LDA(At, 0, 0); PG8_STAGEA(PG8_SA(1, 1), a1 + hstep, voffA);
;             PG8_WAIT_V(8); PG8_WAIT_L(0); PG8_BAR; PG8_MMA(0, 0, At, B0); PG8_MMA(0, 1, At, B1); PG8_BAR; PG8_SCHED;
;     ...
;             PG8_LDA(At, 1, 1); PG8_STAGE(PG8_SB(1, 0), b3, voffB); PG8_STAGE(PG8_SB(1, 1), b3 + hstep, voffB); PG8_STAGEA(PG8_SA(1, 0), a3, voffA);
;             PG8_WAIT_V(8); PG8_WAIT_L(0); PG8_BAR; PG8_MMA(1, 0, At, B0); PG8_MMA(1, 1, At, B1); PG8_BAR; PG8_SCHED;
	s_setprio 0
	s_add_i32 s46, s70, s55
	v_lshl_add_u64 v[140:141], v[140:141], 0, s[8:9]
	s_mov_b32 m0, s46
	ds_read_b128 v[200:203], v145 offset:49152
	ds_read_b128 v[208:211], v145 offset:50176
	ds_read_b128 v[212:215], v145 offset:51200
	ds_read_b128 v[216:219], v145 offset:52224
	ds_read_b128 v[220:223], v145 offset:53248
	ds_read_b128 v[224:227], v145 offset:54272
	ds_read_b128 v[228:231], v145 offset:55296
	ds_read_b128 v[232:235], v145 offset:56320
	global_load_lds_dwordx4 v[140:141], off
	s_add_i32 m0, s46, 0x2000
	s_add_u32 s46, s50, 0xb0080
	v_lshl_add_u64 v[140:141], v[190:191], 0, s[8:9]
	s_addc_u32 s47, s51, 0
	s_add_i32 s50, s71, s55
	global_load_lds_dwordx4 v[140:141], off
	v_lshl_add_u64 v[140:141], s[46:47], 0, v[0:1]
	s_mov_b32 m0, s50
	s_nop 0
	global_load_lds_dwordx4 v[140:141], off
	v_lshl_add_u64 v[140:141], s[46:47], 0, v[130:131]
	s_add_i32 m0, s50, 0x2000
	s_nop 0
	global_load_lds_dwordx4 v[140:141], off
	v_lshl_add_u64 v[140:141], v[236:237], 0, s[8:9]
	s_mov_b32 m0, s60
	s_nop 0
	global_load_lds_dwordx4 v[140:141], off
	v_lshl_add_u64 v[140:141], v[238:239], 0, s[8:9]
	s_mov_b32 m0, s61
	s_nop 0
	global_load_lds_dwordx4 v[140:141], off
	s_waitcnt vmcnt(8)
	s_waitcnt lgkmcnt(0)
	s_setprio 1
	s_barrier
	v_mfma_f32_16x16x32_bf16 v[62:65], v[146:149], v[200:203], v[62:65]
	v_mfma_f32_16x16x32_bf16 v[58:61], v[154:157], v[200:203], v[58:61]
	v_mfma_f32_16x16x32_bf16 v[50:53], v[146:149], v[212:215], v[50:53]
	v_mfma_f32_16x16x32_bf16 v[42:45], v[154:157], v[212:215], v[42:45]
	v_mfma_f32_16x16x32_bf16 v[34:37], v[146:149], v[220:223], v[34:37]
	v_mfma_f32_16x16x32_bf16 v[26:29], v[154:157], v[220:223], v[26:29]
	v_mfma_f32_16x16x32_bf16 v[18:21], v[146:149], v[228:231], v[18:21]
	v_mfma_f32_16x16x32_bf16 v[10:13], v[154:157], v[228:231], v[10:13]
	v_mfma_f32_16x16x32_bf16 v[62:65], v[150:153], v[208:211], v[62:65]
	v_mfma_f32_16x16x32_bf16 v[58:61], v[158:161], v[208:211], v[58:61]
	v_mfma_f32_16x16x32_bf16 v[50:53], v[150:153], v[216:219], v[50:53]
	v_mfma_f32_16x16x32_bf16 v[42:45], v[158:161], v[216:219], v[42:45]
	v_mfma_f32_16x16x32_bf16 v[34:37], v[150:153], v[224:227], v[34:37]
	v_mfma_f32_16x16x32_bf16 v[26:29], v[158:161], v[224:227], v[26:29]
	v_mfma_f32_16x16x32_bf16 v[18:21], v[150:153], v[232:235], v[18:21]
	v_mfma_f32_16x16x32_bf16 v[10:13], v[158:161], v[232:235], v[10:13]
	s_setprio 0
	s_setprio 1
	v_mfma_f32_16x16x32_bf16 v[54:57], v[174:177], v[200:203], v[54:57]
	v_mfma_f32_16x16x32_bf16 v[46:49], v[182:185], v[200:203], v[46:49]
	v_mfma_f32_16x16x32_bf16 v[38:41], v[174:177], v[212:215], v[38:41]
	v_mfma_f32_16x16x32_bf16 v[30:33], v[182:185], v[212:215], v[30:33]
	v_mfma_f32_16x16x32_bf16 v[22:25], v[174:177], v[220:223], v[22:25]
	v_mfma_f32_16x16x32_bf16 v[14:17], v[182:185], v[220:223], v[14:17]
	v_mfma_f32_16x16x32_bf16 v[6:9], v[174:177], v[228:231], v[6:9]
	v_mfma_f32_16x16x32_bf16 v[2:5], v[182:185], v[228:231], v[2:5]
	v_mfma_f32_16x16x32_bf16 v[54:57], v[178:181], v[208:211], v[54:57]
	v_mfma_f32_16x16x32_bf16 v[46:49], v[186:189], v[208:211], v[46:49]
	v_mfma_f32_16x16x32_bf16 v[38:41], v[178:181], v[216:219], v[38:41]
	v_mfma_f32_16x16x32_bf16 v[30:33], v[186:189], v[216:219], v[30:33]
	v_mfma_f32_16x16x32_bf16 v[22:25], v[178:181], v[224:227], v[22:25]
	v_mfma_f32_16x16x32_bf16 v[14:17], v[186:189], v[224:227], v[14:17]
	v_mfma_f32_16x16x32_bf16 v[6:9], v[178:181], v[232:235], v[6:9]
	v_mfma_f32_16x16x32_bf16 v[2:5], v[186:189], v[232:235], v[2:5]
	s_barrier
	s_setprio 0
	s_add_i32 s73, s73, 2
	s_add_u32 s16, s16, 0x100
	s_addc_u32 s17, s17, 0
	s_cmp_gt_u32 s73, 41
	s_mov_b64 s[46:47], s[48:49]
.LBB0_656:
	s_add_u32 s48, s46, 0x100
	s_addc_u32 s49, s47, 0
	s_add_i32 s70, 0, 0x10000
	s_cmp_eq_u32 s73, 40
	s_cselect_b32 s53, s1, s49
	s_cselect_b32 s52, s0, s48
	v_add_u32_e32 v140, s70, v143
	s_cselect_b32 s51, s45, s17
	s_cselect_b32 s50, s44, s16
	s_add_i32 s71, 0, 0x14000
	ds_read_b128 v[146:149], v140
	ds_read_b128 v[150:153], v140 offset:1024
	ds_read_b128 v[154:157], v140 offset:2048
	ds_read_b128 v[158:161], v140 offset:3072
	v_add_u32_e32 v140, s71, v143
	ds_read_b128 v[174:177], v140
	ds_read_b128 v[178:181], v140 offset:1024
	ds_read_b128 v[182:185], v140 offset:2048
	ds_read_b128 v[186:189], v140 offset:3072
	v_lshl_add_u64 v[140:141], s[46:47], 0, v[136:137]
	s_add_i32 m0, s56, 0xc000
	ds_read_b128 v[200:203], v145
	ds_read_b128 v[208:211], v145 offset:1024
	ds_read_b128 v[212:215], v145 offset:2048
	ds_read_b128 v[216:219], v145 offset:3072
	ds_read_b128 v[220:223], v145 offset:4096
	ds_read_b128 v[224:227], v145 offset:5120
	ds_read_b128 v[228:231], v145 offset:6144
	ds_read_b128 v[232:235], v145 offset:7168
	global_load_lds_dwordx4 v[140:141], off
	v_lshl_add_u64 v[140:141], s[46:47], 0, v[138:139]
	s_add_i32 m0, s56, 0xe000
	s_nop 0
	global_load_lds_dwordx4 v[140:141], off
	s_waitcnt vmcnt(8)
	s_waitcnt lgkmcnt(0)
	s_setprio 1
	s_barrier
; #define PG8_STAGE(bufoff, gbase, voff) do { _Pragma("unroll") for (int _i = 0; _i < 2; ++_i) \
;         __builtin_amdgcn_global_load_lds((const unsigned*)((const char*)(gbase) + (voff)[_i]), (PG8_LAS unsigned*)(lds + (bufoff) + ldsw + _i * 8192), 16, 0, 0); } while (0)
; #define PG8_STAGEA(bufoff, gbase, voff) do { _Pragma("unroll") for (int _i = 0; _i < 2; ++_i) \
;         __builtin_amdgcn_global_load_lds((const unsigned*)((const char*)(gbase) + (voff)[_i]), (PG8_LAS unsigned*)(lds + (bufoff) + ldsw + _i * 8192), 16, 0, A_AUX); } while (0)
; #define PG8_LDA(dst, b, h) do { _Pragma("unroll") for (int m = 0; m < 4; ++m) _Pragma("unroll") for (int k = 0; k < 2; ++k) dst[m][k] = *(const PG8_LAS bf16x8*)(lds + PG8_SA(b, h) + aoff + m * 2048 + k * 1024); } while (0)
; #define PG8_LDB(dst, b, h) do { _Pragma("unroll") for (int n = 0; n < 2; ++n) _Pragma("unroll") for (int k = 0; k < 2; ++k) dst[n][k] = *(const PG8_LAS bf16x8*)(lds + PG8_SB(b, h) + boff + n * 2048 + k * 1024); } while (0)
; #define PG8_MMA(ai, bj, At, Bt) do { __builtin_amdgcn_s_setprio(1); _Pragma("unroll") for (int m = 0; m < 4; ++m) _Pragma("unroll") for (int n = 0; n < 2; ++n) _Pragma("unroll") for (int k = 0; k < 2; ++k) \
;         acc[ai][bj][m][n] = __builtin_amdgcn_mfma_f32_16x16x32_bf16(Bt[n][k], At[m][k], acc[ai][bj][m][n], 0, 0, 0); __builtin_amdgcn_s_setprio(0); } while (0)
; #define PG8_WAIT_V(n) asm volatile("s_waitcnt vmcnt(" #n ")" ::: "memory")
; #define PG8_WAIT_L(n) asm volatile("s_waitcnt lgkmcnt(" #n ")" ::: "memory")
; #define PG8_BAR __builtin_amdgcn_s_barrier()
; #define PG8_SCHED __builtin_amdgcn_sched_barrier(0)
;     ...
;             PG8_LDB(B0, 0, 0); PG8_LDB(B1, 0, 1); PG8_SCHED; PG8_LDA(At, 0, 0); PG8_STAGEA(PG8_SA(1, 1), a1 + hstep, voffA);
;             PG8_WAIT_V(8); PG8_WAIT_L(0); PG8_BAR; PG8_MMA(0, 0, At, B0); PG8_MMA(0, 1, At, B1); PG8_BAR; PG8_SCHED;
;             PG8_LDA(At, 0, 1); PG8_STAGE(PG8_SB(0, 0), b2, voffB); PG8_STAGE(PG8_SB(0, 1), b2 + hstep, voffB); PG8_STAGEA(PG8_SA(0, 0), a2, voffA);
;             PG8_WAIT_V(8); PG8_WAIT_L(0); PG8_BAR; PG8_MMA(1, 0, At, B0); PG8_MMA(1, 1, At, B1); PG8_BAR; PG8_SCHED;
	v_mfma_f32_16x16x32_bf16 v[126:129], v[146:149], v[200:203], v[126:129]
	v_mfma_f32_16x16x32_bf16 v[122:125], v[154:157], v[200:203], v[122:125]
	v_mfma_f32_16x16x32_bf16 v[114:117], v[146:149], v[212:215], v[114:117]
	v_mfma_f32_16x16x32_bf16 v[106:109], v[154:157], v[212:215], v[106:109]
	v_mfma_f32_16x16x32_bf16 v[98:101], v[146:149], v[220:223], v[98:101]
	v_mfma_f32_16x16x32_bf16 v[90:93], v[154:157], v[220:223], v[90:93]
	v_mfma_f32_16x16x32_bf16 v[82:85], v[146:149], v[228:231], v[82:85]
	v_mfma_f32_16x16x32_bf16 v[74:77], v[154:157], v[228:231], v[74:77]
	v_mfma_f32_16x16x32_bf16 v[126:129], v[150:153], v[208:211], v[126:129]
	v_mfma_f32_16x16x32_bf16 v[122:125], v[158:161], v[208:211], v[122:125]
	v_mfma_f32_16x16x32_bf16 v[114:117], v[150:153], v[216:219], v[114:117]
	v_mfma_f32_16x16x32_bf16 v[106:109], v[158:161], v[216:219], v[106:109]
	v_mfma_f32_16x16x32_bf16 v[98:101], v[150:153], v[224:227], v[98:101]
	v_mfma_f32_16x16x32_bf16 v[90:93], v[158:161], v[224:227], v[90:93]
	v_mfma_f32_16x16x32_bf16 v[82:85], v[150:153], v[232:235], v[82:85]
	v_mfma_f32_16x16x32_bf16 v[74:77], v[158:161], v[232:235], v[74:77]
	s_setprio 0
	s_setprio 1
	v_mfma_f32_16x16x32_bf16 v[118:121], v[174:177], v[200:203], v[118:121]
	v_mfma_f32_16x16x32_bf16 v[110:113], v[182:185], v[200:203], v[110:113]
	v_mfma_f32_16x16x32_bf16 v[102:105], v[174:177], v[212:215], v[102:105]
	v_mfma_f32_16x16x32_bf16 v[94:97], v[182:185], v[212:215], v[94:97]
	v_mfma_f32_16x16x32_bf16 v[86:89], v[174:177], v[220:223], v[86:89]
	v_mfma_f32_16x16x32_bf16 v[78:81], v[182:185], v[220:223], v[78:81]
	v_mfma_f32_16x16x32_bf16 v[70:73], v[174:177], v[228:231], v[70:73]
	v_mfma_f32_16x16x32_bf16 v[66:69], v[182:185], v[228:231], v[66:69]
	v_mfma_f32_16x16x32_bf16 v[118:121], v[178:181], v[208:211], v[118:121]
	v_mfma_f32_16x16x32_bf16 v[110:113], v[186:189], v[208:211], v[110:113]
	v_mfma_f32_16x16x32_bf16 v[102:105], v[178:181], v[216:219], v[102:105]
	v_mfma_f32_16x16x32_bf16 v[94:97], v[186:189], v[216:219], v[94:97]
	v_mfma_f32_16x16x32_bf16 v[86:89], v[178:181], v[224:227], v[86:89]
	v_mfma_f32_16x16x32_bf16 v[78:81], v[186:189], v[224:227], v[78:81]
	v_mfma_f32_16x16x32_bf16 v[70:73], v[178:181], v[232:235], v[70:73]
	v_mfma_f32_16x16x32_bf16 v[66:69], v[186:189], v[232:235], v[66:69]
	s_barrier
	s_setprio 0
	s_add_i32 s46, s70, s55
	v_lshl_add_u64 v[140:141], s[50:51], 0, v[0:1]
	s_mov_b32 m0, s46
	ds_read_b128 v[200:203], v145 offset:16384
	ds_read_b128 v[208:211], v145 offset:17408
	ds_read_b128 v[212:215], v145 offset:18432
	ds_read_b128 v[216:219], v145 offset:19456
	ds_read_b128 v[220:223], v145 offset:20480
	ds_read_b128 v[224:227], v145 offset:21504
	ds_read_b128 v[228:231], v145 offset:22528
	ds_read_b128 v[232:235], v145 offset:23552
	global_load_lds_dwordx4 v[140:141], off
	s_add_i32 m0, s46, 0x2000
	s_add_u32 s46, s50, 0xb0000
	v_lshl_add_u64 v[190:191], s[50:51], 0, v[130:131]
	s_addc_u32 s47, s51, 0
	s_add_i32 s70, s71, s55
	global_load_lds_dwordx4 v[190:191], off
	v_lshl_add_u64 v[236:237], s[46:47], 0, v[0:1]
	s_mov_b32 m0, s70
	v_lshl_add_u64 v[238:239], s[52:53], 0, v[132:133]
	global_load_lds_dwordx4 v[236:237], off
	v_lshl_add_u64 v[236:237], s[46:47], 0, v[130:131]
	s_add_i32 m0, s70, 0x2000
	s_nop 0
	global_load_lds_dwordx4 v[236:237], off
	v_lshl_add_u64 v[236:237], s[52:53], 0, v[134:135]
	s_mov_b32 m0, s56
	s_nop 0
	global_load_lds_dwordx4 v[236:237], off
	s_mov_b32 m0, s57
	s_nop 0
	global_load_lds_dwordx4 v[238:239], off
	s_waitcnt vmcnt(8)
	s_waitcnt lgkmcnt(0)
	s_setprio 1
	s_barrier
	v_mfma_f32_16x16x32_bf16 v[62:65], v[146:149], v[200:203], v[62:65]
	v_mfma_f32_16x16x32_bf16 v[58:61], v[154:157], v[200:203], v[58:61]
	v_mfma_f32_16x16x32_bf16 v[50:53], v[146:149], v[212:215], v[50:53]
	v_mfma_f32_16x16x32_bf16 v[42:45], v[154:157], v[212:215], v[42:45]
	v_mfma_f32_16x16x32_bf16 v[34:37], v[146:149], v[220:223], v[34:37]
	v_mfma_f32_16x16x32_bf16 v[26:29], v[154:157], v[220:223], v[26:29]
	v_mfma_f32_16x16x32_bf16 v[18:21], v[146:149], v[228:231], v[18:21]
	v_mfma_f32_16x16x32_bf16 v[10:13], v[154:157], v[228:231], v[10:13]
	v_mfma_f32_16x16x32_bf16 v[62:65], v[150:153], v[208:211], v[62:65]
	v_mfma_f32_16x16x32_bf16 v[58:61], v[158:161], v[208:211], v[58:61]
	v_mfma_f32_16x16x32_bf16 v[50:53], v[150:153], v[216:219], v[50:53]
	v_mfma_f32_16x16x32_bf16 v[42:45], v[158:161], v[216:219], v[42:45]
	v_mfma_f32_16x16x32_bf16 v[34:37], v[150:153], v[224:227], v[34:37]
	v_mfma_f32_16x16x32_bf16 v[26:29], v[158:161], v[224:227], v[26:29]
	v_mfma_f32_16x16x32_bf16 v[18:21], v[150:153], v[232:235], v[18:21]
	v_mfma_f32_16x16x32_bf16 v[10:13], v[158:161], v[232:235], v[10:13]
	s_setprio 0
	s_setprio 1
	v_mfma_f32_16x16x32_bf16 v[54:57], v[174:177], v[200:203], v[54:57]
	v_mfma_f32_16x16x32_bf16 v[46:49], v[182:185], v[200:203], v[46:49]
	v_mfma_f32_16x16x32_bf16 v[38:41], v[174:177], v[212:215], v[38:41]
	v_mfma_f32_16x16x32_bf16 v[30:33], v[182:185], v[212:215], v[30:33]
	v_mfma_f32_16x16x32_bf16 v[22:25], v[174:177], v[220:223], v[22:25]
	v_mfma_f32_16x16x32_bf16 v[14:17], v[182:185], v[220:223], v[14:17]
	v_mfma_f32_16x16x32_bf16 v[6:9], v[174:177], v[228:231], v[6:9]
	v_mfma_f32_16x16x32_bf16 v[2:5], v[182:185], v[228:231], v[2:5]
	v_mfma_f32_16x16x32_bf16 v[54:57], v[178:181], v[208:211], v[54:57]
	v_mfma_f32_16x16x32_bf16 v[46:49], v[186:189], v[208:211], v[46:49]
	v_mfma_f32_16x16x32_bf16 v[38:41], v[178:181], v[216:219], v[38:41]
	v_mfma_f32_16x16x32_bf16 v[30:33], v[186:189], v[216:219], v[30:33]
	v_mfma_f32_16x16x32_bf16 v[22:25], v[178:181], v[224:227], v[22:25]
	v_mfma_f32_16x16x32_bf16 v[14:17], v[186:189], v[224:227], v[14:17]
	v_mfma_f32_16x16x32_bf16 v[6:9], v[178:181], v[232:235], v[6:9]
	v_mfma_f32_16x16x32_bf16 v[2:5], v[186:189], v[232:235], v[2:5]
	s_barrier
; #define PG8_STAGEA(bufoff, gbase, voff) do { _Pragma("unroll") for (int _i = 0; _i < 2; ++_i) \
;         __builtin_amdgcn_global_load_lds((const unsigned*)((const char*)(gbase) + (voff)[_i]), (PG8_LAS unsigned*)(lds + (bufoff) + ldsw + _i * 8192), 16, 0, A_AUX); } while (0)
; #define PG8_LDA(dst, b, h) do { _Pragma("unroll") for (int m = 0; m < 4; ++m) _Pragma("unroll") for (int k = 0; k < 2; ++k) dst[m][k] = *(const PG8_LAS bf16x8*)(lds + PG8_SA(b, h) + aoff + m * 2048 + k * 1024); } while (0)
; #define PG8_LDB(dst, b, h) do { _Pragma("unroll") for (int n = 0; n < 2; ++n) _Pragma("unroll") for (int k = 0; k < 2; ++k) dst[n][k] = *(const PG8_LAS bf16x8*)(lds + PG8_SB(b, h) + boff + n * 2048 + k * 1024); } while (0)
; #define PG8_MMA(ai, bj, At, Bt) do { __builtin_amdgcn_s_setprio(1); _Pragma("unroll") for (int m = 0; m < 4; ++m) _Pragma("unroll") for (int n = 0; n < 2; ++n) _Pragma("unroll") for (int k = 0; k < 2; ++k) \
;         acc[ai][bj][m][n] = __builtin_amdgcn_mfma_f32_16x16x32_bf16(Bt[n][k], At[m][k], acc[ai][bj][m][n], 0, 0, 0); __builtin_amdgcn_s_setprio(0); } while (0)
; #define PG8_WAIT_V(n) asm volatile("s_waitcnt vmcnt(" #n ")" ::: "memory")
; #define PG8_WAIT_L(n) asm volatile("s_waitcnt lgkmcnt(" #n ")" ::: "memory")
; #define PG8_BAR __builtin_amdgcn_s_barrier()
; #define PG8_SCHED __builtin_amdgcn_sched_barrier(0)
;     ...
;             PG8_LDB(B0, 1, 0); PG8_LDB(B1, 1, 1); PG8_SCHED; PG8_LDA(At, 1, 0); PG8_STAGEA(PG8_SA(0, 1), a2 + hstep, voffA);
;             PG8_WAIT_V(8); PG8_WAIT_L(0); PG8_BAR; PG8_MMA(0, 0, At, B0); PG8_MMA(0, 1, At, B1); PG8_BAR; PG8_SCHED;
	s_setprio 0
	s_add_i32 s70, 0, 0x18000
	s_add_i32 s71, 0, 0x1c000
	v_add_u32_e32 v158, s70, v143
	v_add_u32_e32 v186, s71, v143
	ds_read_b128 v[146:149], v158
	ds_read_b128 v[150:153], v158 offset:1024
	ds_read_b128 v[154:157], v158 offset:2048
	ds_read_b128 v[158:161], v158 offset:3072
	ds_read_b128 v[174:177], v186
	ds_read_b128 v[178:181], v186 offset:1024
	ds_read_b128 v[182:185], v186 offset:2048
	ds_read_b128 v[186:189], v186 offset:3072
	s_add_u32 s46, s52, 0xb0000
	s_addc_u32 s47, s53, 0
	s_mov_b32 m0, s58
	v_lshl_add_u64 v[240:241], s[46:47], 0, v[134:135]
	ds_read_b128 v[200:203], v145 offset:32768
	ds_read_b128 v[208:211], v145 offset:33792
	ds_read_b128 v[212:215], v145 offset:34816
	ds_read_b128 v[216:219], v145 offset:35840
	ds_read_b128 v[220:223], v145 offset:36864
	ds_read_b128 v[224:227], v145 offset:37888
	ds_read_b128 v[228:231], v145 offset:38912
	ds_read_b128 v[232:235], v145 offset:39936
	global_load_lds_dwordx4 v[240:241], off
	v_lshl_add_u64 v[240:241], s[46:47], 0, v[132:133]
	s_mov_b32 m0, s59
	s_nop 0
	global_load_lds_dwordx4 v[240:241], off
	s_waitcnt vmcnt(8)
	s_waitcnt lgkmcnt(0)
	s_setprio 1
	s_barrier
	v_mfma_f32_16x16x32_bf16 v[126:129], v[146:149], v[200:203], v[126:129]
	v_mfma_f32_16x16x32_bf16 v[122:125], v[154:157], v[200:203], v[122:125]
	v_mfma_f32_16x16x32_bf16 v[114:117], v[146:149], v[212:215], v[114:117]
	v_mfma_f32_16x16x32_bf16 v[106:109], v[154:157], v[212:215], v[106:109]
	v_mfma_f32_16x16x32_bf16 v[98:101], v[146:149], v[220:223], v[98:101]
	v_mfma_f32_16x16x32_bf16 v[90:93], v[154:157], v[220:223], v[90:93]
	v_mfma_f32_16x16x32_bf16 v[82:85], v[146:149], v[228:231], v[82:85]
	v_mfma_f32_16x16x32_bf16 v[74:77], v[154:157], v[228:231], v[74:77]
	v_mfma_f32_16x16x32_bf16 v[126:129], v[150:153], v[208:211], v[126:129]
	v_mfma_f32_16x16x32_bf16 v[122:125], v[158:161], v[208:211], v[122:125]
	v_mfma_f32_16x16x32_bf16 v[114:117], v[150:153], v[216:219], v[114:117]
	v_mfma_f32_16x16x32_bf16 v[106:109], v[158:161], v[216:219], v[106:109]
	v_mfma_f32_16x16x32_bf16 v[98:101], v[150:153], v[224:227], v[98:101]
	v_mfma_f32_16x16x32_bf16 v[90:93], v[158:161], v[224:227], v[90:93]
	v_mfma_f32_16x16x32_bf16 v[82:85], v[150:153], v[232:235], v[82:85]
	v_mfma_f32_16x16x32_bf16 v[74:77], v[158:161], v[232:235], v[74:77]
	s_setprio 0
	s_setprio 1
	v_mfma_f32_16x16x32_bf16 v[118:121], v[174:177], v[200:203], v[118:121]
	v_mfma_f32_16x16x32_bf16 v[110:113], v[182:185], v[200:203], v[110:113]
	v_mfma_f32_16x16x32_bf16 v[102:105], v[174:177], v[212:215], v[102:105]
	v_mfma_f32_16x16x32_bf16 v[94:97], v[182:185], v[212:215], v[94:97]
	v_mfma_f32_16x16x32_bf16 v[86:89], v[174:177], v[220:223], v[86:89]
	v_mfma_f32_16x16x32_bf16 v[78:81], v[182:185], v[220:223], v[78:81]
	v_mfma_f32_16x16x32_bf16 v[70:73], v[174:177], v[228:231], v[70:73]
	v_mfma_f32_16x16x32_bf16 v[66:69], v[182:185], v[228:231], v[66:69]
	v_mfma_f32_16x16x32_bf16 v[118:121], v[178:181], v[208:211], v[118:121]
	v_mfma_f32_16x16x32_bf16 v[110:113], v[186:189], v[208:211], v[110:113]
	v_mfma_f32_16x16x32_bf16 v[102:105], v[178:181], v[216:219], v[102:105]
	v_mfma_f32_16x16x32_bf16 v[94:97], v[186:189], v[216:219], v[94:97]
	v_mfma_f32_16x16x32_bf16 v[86:89], v[178:181], v[224:227], v[86:89]
	v_mfma_f32_16x16x32_bf16 v[78:81], v[186:189], v[224:227], v[78:81]
	v_mfma_f32_16x16x32_bf16 v[70:73], v[178:181], v[232:235], v[70:73]
	v_mfma_f32_16x16x32_bf16 v[66:69], v[186:189], v[232:235], v[66:69]
	s_barrier
; #define PG8_STAGE(bufoff, gbase, voff) do { _Pragma("unroll") for (int _i = 0; _i < 2; ++_i) \
;         __builtin_amdgcn_global_load_lds((const unsigned*)((const char*)(gbase) + (voff)[_i]), (PG8_LAS unsigned*)(lds + (bufoff) + ldsw + _i * 8192), 16, 0, 0); } while (0)
; #define PG8_STAGEA(bufoff, gbase, voff) do { _Pragma("unroll") for (int _i = 0; _i < 2; ++_i) \
;         __builtin_amdgcn_global_load_lds((const unsigned*)((const char*)(gbase) + (voff)[_i]), (PG8_LAS unsigned*)(lds + (bufoff) + ldsw + _i * 8192), 16, 0, A_AUX); } while (0)
; #define PG8_LDA(dst, b, h) do { _Pragma("unroll") for (int m = 0; m < 4; ++m) _Pragma("unroll") for (int k = 0; k < 2; ++k) dst[m][k] = *(const PG8_LAS bf16x8*)(lds + PG8_SA(b, h) + aoff + m * 2048 + k * 1024); } while (0)
; #define PG8_MMA(ai, bj, At, Bt) do { __builtin_amdgcn_s_setprio(1); _Pragma("unroll") for (int m = 0; m < 4; ++m) _Pragma("unroll") for (int n = 0; n < 2; ++n) _Pragma("unroll") for (int k = 0; k < 2; ++k) \
;         acc[ai][bj][m][n] = __builtin_amdgcn_mfma_f32_16x16x32_bf16(Bt[n][k], At[m][k], acc[ai][bj][m][n], 0, 0, 0); __builtin_amdgcn_s_setprio(0); } while (0)
; #define PG8_WAIT_V(n) asm volatile("s_waitcnt vmcnt(" #n ")" ::: "memory")
; #define PG8_WAIT_L(n) asm volatile("s_waitcnt lgkmcnt(" #n ")" ::: "memory")
; #define PG8_BAR __builtin_amdgcn_s_barrier()
; #define PG8_SCHED __builtin_amdgcn_sched_barrier(0)
;     ...
;         for (int t = 0; t < nt; t += 2) {
;             const bool last = (t == nt - 2);
;             const char* a1 = cA + (size_t)(t + 1) * kstep;
;             const char* a2 = last ? nA : cA + (size_t)(t + 2) * kstep; const char* b2 = last ? nB : cB + (size_t)(t + 2) * kstep;
;             const char* a3 = a2 + kstep; const char* b3 = b2 + kstep;
;             if (last && has_next) S.a_ready(nxt);
;     ...
;             PG8_LDA(At, 1, 1); PG8_STAGE(PG8_SB(1, 0), b3, voffB); PG8_STAGE(PG8_SB(1, 1), b3 + hstep, voffB); PG8_STAGEA(PG8_SA(1, 0), a3, voffA);
;             PG8_WAIT_V(8); PG8_WAIT_L(0); PG8_BAR; PG8_MMA(1, 0, At, B0); PG8_MMA(1, 1, At, B1); PG8_BAR; PG8_SCHED;
	s_setprio 0
	s_add_i32 s46, s70, s55
	v_lshl_add_u64 v[140:141], v[140:141], 0, s[8:9]
	s_mov_b32 m0, s46
	ds_read_b128 v[200:203], v145 offset:49152
	ds_read_b128 v[208:211], v145 offset:50176
	ds_read_b128 v[212:215], v145 offset:51200
	ds_read_b128 v[216:219], v145 offset:52224
	ds_read_b128 v[220:223], v145 offset:53248
	ds_read_b128 v[224:227], v145 offset:54272
	ds_read_b128 v[228:231], v145 offset:55296
	ds_read_b128 v[232:235], v145 offset:56320
	global_load_lds_dwordx4 v[140:141], off
	s_add_i32 m0, s46, 0x2000
	s_add_u32 s46, s50, 0xb0080
	v_lshl_add_u64 v[140:141], v[190:191], 0, s[8:9]
	s_addc_u32 s47, s51, 0
	s_add_i32 s50, s71, s55
	global_load_lds_dwordx4 v[140:141], off
	v_lshl_add_u64 v[140:141], s[46:47], 0, v[0:1]
	s_mov_b32 m0, s50
	s_nop 0
	global_load_lds_dwordx4 v[140:141], off
	v_lshl_add_u64 v[140:141], s[46:47], 0, v[130:131]
	s_add_i32 m0, s50, 0x2000
	s_nop 0
	global_load_lds_dwordx4 v[140:141], off
	v_lshl_add_u64 v[140:141], v[236:237], 0, s[8:9]
	s_mov_b32 m0, s60
	s_nop 0
	global_load_lds_dwordx4 v[140:141], off
	v_lshl_add_u64 v[140:141], v[238:239], 0, s[8:9]
	s_mov_b32 m0, s61
	s_nop 0
	global_load_lds_dwordx4 v[140:141], off
	s_waitcnt vmcnt(8)
	s_waitcnt lgkmcnt(0)
	s_setprio 1
	s_barrier
	v_mfma_f32_16x16x32_bf16 v[62:65], v[146:149], v[200:203], v[62:65]
	v_mfma_f32_16x16x32_bf16 v[58:61], v[154:157], v[200:203], v[58:61]
	v_mfma_f32_16x16x32_bf16 v[50:53], v[146:149], v[212:215], v[50:53]
	v_mfma_f32_16x16x32_bf16 v[42:45], v[154:157], v[212:215], v[42:45]
	v_mfma_f32_16x16x32_bf16 v[34:37], v[146:149], v[220:223], v[34:37]
	v_mfma_f32_16x16x32_bf16 v[26:29], v[154:157], v[220:223], v[26:29]
	v_mfma_f32_16x16x32_bf16 v[18:21], v[146:149], v[228:231], v[18:21]
	v_mfma_f32_16x16x32_bf16 v[10:13], v[154:157], v[228:231], v[10:13]
	v_mfma_f32_16x16x32_bf16 v[62:65], v[150:153], v[208:211], v[62:65]
	v_mfma_f32_16x16x32_bf16 v[58:61], v[158:161], v[208:211], v[58:61]
	v_mfma_f32_16x16x32_bf16 v[50:53], v[150:153], v[216:219], v[50:53]
	v_mfma_f32_16x16x32_bf16 v[42:45], v[158:161], v[216:219], v[42:45]
	v_mfma_f32_16x16x32_bf16 v[34:37], v[150:153], v[224:227], v[34:37]
	v_mfma_f32_16x16x32_bf16 v[26:29], v[158:161], v[224:227], v[26:29]
	v_mfma_f32_16x16x32_bf16 v[18:21], v[150:153], v[232:235], v[18:21]
	v_mfma_f32_16x16x32_bf16 v[10:13], v[158:161], v[232:235], v[10:13]
	s_setprio 0
	s_setprio 1
	v_mfma_f32_16x16x32_bf16 v[54:57], v[174:177], v[200:203], v[54:57]
	v_mfma_f32_16x16x32_bf16 v[46:49], v[182:185], v[200:203], v[46:49]
	v_mfma_f32_16x16x32_bf16 v[38:41], v[174:177], v[212:215], v[38:41]
	v_mfma_f32_16x16x32_bf16 v[30:33], v[182:185], v[212:215], v[30:33]
	v_mfma_f32_16x16x32_bf16 v[22:25], v[174:177], v[220:223], v[22:25]
	v_mfma_f32_16x16x32_bf16 v[14:17], v[182:185], v[220:223], v[14:17]
	v_mfma_f32_16x16x32_bf16 v[6:9], v[174:177], v[228:231], v[6:9]
	v_mfma_f32_16x16x32_bf16 v[2:5], v[182:185], v[228:231], v[2:5]
	v_mfma_f32_16x16x32_bf16 v[54:57], v[178:181], v[208:211], v[54:57]
	v_mfma_f32_16x16x32_bf16 v[46:49], v[186:189], v[208:211], v[46:49]
	v_mfma_f32_16x16x32_bf16 v[38:41], v[178:181], v[216:219], v[38:41]
	v_mfma_f32_16x16x32_bf16 v[30:33], v[186:189], v[216:219], v[30:33]
	v_mfma_f32_16x16x32_bf16 v[22:25], v[178:181], v[224:227], v[22:25]
	v_mfma_f32_16x16x32_bf16 v[14:17], v[186:189], v[224:227], v[14:17]
	v_mfma_f32_16x16x32_bf16 v[6:9], v[178:181], v[232:235], v[6:9]
	v_mfma_f32_16x16x32_bf16 v[2:5], v[186:189], v[232:235], v[2:5]
	s_barrier
	s_setprio 0
	s_add_i32 s73, s73, 2
	s_add_u32 s16, s16, 0x100
	s_addc_u32 s17, s17, 0
	s_cmp_gt_u32 s73, 41
	s_mov_b64 s[46:47], s[48:49]
	s_cbranch_scc0 .LBB0_656
	s_and_b64 vcc, exec, s[42:43]
	s_cbranch_vccz .LBB0_659
	s_barrier
